# elementwise phases P5/P8: wave reductions via DPP + permlane swaps instead of ds_bpermute butterflies; flat->global there
# speedup vs baseline: 1.0141x; 1.0063x over previous
; __device__ __forceinline__ float bflo(unsigned u) { return __uint_as_float(u << 16); }
; __device__ __forceinline__ float bfhi(unsigned u) { return __uint_as_float(u & 0xffff0000u); }
; __device__ __forceinline__ float wave_sum(float v) {
; #pragma unroll
;     for (int o = 1; o < 64; o <<= 1) v += __shfl_xor(v, o);
;     return v;
; template <int NR, bool XBF, bool WOUT, bool WXB = true>
; __device__ __forceinline__ void rows_final(const float* xp, const float* xs, const bf16_t* __restrict__ Y, const float* __restrict__ ss, const float* __restrict__ gpost, float* out, bf16_t* xb, float* rs, int row0, int lane) {
;     f32x4 v[NR][4]; u32x2 yy[NR][4]; float ssl[NR];
; #pragma unroll
;     for (int r = 0; r < NR; ++r) { const int row = row0 + r;
;         const float* xrow = (row < NP_TOK) ? xp + (size_t)row * DM : xs + (size_t)(row - NP_TOK) * DM;
;         ssl[r] = (lane < 32) ? ss[(size_t)row * 32 + lane] : 0.f;
; #pragma unroll
;         for (int j = 0; j < 4; ++j) {
;             if (XBF) { const u32x2 xw = *((const u32x2*)(xb + (size_t)row * DM) + lane + 64 * j); v[r][j] = (f32x4){bflo(xw.x), bfhi(xw.x), bflo(xw.y), bfhi(xw.y)}; }
;             else v[r][j] = *((const f32x4*)xrow + lane + 64 * j);
;             yy[r][j] = *((const u32x2*)(Y + (size_t)row * DM) + lane + 64 * j); } }
;     f32x4 g[4];
; #pragma unroll
;     for (int j = 0; j < 4; ++j) g[j] = *((const f32x4*)gpost + lane + 64 * j);
; #pragma unroll
;     for (int r = 0; r < NR; ++r) { const int row = row0 + r;
;         const float rn = rsqrtf(wave_sum(ssl[r]) * (1.f / DM) + EPS); float s = 0.f;
.LBB0_611:
	v_mov_b32_e32 v88, 0
	v_lshl_add_u64 v[30:31], s[0:1], 0, v[18:19]
	v_mov_b32_e32 v34, 0
	s_and_saveexec_b64 s[2:3], s[4:5]
	s_cbranch_execz .LBB0_613
	v_add_co_u32_e32 v22, vcc, 0x3b7a0000, v30
	s_waitcnt lgkmcnt(0)
	s_nop 0
	v_addc_co_u32_e32 v23, vcc, 0, v31, vcc
	global_load_dword v34, v[22:23], off
.LBB0_613:
	s_or_b64 exec, exec, s[2:3]
	s_waitcnt lgkmcnt(0)
	v_lshl_add_u64 v[22:23], s[0:1], 0, v[20:21]
	v_add_co_u32_e32 v24, vcc, 0x2d000000, v22
	s_nop 1
	v_addc_co_u32_e32 v25, vcc, 0, v23, vcc
	v_add_co_u32_e32 v36, vcc, 0xf000000, v22
	s_nop 1
	v_addc_co_u32_e32 v37, vcc, 0, v23, vcc
	global_load_dwordx2 v[32:33], v[24:25], off
	global_load_dwordx2 v[28:29], v[24:25], off offset:512
	global_load_dwordx2 v[26:27], v[24:25], off offset:1024
	s_nop 0
	global_load_dwordx2 v[24:25], v[24:25], off offset:1536
	s_nop 0
	global_load_dwordx2 v[78:79], v[36:37], off
	global_load_dwordx2 v[76:77], v[36:37], off offset:512
	global_load_dwordx2 v[74:75], v[36:37], off offset:1024
	global_load_dwordx2 v[72:73], v[36:37], off offset:1536
	s_and_saveexec_b64 s[2:3], s[4:5]
	s_cbranch_execz .LBB0_615
	v_add_co_u32_e32 v36, vcc, 0x3b7a0000, v30
	s_nop 1
	v_addc_co_u32_e32 v37, vcc, 0, v31, vcc
	global_load_dword v88, v[36:37], off offset:128
.LBB0_615:
	s_or_b64 exec, exec, s[2:3]
	v_add_co_u32_e32 v36, vcc, 0x2d000000, v22
	v_mov_b32_e32 v86, 0
	s_nop 0
	v_addc_co_u32_e32 v37, vcc, 0, v23, vcc
	v_add_co_u32_e32 v38, vcc, 0xf000000, v22
	v_mov_b32_e32 v87, 0
	s_nop 0
	v_addc_co_u32_e32 v39, vcc, 0, v23, vcc
	global_load_dwordx2 v[70:71], v[36:37], off offset:2048
	global_load_dwordx2 v[68:69], v[36:37], off offset:2560
	global_load_dwordx2 v[66:67], v[36:37], off offset:3072
	global_load_dwordx2 v[64:65], v[36:37], off offset:3584
	global_load_dwordx2 v[62:63], v[38:39], off offset:2048
	global_load_dwordx2 v[60:61], v[38:39], off offset:2560
	global_load_dwordx2 v[58:59], v[38:39], off offset:3072
	global_load_dwordx2 v[56:57], v[38:39], off offset:3584
	s_and_saveexec_b64 s[2:3], s[4:5]
	s_cbranch_execz .LBB0_617
	v_add_co_u32_e32 v36, vcc, 0x3b7a0000, v30
	s_nop 1
	v_addc_co_u32_e32 v37, vcc, 0, v31, vcc
	global_load_dword v87, v[36:37], off offset:256
.LBB0_617:
	s_or_b64 exec, exec, s[2:3]
	v_add_co_u32_e32 v36, vcc, 0x2d001000, v22
	s_nop 1
	v_addc_co_u32_e32 v37, vcc, 0, v23, vcc
	v_add_co_u32_e32 v38, vcc, 0xf001000, v22
	s_nop 1
	v_addc_co_u32_e32 v39, vcc, 0, v23, vcc
	global_load_dwordx2 v[54:55], v[36:37], off
	global_load_dwordx2 v[52:53], v[36:37], off offset:512
	global_load_dwordx2 v[50:51], v[36:37], off offset:1024
	global_load_dwordx2 v[48:49], v[36:37], off offset:1536
	global_load_dwordx2 v[46:47], v[38:39], off
	global_load_dwordx2 v[44:45], v[38:39], off offset:512
	global_load_dwordx2 v[42:43], v[38:39], off offset:1024
	global_load_dwordx2 v[40:41], v[38:39], off offset:1536
	s_and_saveexec_b64 s[2:3], s[4:5]
	s_cbranch_execz .LBB0_619
	v_add_co_u32_e32 v30, vcc, 0x3b7a0000, v30
	s_nop 1
	v_addc_co_u32_e32 v31, vcc, 0, v31, vcc
	global_load_dword v86, v[30:31], off offset:384
.LBB0_619:
	s_or_b64 exec, exec, s[2:3]
	s_waitcnt vmcnt(0) lgkmcnt(0)
	s_nop 1
	v_mov_b32_dpp v30, v34 quad_perm:[1,0,3,2] row_mask:0xf bank_mask:0xf
	v_lshlrev_b32_e32 v94, 16, v28
	v_and_b32_e32 v95, 0xffff0000, v28
	v_lshlrev_b32_e32 v96, 16, v29
	v_and_b32_e32 v97, 0xffff0000, v29
	s_waitcnt lgkmcnt(0)
	v_add_f32_e32 v28, v34, v30
	s_nop 1
	v_mov_b32_dpp v29, v28 quad_perm:[2,3,0,1] row_mask:0xf bank_mask:0xf
	v_lshlrev_b32_e32 v98, 16, v26
	v_and_b32_e32 v99, 0xffff0000, v26
	v_lshlrev_b32_e32 v100, 16, v27
	v_and_b32_e32 v101, 0xffff0000, v27
	s_waitcnt lgkmcnt(0)
	v_add_f32_e32 v26, v28, v29
	s_nop 1
	v_mov_b32_dpp v27, v26 row_half_mirror row_mask:0xf bank_mask:0xf
	s_mov_b32 s2, 0x2d001000
	v_lshlrev_b32_e32 v102, 16, v24
	v_and_b32_e32 v103, 0xffff0000, v24
	v_add_co_u32_e32 v24, vcc, s2, v22
	s_waitcnt lgkmcnt(0)
	v_add_f32_e32 v26, v26, v27
	s_nop 1
	v_mov_b32_dpp v27, v26 row_mirror row_mask:0xf bank_mask:0xf
	v_lshlrev_b32_e32 v104, 16, v25
	v_and_b32_e32 v105, 0xffff0000, v25
	v_addc_co_u32_e32 v25, vcc, 0, v23, vcc
	s_waitcnt lgkmcnt(0)
	v_add_f32_e32 v26, v26, v27
	v_mov_b32_e32 v27, v26
	v_mov_b32_e32 v254, v26
	s_nop 1
	v_permlane16_swap_b32_e32 v27, v254
	s_mov_b32 s2, 0xf001000
	v_lshlrev_b32_e32 v90, 16, v32
	v_and_b32_e32 v91, 0xffff0000, v32
	v_lshlrev_b32_e32 v92, 16, v33
	s_waitcnt lgkmcnt(0)
	v_add_f32_e32 v26, v254, v27
	v_mov_b32_e32 v27, v26
	v_mov_b32_e32 v254, v26
	s_nop 1
	v_permlane32_swap_b32_e32 v27, v254
	v_and_b32_e32 v93, 0xffff0000, v33
	v_add_co_u32_e32 v106, vcc, s2, v22
	global_load_dwordx2 v[38:39], v[24:25], off offset:2048
	global_load_dwordx2 v[36:37], v[24:25], off offset:2560
	global_load_dwordx2 v[34:35], v[24:25], off offset:3072
	global_load_dwordx2 v[32:33], v[24:25], off offset:3584
	s_waitcnt lgkmcnt(0)
; __device__ __forceinline__ unsigned cvtpk(float lo, float hi) { f32x2 v = {lo, hi}; bf16x2_t b = __builtin_convertvector(v, bf16x2_t); return __builtin_bit_cast(unsigned, b); }
; __device__ __forceinline__ float bflo(unsigned u) { return __uint_as_float(u << 16); }
; __device__ __forceinline__ float bfhi(unsigned u) { return __uint_as_float(u & 0xffff0000u); }
; template <int NR, bool XBF, bool WOUT, bool WXB = true>
; __device__ __forceinline__ void rows_final(const float* xp, const float* xs, const bf16_t* __restrict__ Y, const float* __restrict__ ss, const float* __restrict__ gpost, float* out, bf16_t* xb, float* rs, int row0, int lane) {
;     ...
;     for (int r = 0; r < NR; ++r) { const int row = row0 + r;
;         const float rn = rsqrtf(wave_sum(ssl[r]) * (1.f / DM) + EPS); float s = 0.f;
; #pragma unroll
;         for (int j = 0; j < 4; ++j) { const f32x4 yf = {bflo(yy[r][j].x), bfhi(yy[r][j].x), bflo(yy[r][j].y), bfhi(yy[r][j].y)};
;             v[r][j] = v[r][j] + yf * rn * g[j]; s += (v[r][j][0] * v[r][j][0] + v[r][j][1] * v[r][j][1]) + (v[r][j][2] * v[r][j][2] + v[r][j][3] * v[r][j][3]); }
;         s = wave_sum(s);
;         f32x4* oo = (f32x4*)(out + (size_t)row * DM) + lane; u32x2* o = (u32x2*)(xb + (size_t)row * DM) + lane;
; #pragma unroll
;         for (int j = 0; j < 4; ++j) { if (WOUT) oo[64 * j] = v[r][j]; if (WXB) { u32x2 w; w.x = cvtpk(v[r][j][0], v[r][j][1]); w.y = cvtpk(v[r][j][2], v[r][j][3]); o[64 * j] = w; } }
;         if (WXB && lane == 0) rs[row] = rsqrtf(s * (1.f / DM) + EPS); }
	v_add_f32_e32 v24, v254, v27
	v_addc_co_u32_e32 v107, vcc, 0, v23, vcc
	v_fmamk_f32 v24, v24, 0x3a800000, v241
	v_mul_f32_e32 v25, 0x4b800000, v24
	v_cmp_gt_f32_e32 vcc, s21, v24
	v_lshlrev_b32_e32 v108, 16, v78
	v_and_b32_e32 v109, 0xffff0000, v78
	v_cndmask_b32_e32 v24, v24, v25, vcc
	v_rsq_f32_e32 v89, v24
	global_load_dwordx2 v[30:31], v[106:107], off offset:2048
	global_load_dwordx2 v[28:29], v[106:107], off offset:2560
	global_load_dwordx2 v[26:27], v[106:107], off offset:3072
	global_load_dwordx2 v[24:25], v[106:107], off offset:3584
	v_lshlrev_b32_e32 v78, 16, v79
	v_and_b32_e32 v79, 0xffff0000, v79
	v_mul_f32_e32 v106, 0x45800000, v89
	v_cndmask_b32_e32 v106, v89, v106, vcc
	v_pk_mul_f32 v[108:109], v[106:107], v[108:109] op_sel_hi:[0,1]
	v_pk_mul_f32 v[78:79], v[106:107], v[78:79] op_sel_hi:[0,1]
	v_pk_fma_f32 v[78:79], v[4:5], v[78:79], v[92:93]
	v_pk_fma_f32 v[90:91], v[2:3], v[108:109], v[90:91]
	v_mul_f32_e32 v92, v79, v79
	v_mul_f32_e32 v89, v91, v91
	v_fmac_f32_e32 v89, v90, v90
	v_fmac_f32_e32 v92, v78, v78
	v_add_f32_e32 v89, v89, v92
	v_lshlrev_b32_e32 v92, 16, v76
	v_and_b32_e32 v93, 0xffff0000, v76
	v_lshlrev_b32_e32 v76, 16, v77
	v_and_b32_e32 v77, 0xffff0000, v77
	v_pk_mul_f32 v[92:93], v[106:107], v[92:93] op_sel_hi:[0,1]
	v_pk_mul_f32 v[76:77], v[106:107], v[76:77] op_sel_hi:[0,1]
	v_pk_fma_f32 v[76:77], v[8:9], v[76:77], v[96:97]
	v_pk_fma_f32 v[92:93], v[6:7], v[92:93], v[94:95]
	v_mul_f32_e32 v95, v77, v77
	v_mul_f32_e32 v94, v93, v93
	v_fmac_f32_e32 v94, v92, v92
	v_fmac_f32_e32 v95, v76, v76
	v_add_f32_e32 v94, v94, v95
	v_add_f32_e32 v89, v89, v94
	v_lshlrev_b32_e32 v94, 16, v74
	v_and_b32_e32 v95, 0xffff0000, v74
	v_lshlrev_b32_e32 v74, 16, v75
	v_and_b32_e32 v75, 0xffff0000, v75
	v_pk_mul_f32 v[94:95], v[106:107], v[94:95] op_sel_hi:[0,1]
	v_pk_mul_f32 v[74:75], v[106:107], v[74:75] op_sel_hi:[0,1]
	v_pk_fma_f32 v[74:75], v[12:13], v[74:75], v[100:101]
	v_pk_fma_f32 v[94:95], v[10:11], v[94:95], v[98:99]
	v_mul_f32_e32 v97, v75, v75
	v_mul_f32_e32 v96, v95, v95
	v_fmac_f32_e32 v96, v94, v94
	v_fmac_f32_e32 v97, v74, v74
	v_add_f32_e32 v96, v96, v97
	v_add_f32_e32 v89, v96, v89
	v_lshlrev_b32_e32 v96, 16, v72
	v_and_b32_e32 v97, 0xffff0000, v72
	v_lshlrev_b32_e32 v72, 16, v73
	v_and_b32_e32 v73, 0xffff0000, v73
	v_pk_mul_f32 v[96:97], v[106:107], v[96:97] op_sel_hi:[0,1]
	v_pk_mul_f32 v[72:73], v[106:107], v[72:73] op_sel_hi:[0,1]
	v_pk_fma_f32 v[98:99], v[16:17], v[72:73], v[104:105]
	v_pk_fma_f32 v[96:97], v[14:15], v[96:97], v[102:103]
	v_mul_f32_e32 v73, v99, v99
	v_mul_f32_e32 v72, v97, v97
	v_fmac_f32_e32 v72, v96, v96
	v_fmac_f32_e32 v73, v98, v98
	v_add_f32_e32 v72, v72, v73
	v_add_f32_e32 v72, v72, v89
	s_nop 1
	v_mov_b32_dpp v73, v72 quad_perm:[1,0,3,2] row_mask:0xf bank_mask:0xf
	s_mov_b64 s[2:3], 0x2d000000
	v_lshl_add_u64 v[100:101], v[22:23], 0, s[2:3]
	s_mov_b64 s[2:3], 0x2d000200
	v_lshl_add_u64 v[102:103], v[22:23], 0, s[2:3]
	s_waitcnt lgkmcnt(0)
	v_add_f32_e32 v72, v72, v73
	s_nop 1
	v_mov_b32_dpp v73, v72 quad_perm:[2,3,0,1] row_mask:0xf bank_mask:0xf
	s_mov_b64 s[2:3], 0x2d000400
	v_lshl_add_u64 v[104:105], v[22:23], 0, s[2:3]
	s_mov_b64 s[2:3], 0x2d000600
	v_lshl_add_u64 v[106:107], v[22:23], 0, s[2:3]
	s_waitcnt lgkmcnt(0)
	v_add_f32_e32 v72, v72, v73
	s_nop 1
	v_mov_b32_dpp v73, v72 row_half_mirror row_mask:0xf bank_mask:0xf
	v_cvt_pk_bf16_f32 v90, v90, v91
	v_cvt_pk_bf16_f32 v91, v78, v79
	v_cvt_pk_bf16_f32 v78, v92, v93
	v_cvt_pk_bf16_f32 v79, v76, v77
	s_waitcnt lgkmcnt(0)
	v_add_f32_e32 v72, v72, v73
	s_nop 1
	v_mov_b32_dpp v73, v72 row_mirror row_mask:0xf bank_mask:0xf
	v_cvt_pk_bf16_f32 v76, v94, v95
	v_cvt_pk_bf16_f32 v77, v74, v75
	v_cvt_pk_bf16_f32 v74, v96, v97
	v_cvt_pk_bf16_f32 v75, v98, v99
	s_waitcnt lgkmcnt(0)
	v_add_f32_e32 v72, v72, v73
	v_mov_b32_e32 v73, v72
	v_mov_b32_e32 v254, v72
	s_nop 1
	v_permlane16_swap_b32_e32 v73, v254
	global_store_dwordx2 v[100:101], v[90:91], off
	global_store_dwordx2 v[102:103], v[78:79], off
	global_store_dwordx2 v[104:105], v[76:77], off
	global_store_dwordx2 v[106:107], v[74:75], off
	s_waitcnt lgkmcnt(0)
	v_add_f32_e32 v72, v254, v73
	v_mov_b32_e32 v73, v72
	v_mov_b32_e32 v254, v72
	s_nop 1
	v_permlane32_swap_b32_e32 v73, v254
	s_and_saveexec_b64 s[2:3], s[6:7]
	s_cbranch_execz .LBB0_621
	s_waitcnt lgkmcnt(0)
	v_add_f32_e32 v72, v254, v73
	v_fmamk_f32 v72, v72, 0x3a800000, v241
	v_mul_f32_e32 v73, 0x4b800000, v72
	v_cmp_gt_f32_e32 vcc, s21, v72
	s_add_u32 s11, s0, s12
	s_addc_u32 s15, s1, s13
	v_cndmask_b32_e32 v72, v72, v73, vcc
	v_rsq_f32_e32 v72, v72
	s_nop 0
	v_mul_f32_e32 v73, 0x45800000, v72
	v_cndmask_b32_e32 v74, v72, v73, vcc
	v_mov_b32_e32 v72, s11
	v_add_co_u32_e32 v72, vcc, 0x3b750000, v72
	v_mov_b32_e32 v73, s15
	s_nop 0
	v_addc_co_u32_e32 v73, vcc, 0, v73, vcc
	global_store_dword v[72:73], v74, off
; __device__ __forceinline__ unsigned cvtpk(float lo, float hi) { f32x2 v = {lo, hi}; bf16x2_t b = __builtin_convertvector(v, bf16x2_t); return __builtin_bit_cast(unsigned, b); }
; __device__ __forceinline__ float bflo(unsigned u) { return __uint_as_float(u << 16); }
; __device__ __forceinline__ float bfhi(unsigned u) { return __uint_as_float(u & 0xffff0000u); }
; template <int NR, bool XBF, bool WOUT, bool WXB = true>
; __device__ __forceinline__ void rows_final(const float* xp, const float* xs, const bf16_t* __restrict__ Y, const float* __restrict__ ss, const float* __restrict__ gpost, float* out, bf16_t* xb, float* rs, int row0, int lane) {
;     ...
;     for (int r = 0; r < NR; ++r) { const int row = row0 + r;
;         const float rn = rsqrtf(wave_sum(ssl[r]) * (1.f / DM) + EPS); float s = 0.f;
; #pragma unroll
;         for (int j = 0; j < 4; ++j) { const f32x4 yf = {bflo(yy[r][j].x), bfhi(yy[r][j].x), bflo(yy[r][j].y), bfhi(yy[r][j].y)};
;             v[r][j] = v[r][j] + yf * rn * g[j]; s += (v[r][j][0] * v[r][j][0] + v[r][j][1] * v[r][j][1]) + (v[r][j][2] * v[r][j][2] + v[r][j][3] * v[r][j][3]); }
;         s = wave_sum(s);
;         f32x4* oo = (f32x4*)(out + (size_t)row * DM) + lane; u32x2* o = (u32x2*)(xb + (size_t)row * DM) + lane;
; #pragma unroll
;         for (int j = 0; j < 4; ++j) { if (WOUT) oo[64 * j] = v[r][j]; if (WXB) { u32x2 w; w.x = cvtpk(v[r][j][0], v[r][j][1]); w.y = cvtpk(v[r][j][2], v[r][j][3]); o[64 * j] = w; } }
;         if (WXB && lane == 0) rs[row] = rsqrtf(s * (1.f / DM) + EPS); }
.LBB0_621:
	s_or_b64 exec, exec, s[2:3]
	s_nop 1
	v_mov_b32_dpp v72, v88 quad_perm:[1,0,3,2] row_mask:0xf bank_mask:0xf
	s_waitcnt lgkmcnt(0)
	v_and_b32_e32 v73, 0xffff0000, v70
	s_mov_b64 s[2:3], 0x2d000800
	v_add_f32_e32 v74, v88, v72
	s_nop 1
	v_mov_b32_dpp v75, v74 quad_perm:[2,3,0,1] row_mask:0xf bank_mask:0xf
	v_lshlrev_b32_e32 v72, 16, v70
	v_lshlrev_b32_e32 v70, 16, v71
	v_and_b32_e32 v71, 0xffff0000, v71
	s_waitcnt lgkmcnt(0)
	v_add_f32_e32 v76, v74, v75
	s_nop 1
	v_mov_b32_dpp v77, v76 row_half_mirror row_mask:0xf bank_mask:0xf
	v_lshlrev_b32_e32 v74, 16, v68
	v_and_b32_e32 v75, 0xffff0000, v68
	v_lshlrev_b32_e32 v68, 16, v69
	v_and_b32_e32 v69, 0xffff0000, v69
	s_waitcnt lgkmcnt(0)
	v_add_f32_e32 v78, v76, v77
	s_nop 1
	v_mov_b32_dpp v79, v78 row_mirror row_mask:0xf bank_mask:0xf
	v_lshlrev_b32_e32 v76, 16, v66
	v_and_b32_e32 v77, 0xffff0000, v66
	v_lshlrev_b32_e32 v66, 16, v67
	v_and_b32_e32 v67, 0xffff0000, v67
	s_waitcnt lgkmcnt(0)
	v_add_f32_e32 v88, v78, v79
	v_mov_b32_e32 v89, v88
	v_mov_b32_e32 v254, v88
	s_nop 1
	v_permlane16_swap_b32_e32 v89, v254
	v_lshlrev_b32_e32 v78, 16, v64
	v_and_b32_e32 v79, 0xffff0000, v64
	v_lshlrev_b32_e32 v64, 16, v65
	v_and_b32_e32 v65, 0xffff0000, v65
	s_waitcnt lgkmcnt(0)
	v_add_f32_e32 v90, v254, v89
	v_mov_b32_e32 v91, v90
	v_mov_b32_e32 v254, v90
	s_nop 1
	v_permlane32_swap_b32_e32 v91, v254
	v_lshlrev_b32_e32 v88, 16, v62
	v_and_b32_e32 v89, 0xffff0000, v62
	v_lshlrev_b32_e32 v62, 16, v63
	v_and_b32_e32 v63, 0xffff0000, v63
	s_waitcnt lgkmcnt(0)
	v_add_f32_e32 v90, v254, v91
	v_fmamk_f32 v90, v90, 0x3a800000, v241
	v_mul_f32_e32 v91, 0x4b800000, v90
	v_cmp_gt_f32_e32 vcc, s21, v90
	s_nop 1
	v_cndmask_b32_e32 v90, v90, v91, vcc
	v_rsq_f32_e32 v92, v90
	v_lshlrev_b32_e32 v90, 16, v60
	v_and_b32_e32 v91, 0xffff0000, v60
	v_mul_f32_e32 v60, 0x45800000, v92
	v_cndmask_b32_e32 v60, v92, v60, vcc
	v_pk_mul_f32 v[88:89], v[60:61], v[88:89] op_sel_hi:[0,1]
	v_pk_mul_f32 v[62:63], v[60:61], v[62:63] op_sel_hi:[0,1]
	v_pk_fma_f32 v[62:63], v[4:5], v[62:63], v[70:71]
	v_pk_fma_f32 v[70:71], v[2:3], v[88:89], v[72:73]
	v_mul_f32_e32 v73, v63, v63
	v_mul_f32_e32 v72, v71, v71
	v_fmac_f32_e32 v72, v70, v70
	v_fmac_f32_e32 v73, v62, v62
	v_add_f32_e32 v92, v72, v73
	v_lshlrev_b32_e32 v72, 16, v61
	v_and_b32_e32 v73, 0xffff0000, v61
	v_pk_mul_f32 v[88:89], v[60:61], v[90:91] op_sel_hi:[0,1]
	v_pk_mul_f32 v[72:73], v[60:61], v[72:73] op_sel_hi:[0,1]
	v_pk_fma_f32 v[68:69], v[8:9], v[72:73], v[68:69]
	v_pk_fma_f32 v[72:73], v[6:7], v[88:89], v[74:75]
	v_mul_f32_e32 v74, v69, v69
	v_mul_f32_e32 v61, v73, v73
	v_fmac_f32_e32 v61, v72, v72
	v_fmac_f32_e32 v74, v68, v68
	v_add_f32_e32 v61, v61, v74
	v_add_f32_e32 v61, v92, v61
	v_lshlrev_b32_e32 v74, 16, v58
	v_and_b32_e32 v75, 0xffff0000, v58
	v_lshlrev_b32_e32 v58, 16, v59
	v_and_b32_e32 v59, 0xffff0000, v59
	v_pk_mul_f32 v[74:75], v[60:61], v[74:75] op_sel_hi:[0,1]
	v_pk_mul_f32 v[58:59], v[60:61], v[58:59] op_sel_hi:[0,1]
	v_pk_fma_f32 v[58:59], v[12:13], v[58:59], v[66:67]
	v_pk_fma_f32 v[66:67], v[10:11], v[74:75], v[76:77]
	v_mul_f32_e32 v75, v59, v59
	v_mul_f32_e32 v74, v67, v67
	v_fmac_f32_e32 v74, v66, v66
	v_fmac_f32_e32 v75, v58, v58
	v_add_f32_e32 v74, v74, v75
	v_add_f32_e32 v76, v74, v61
	v_lshlrev_b32_e32 v74, 16, v56
	v_and_b32_e32 v75, 0xffff0000, v56
	v_lshlrev_b32_e32 v56, 16, v57
	v_and_b32_e32 v57, 0xffff0000, v57
	v_pk_mul_f32 v[74:75], v[60:61], v[74:75] op_sel_hi:[0,1]
	v_pk_mul_f32 v[56:57], v[60:61], v[56:57] op_sel_hi:[0,1]
	v_pk_fma_f32 v[60:61], v[16:17], v[56:57], v[64:65]
	v_pk_fma_f32 v[64:65], v[14:15], v[74:75], v[78:79]
	v_mul_f32_e32 v57, v61, v61
	v_mul_f32_e32 v56, v65, v65
	v_fmac_f32_e32 v56, v64, v64
	v_fmac_f32_e32 v57, v60, v60
	v_add_f32_e32 v56, v56, v57
	v_add_f32_e32 v56, v56, v76
	s_nop 1
	v_mov_b32_dpp v57, v56 quad_perm:[1,0,3,2] row_mask:0xf bank_mask:0xf
	v_lshl_add_u64 v[74:75], v[22:23], 0, s[2:3]
	s_mov_b64 s[2:3], 0x2d000a00
	v_lshl_add_u64 v[76:77], v[22:23], 0, s[2:3]
	s_mov_b64 s[2:3], 0x2d000c00
	s_waitcnt lgkmcnt(0)
	v_add_f32_e32 v56, v56, v57
	s_nop 1
	v_mov_b32_dpp v57, v56 quad_perm:[2,3,0,1] row_mask:0xf bank_mask:0xf
	v_lshl_add_u64 v[78:79], v[22:23], 0, s[2:3]
	s_mov_b64 s[2:3], 0x2d000e00
	v_cvt_pk_bf16_f32 v70, v70, v71
	v_cvt_pk_bf16_f32 v71, v62, v63
	s_waitcnt lgkmcnt(0)
	v_add_f32_e32 v56, v56, v57
	s_nop 1
	v_mov_b32_dpp v57, v56 row_half_mirror row_mask:0xf bank_mask:0xf
	v_cvt_pk_bf16_f32 v62, v72, v73
	v_cvt_pk_bf16_f32 v63, v68, v69
	v_lshl_add_u64 v[88:89], v[22:23], 0, s[2:3]
	global_store_dwordx2 v[76:77], v[62:63], off
	s_waitcnt lgkmcnt(0)
	v_add_f32_e32 v56, v56, v57
	s_nop 1
	v_mov_b32_dpp v57, v56 row_mirror row_mask:0xf bank_mask:0xf
	v_cvt_pk_bf16_f32 v62, v66, v67
	v_cvt_pk_bf16_f32 v63, v58, v59
	v_cvt_pk_bf16_f32 v58, v64, v65
	v_cvt_pk_bf16_f32 v59, v60, v61
	s_waitcnt lgkmcnt(0)
	v_add_f32_e32 v56, v56, v57
	v_mov_b32_e32 v57, v56
	v_mov_b32_e32 v254, v56
	s_nop 1
	v_permlane16_swap_b32_e32 v57, v254
	global_store_dwordx2 v[74:75], v[70:71], off
	global_store_dwordx2 v[78:79], v[62:63], off
	global_store_dwordx2 v[88:89], v[58:59], off
	s_waitcnt lgkmcnt(0)
	v_add_f32_e32 v56, v254, v57
	v_mov_b32_e32 v57, v56
	v_mov_b32_e32 v254, v56
	s_nop 1
	v_permlane32_swap_b32_e32 v57, v254
	s_and_saveexec_b64 s[2:3], s[6:7]
	s_cbranch_execz .LBB0_623
	s_waitcnt lgkmcnt(0)
	v_add_f32_e32 v56, v254, v57
	v_fmamk_f32 v56, v56, 0x3a800000, v241
	v_mul_f32_e32 v57, 0x4b800000, v56
	v_cmp_gt_f32_e32 vcc, s21, v56
	s_add_u32 s11, s0, s12
	s_addc_u32 s15, s1, s13
	v_cndmask_b32_e32 v56, v56, v57, vcc
	v_rsq_f32_e32 v56, v56
	s_nop 0
	v_mul_f32_e32 v57, 0x45800000, v56
	v_cndmask_b32_e32 v58, v56, v57, vcc
	v_mov_b32_e32 v56, s11
	v_add_co_u32_e32 v56, vcc, 0x3b750000, v56
	v_mov_b32_e32 v57, s15
	s_nop 0
	v_addc_co_u32_e32 v57, vcc, 0, v57, vcc
	global_store_dword v[56:57], v58, off offset:4
; __device__ __forceinline__ unsigned cvtpk(float lo, float hi) { f32x2 v = {lo, hi}; bf16x2_t b = __builtin_convertvector(v, bf16x2_t); return __builtin_bit_cast(unsigned, b); }
; __device__ __forceinline__ float bflo(unsigned u) { return __uint_as_float(u << 16); }
; __device__ __forceinline__ float bfhi(unsigned u) { return __uint_as_float(u & 0xffff0000u); }
; template <int NR, bool XBF, bool WOUT, bool WXB = true>
; __device__ __forceinline__ void rows_final(const float* xp, const float* xs, const bf16_t* __restrict__ Y, const float* __restrict__ ss, const float* __restrict__ gpost, float* out, bf16_t* xb, float* rs, int row0, int lane) {
;     ...
;     for (int r = 0; r < NR; ++r) { const int row = row0 + r;
;         const float rn = rsqrtf(wave_sum(ssl[r]) * (1.f / DM) + EPS); float s = 0.f;
; #pragma unroll
;         for (int j = 0; j < 4; ++j) { const f32x4 yf = {bflo(yy[r][j].x), bfhi(yy[r][j].x), bflo(yy[r][j].y), bfhi(yy[r][j].y)};
;             v[r][j] = v[r][j] + yf * rn * g[j]; s += (v[r][j][0] * v[r][j][0] + v[r][j][1] * v[r][j][1]) + (v[r][j][2] * v[r][j][2] + v[r][j][3] * v[r][j][3]); }
;         s = wave_sum(s);
;         f32x4* oo = (f32x4*)(out + (size_t)row * DM) + lane; u32x2* o = (u32x2*)(xb + (size_t)row * DM) + lane;
; #pragma unroll
;         for (int j = 0; j < 4; ++j) { if (WOUT) oo[64 * j] = v[r][j]; if (WXB) { u32x2 w; w.x = cvtpk(v[r][j][0], v[r][j][1]); w.y = cvtpk(v[r][j][2], v[r][j][3]); o[64 * j] = w; } }
;         if (WXB && lane == 0) rs[row] = rsqrtf(s * (1.f / DM) + EPS); }
.LBB0_623:
	s_or_b64 exec, exec, s[2:3]
	s_nop 1
	v_mov_b32_dpp v56, v87 quad_perm:[1,0,3,2] row_mask:0xf bank_mask:0xf
	s_waitcnt lgkmcnt(0)
	v_and_b32_e32 v57, 0xffff0000, v54
	s_mov_b64 s[2:3], 0x2d001000
	v_add_f32_e32 v58, v87, v56
	s_nop 1
	v_mov_b32_dpp v59, v58 quad_perm:[2,3,0,1] row_mask:0xf bank_mask:0xf
	v_lshlrev_b32_e32 v56, 16, v54
	v_lshlrev_b32_e32 v54, 16, v55
	v_and_b32_e32 v55, 0xffff0000, v55
	s_waitcnt lgkmcnt(0)
	v_add_f32_e32 v60, v58, v59
	s_nop 1
	v_mov_b32_dpp v61, v60 row_half_mirror row_mask:0xf bank_mask:0xf
	v_lshlrev_b32_e32 v58, 16, v52
	v_and_b32_e32 v59, 0xffff0000, v52
	v_lshlrev_b32_e32 v52, 16, v53
	v_and_b32_e32 v53, 0xffff0000, v53
	s_waitcnt lgkmcnt(0)
	v_add_f32_e32 v62, v60, v61
	s_nop 1
	v_mov_b32_dpp v63, v62 row_mirror row_mask:0xf bank_mask:0xf
	v_lshlrev_b32_e32 v60, 16, v50
	v_and_b32_e32 v61, 0xffff0000, v50
	v_lshlrev_b32_e32 v50, 16, v51
	v_and_b32_e32 v51, 0xffff0000, v51
	s_waitcnt lgkmcnt(0)
	v_add_f32_e32 v64, v62, v63
	v_mov_b32_e32 v65, v64
	v_mov_b32_e32 v254, v64
	s_nop 1
	v_permlane16_swap_b32_e32 v65, v254
	v_lshlrev_b32_e32 v62, 16, v48
	v_and_b32_e32 v63, 0xffff0000, v48
	v_lshlrev_b32_e32 v48, 16, v49
	v_and_b32_e32 v49, 0xffff0000, v49
	s_waitcnt lgkmcnt(0)
	v_add_f32_e32 v66, v254, v65
	v_mov_b32_e32 v67, v66
	v_mov_b32_e32 v254, v66
	s_nop 1
	v_permlane32_swap_b32_e32 v67, v254
	v_lshlrev_b32_e32 v64, 16, v46
	v_and_b32_e32 v65, 0xffff0000, v46
	v_lshlrev_b32_e32 v46, 16, v47
	v_and_b32_e32 v47, 0xffff0000, v47
	s_waitcnt lgkmcnt(0)
	v_add_f32_e32 v66, v254, v67
	v_fmamk_f32 v66, v66, 0x3a800000, v241
	v_mul_f32_e32 v67, 0x4b800000, v66
	v_cmp_gt_f32_e32 vcc, s21, v66
	s_nop 1
	v_cndmask_b32_e32 v66, v66, v67, vcc
	v_rsq_f32_e32 v68, v66
	v_lshlrev_b32_e32 v66, 16, v44
	v_and_b32_e32 v67, 0xffff0000, v44
	v_mul_f32_e32 v44, 0x45800000, v68
	v_cndmask_b32_e32 v44, v68, v44, vcc
	v_pk_mul_f32 v[64:65], v[44:45], v[64:65] op_sel_hi:[0,1]
	v_pk_mul_f32 v[46:47], v[44:45], v[46:47] op_sel_hi:[0,1]
	v_pk_fma_f32 v[46:47], v[4:5], v[46:47], v[54:55]
	v_pk_fma_f32 v[54:55], v[2:3], v[64:65], v[56:57]
	v_mul_f32_e32 v57, v47, v47
	v_mul_f32_e32 v56, v55, v55
	v_fmac_f32_e32 v56, v54, v54
	v_fmac_f32_e32 v57, v46, v46
	v_add_f32_e32 v68, v56, v57
	v_lshlrev_b32_e32 v56, 16, v45
	v_and_b32_e32 v57, 0xffff0000, v45
	v_pk_mul_f32 v[64:65], v[44:45], v[66:67] op_sel_hi:[0,1]
	v_pk_mul_f32 v[56:57], v[44:45], v[56:57] op_sel_hi:[0,1]
	v_pk_fma_f32 v[52:53], v[8:9], v[56:57], v[52:53]
	v_pk_fma_f32 v[56:57], v[6:7], v[64:65], v[58:59]
	v_mul_f32_e32 v58, v53, v53
	v_mul_f32_e32 v45, v57, v57
	v_fmac_f32_e32 v45, v56, v56
	v_fmac_f32_e32 v58, v52, v52
	v_add_f32_e32 v45, v45, v58
	v_add_f32_e32 v45, v68, v45
	v_lshlrev_b32_e32 v58, 16, v42
	v_and_b32_e32 v59, 0xffff0000, v42
	v_lshlrev_b32_e32 v42, 16, v43
	v_and_b32_e32 v43, 0xffff0000, v43
	v_pk_mul_f32 v[58:59], v[44:45], v[58:59] op_sel_hi:[0,1]
	v_pk_mul_f32 v[42:43], v[44:45], v[42:43] op_sel_hi:[0,1]
	v_pk_fma_f32 v[42:43], v[12:13], v[42:43], v[50:51]
	v_pk_fma_f32 v[50:51], v[10:11], v[58:59], v[60:61]
	v_mul_f32_e32 v59, v43, v43
	v_mul_f32_e32 v58, v51, v51
	v_fmac_f32_e32 v58, v50, v50
	v_fmac_f32_e32 v59, v42, v42
	v_add_f32_e32 v58, v58, v59
	v_add_f32_e32 v60, v58, v45
	v_lshlrev_b32_e32 v58, 16, v40
	v_and_b32_e32 v59, 0xffff0000, v40
	v_lshlrev_b32_e32 v40, 16, v41
	v_and_b32_e32 v41, 0xffff0000, v41
	v_pk_mul_f32 v[58:59], v[44:45], v[58:59] op_sel_hi:[0,1]
	v_pk_mul_f32 v[40:41], v[44:45], v[40:41] op_sel_hi:[0,1]
	v_pk_fma_f32 v[44:45], v[16:17], v[40:41], v[48:49]
	v_pk_fma_f32 v[48:49], v[14:15], v[58:59], v[62:63]
	v_mul_f32_e32 v41, v45, v45
	v_mul_f32_e32 v40, v49, v49
	v_fmac_f32_e32 v40, v48, v48
	v_fmac_f32_e32 v41, v44, v44
	v_add_f32_e32 v40, v40, v41
	v_add_f32_e32 v40, v40, v60
	s_nop 1
	v_mov_b32_dpp v41, v40 quad_perm:[1,0,3,2] row_mask:0xf bank_mask:0xf
	v_lshl_add_u64 v[58:59], v[22:23], 0, s[2:3]
	s_mov_b64 s[2:3], 0x2d001200
	v_lshl_add_u64 v[60:61], v[22:23], 0, s[2:3]
	s_mov_b64 s[2:3], 0x2d001400
	s_waitcnt lgkmcnt(0)
	v_add_f32_e32 v40, v40, v41
	s_nop 1
	v_mov_b32_dpp v41, v40 quad_perm:[2,3,0,1] row_mask:0xf bank_mask:0xf
	v_lshl_add_u64 v[62:63], v[22:23], 0, s[2:3]
	s_mov_b64 s[2:3], 0x2d001600
	v_cvt_pk_bf16_f32 v54, v54, v55
	v_cvt_pk_bf16_f32 v55, v46, v47
	s_waitcnt lgkmcnt(0)
	v_add_f32_e32 v40, v40, v41
	s_nop 1
	v_mov_b32_dpp v41, v40 row_half_mirror row_mask:0xf bank_mask:0xf
	v_cvt_pk_bf16_f32 v46, v56, v57
	v_cvt_pk_bf16_f32 v47, v52, v53
	v_lshl_add_u64 v[64:65], v[22:23], 0, s[2:3]
	global_store_dwordx2 v[60:61], v[46:47], off
	s_waitcnt lgkmcnt(0)
	v_add_f32_e32 v40, v40, v41
	s_nop 1
	v_mov_b32_dpp v41, v40 row_mirror row_mask:0xf bank_mask:0xf
	v_cvt_pk_bf16_f32 v46, v50, v51
	v_cvt_pk_bf16_f32 v47, v42, v43
	v_cvt_pk_bf16_f32 v42, v48, v49
	v_cvt_pk_bf16_f32 v43, v44, v45
	s_waitcnt lgkmcnt(0)
	v_add_f32_e32 v40, v40, v41
	v_mov_b32_e32 v41, v40
	v_mov_b32_e32 v254, v40
	s_nop 1
	v_permlane16_swap_b32_e32 v41, v254
	global_store_dwordx2 v[58:59], v[54:55], off
	global_store_dwordx2 v[62:63], v[46:47], off
	global_store_dwordx2 v[64:65], v[42:43], off
	s_waitcnt lgkmcnt(0)
	v_add_f32_e32 v40, v254, v41
	v_mov_b32_e32 v41, v40
	v_mov_b32_e32 v254, v40
	s_nop 1
	v_permlane32_swap_b32_e32 v41, v254
	s_and_saveexec_b64 s[2:3], s[6:7]
	s_cbranch_execz .LBB0_625
	s_waitcnt lgkmcnt(0)
	v_add_f32_e32 v40, v254, v41
	v_fmamk_f32 v40, v40, 0x3a800000, v241
	v_mul_f32_e32 v41, 0x4b800000, v40
	v_cmp_gt_f32_e32 vcc, s21, v40
	s_add_u32 s11, s0, s12
	s_addc_u32 s15, s1, s13
	v_cndmask_b32_e32 v40, v40, v41, vcc
	v_rsq_f32_e32 v40, v40
	s_nop 0
	v_mul_f32_e32 v41, 0x45800000, v40
	v_cndmask_b32_e32 v42, v40, v41, vcc
	v_mov_b32_e32 v40, s11
	v_add_co_u32_e32 v40, vcc, 0x3b750000, v40
	v_mov_b32_e32 v41, s15
	s_nop 0
	v_addc_co_u32_e32 v41, vcc, 0, v41, vcc
	global_store_dword v[40:41], v42, off offset:8
; __device__ __forceinline__ unsigned cvtpk(float lo, float hi) { f32x2 v = {lo, hi}; bf16x2_t b = __builtin_convertvector(v, bf16x2_t); return __builtin_bit_cast(unsigned, b); }
; __device__ __forceinline__ float bflo(unsigned u) { return __uint_as_float(u << 16); }
; __device__ __forceinline__ float bfhi(unsigned u) { return __uint_as_float(u & 0xffff0000u); }
; template <int NR, bool XBF, bool WOUT, bool WXB = true>
; __device__ __forceinline__ void rows_final(const float* xp, const float* xs, const bf16_t* __restrict__ Y, const float* __restrict__ ss, const float* __restrict__ gpost, float* out, bf16_t* xb, float* rs, int row0, int lane) {
;     ...
;     for (int r = 0; r < NR; ++r) { const int row = row0 + r;
;         const float rn = rsqrtf(wave_sum(ssl[r]) * (1.f / DM) + EPS); float s = 0.f;
; #pragma unroll
;         for (int j = 0; j < 4; ++j) { const f32x4 yf = {bflo(yy[r][j].x), bfhi(yy[r][j].x), bflo(yy[r][j].y), bfhi(yy[r][j].y)};
;             v[r][j] = v[r][j] + yf * rn * g[j]; s += (v[r][j][0] * v[r][j][0] + v[r][j][1] * v[r][j][1]) + (v[r][j][2] * v[r][j][2] + v[r][j][3] * v[r][j][3]); }
;         s = wave_sum(s);
;         f32x4* oo = (f32x4*)(out + (size_t)row * DM) + lane; u32x2* o = (u32x2*)(xb + (size_t)row * DM) + lane;
; #pragma unroll
;         for (int j = 0; j < 4; ++j) { if (WOUT) oo[64 * j] = v[r][j]; if (WXB) { u32x2 w; w.x = cvtpk(v[r][j][0], v[r][j][1]); w.y = cvtpk(v[r][j][2], v[r][j][3]); o[64 * j] = w; } }
;         if (WXB && lane == 0) rs[row] = rsqrtf(s * (1.f / DM) + EPS); }
.LBB0_625:
	s_or_b64 exec, exec, s[2:3]
	s_nop 1
	v_mov_b32_dpp v40, v86 quad_perm:[1,0,3,2] row_mask:0xf bank_mask:0xf
	s_waitcnt vmcnt(0) lgkmcnt(0)
	v_and_b32_e32 v41, 0xffff0000, v38
	s_mov_b64 s[2:3], 0x2d001800
	v_add_f32_e32 v42, v86, v40
	s_nop 1
	v_mov_b32_dpp v43, v42 quad_perm:[2,3,0,1] row_mask:0xf bank_mask:0xf
	v_lshlrev_b32_e32 v40, 16, v38
	v_lshlrev_b32_e32 v38, 16, v39
	v_and_b32_e32 v39, 0xffff0000, v39
	s_waitcnt lgkmcnt(0)
	v_add_f32_e32 v44, v42, v43
	s_nop 1
	v_mov_b32_dpp v45, v44 row_half_mirror row_mask:0xf bank_mask:0xf
	v_lshlrev_b32_e32 v42, 16, v36
	v_and_b32_e32 v43, 0xffff0000, v36
	v_lshlrev_b32_e32 v36, 16, v37
	v_and_b32_e32 v37, 0xffff0000, v37
	s_waitcnt lgkmcnt(0)
	v_add_f32_e32 v46, v44, v45
	s_nop 1
	v_mov_b32_dpp v47, v46 row_mirror row_mask:0xf bank_mask:0xf
	v_lshlrev_b32_e32 v44, 16, v34
	v_and_b32_e32 v45, 0xffff0000, v34
	v_lshlrev_b32_e32 v34, 16, v35
	v_and_b32_e32 v35, 0xffff0000, v35
	s_waitcnt lgkmcnt(0)
	v_add_f32_e32 v48, v46, v47
	v_mov_b32_e32 v49, v48
	v_mov_b32_e32 v254, v48
	s_nop 1
	v_permlane16_swap_b32_e32 v49, v254
	v_lshlrev_b32_e32 v46, 16, v32
	v_and_b32_e32 v47, 0xffff0000, v32
	v_lshlrev_b32_e32 v32, 16, v33
	v_and_b32_e32 v33, 0xffff0000, v33
	s_waitcnt lgkmcnt(0)
	v_add_f32_e32 v50, v254, v49
	v_mov_b32_e32 v51, v50
	v_mov_b32_e32 v254, v50
	s_nop 1
	v_permlane32_swap_b32_e32 v51, v254
	v_lshlrev_b32_e32 v48, 16, v30
	v_and_b32_e32 v49, 0xffff0000, v30
	v_lshlrev_b32_e32 v30, 16, v31
	v_and_b32_e32 v31, 0xffff0000, v31
	s_waitcnt lgkmcnt(0)
	v_add_f32_e32 v50, v254, v51
	v_fmamk_f32 v50, v50, 0x3a800000, v241
	v_mul_f32_e32 v51, 0x4b800000, v50
	v_cmp_gt_f32_e32 vcc, s21, v50
	s_nop 1
	v_cndmask_b32_e32 v50, v50, v51, vcc
	v_rsq_f32_e32 v52, v50
	v_lshlrev_b32_e32 v50, 16, v28
	v_and_b32_e32 v51, 0xffff0000, v28
	v_mul_f32_e32 v28, 0x45800000, v52
	v_cndmask_b32_e32 v28, v52, v28, vcc
	v_pk_mul_f32 v[48:49], v[28:29], v[48:49] op_sel_hi:[0,1]
	v_pk_mul_f32 v[30:31], v[28:29], v[30:31] op_sel_hi:[0,1]
	v_pk_fma_f32 v[30:31], v[4:5], v[30:31], v[38:39]
	v_pk_fma_f32 v[38:39], v[2:3], v[48:49], v[40:41]
	v_mul_f32_e32 v41, v31, v31
	v_mul_f32_e32 v40, v39, v39
	v_fmac_f32_e32 v40, v38, v38
	v_fmac_f32_e32 v41, v30, v30
	v_add_f32_e32 v52, v40, v41
	v_lshlrev_b32_e32 v40, 16, v29
	v_and_b32_e32 v41, 0xffff0000, v29
	v_pk_mul_f32 v[48:49], v[28:29], v[50:51] op_sel_hi:[0,1]
	v_pk_mul_f32 v[40:41], v[28:29], v[40:41] op_sel_hi:[0,1]
	v_pk_fma_f32 v[36:37], v[8:9], v[40:41], v[36:37]
	v_pk_fma_f32 v[40:41], v[6:7], v[48:49], v[42:43]
	v_mul_f32_e32 v42, v37, v37
	v_mul_f32_e32 v29, v41, v41
	v_fmac_f32_e32 v29, v40, v40
	v_fmac_f32_e32 v42, v36, v36
	v_add_f32_e32 v29, v29, v42
	v_add_f32_e32 v29, v52, v29
	v_lshlrev_b32_e32 v42, 16, v26
	v_and_b32_e32 v43, 0xffff0000, v26
	v_lshlrev_b32_e32 v26, 16, v27
	v_and_b32_e32 v27, 0xffff0000, v27
	v_pk_mul_f32 v[42:43], v[28:29], v[42:43] op_sel_hi:[0,1]
	v_pk_mul_f32 v[26:27], v[28:29], v[26:27] op_sel_hi:[0,1]
	v_pk_fma_f32 v[26:27], v[12:13], v[26:27], v[34:35]
	v_pk_fma_f32 v[34:35], v[10:11], v[42:43], v[44:45]
	v_mul_f32_e32 v43, v27, v27
	v_mul_f32_e32 v42, v35, v35
	v_fmac_f32_e32 v42, v34, v34
	v_fmac_f32_e32 v43, v26, v26
	v_add_f32_e32 v42, v42, v43
	v_add_f32_e32 v44, v42, v29
	v_lshlrev_b32_e32 v42, 16, v24
	v_and_b32_e32 v43, 0xffff0000, v24
	v_lshlrev_b32_e32 v24, 16, v25
	v_and_b32_e32 v25, 0xffff0000, v25
	v_pk_mul_f32 v[42:43], v[28:29], v[42:43] op_sel_hi:[0,1]
	v_pk_mul_f32 v[24:25], v[28:29], v[24:25] op_sel_hi:[0,1]
	v_pk_fma_f32 v[24:25], v[16:17], v[24:25], v[32:33]
	v_pk_fma_f32 v[28:29], v[14:15], v[42:43], v[46:47]
	v_mul_f32_e32 v33, v25, v25
	v_mul_f32_e32 v32, v29, v29
	v_fmac_f32_e32 v32, v28, v28
	v_fmac_f32_e32 v33, v24, v24
	v_add_f32_e32 v32, v32, v33
	v_add_f32_e32 v32, v32, v44
	s_nop 1
	v_mov_b32_dpp v33, v32 quad_perm:[1,0,3,2] row_mask:0xf bank_mask:0xf
	v_cvt_pk_bf16_f32 v38, v38, v39
	v_cvt_pk_bf16_f32 v39, v30, v31
	v_cvt_pk_bf16_f32 v30, v40, v41
	v_cvt_pk_bf16_f32 v31, v36, v37
	s_waitcnt lgkmcnt(0)
	v_add_f32_e32 v32, v32, v33
	s_nop 1
	v_mov_b32_dpp v33, v32 quad_perm:[2,3,0,1] row_mask:0xf bank_mask:0xf
	s_waitcnt lgkmcnt(0)
	v_add_f32_e32 v32, v32, v33
	s_nop 1
	v_mov_b32_dpp v33, v32 row_half_mirror row_mask:0xf bank_mask:0xf
	s_waitcnt lgkmcnt(0)
	v_add_f32_e32 v32, v32, v33
	s_nop 1
	v_mov_b32_dpp v33, v32 row_mirror row_mask:0xf bank_mask:0xf
	s_waitcnt lgkmcnt(0)
	v_add_f32_e32 v48, v32, v33
	v_mov_b32_e32 v49, v48
	v_mov_b32_e32 v254, v48
	s_nop 1
	v_permlane16_swap_b32_e32 v49, v254
	v_lshl_add_u64 v[32:33], v[22:23], 0, s[2:3]
	s_mov_b64 s[2:3], 0x2d001a00
	v_lshl_add_u64 v[42:43], v[22:23], 0, s[2:3]
	s_mov_b64 s[2:3], 0x2d001c00
	v_lshl_add_u64 v[44:45], v[22:23], 0, s[2:3]
	s_mov_b64 s[2:3], 0x2d001e00
	v_lshl_add_u64 v[46:47], v[22:23], 0, s[2:3]
	s_waitcnt lgkmcnt(0)
	v_add_f32_e32 v22, v254, v49
	v_mov_b32_e32 v23, v22
	v_mov_b32_e32 v254, v22
	s_nop 1
	v_permlane32_swap_b32_e32 v23, v254
	global_store_dwordx2 v[42:43], v[30:31], off
	v_cvt_pk_bf16_f32 v30, v34, v35
	v_cvt_pk_bf16_f32 v31, v26, v27
	v_cvt_pk_bf16_f32 v26, v28, v29
	v_cvt_pk_bf16_f32 v27, v24, v25
	global_store_dwordx2 v[32:33], v[38:39], off
	global_store_dwordx2 v[44:45], v[30:31], off
	global_store_dwordx2 v[46:47], v[26:27], off
	s_and_saveexec_b64 s[2:3], s[6:7]
	s_cbranch_execz .LBB0_610
	s_waitcnt lgkmcnt(0)
	v_add_f32_e32 v22, v254, v23
	v_fmamk_f32 v22, v22, 0x3a800000, v241
	v_mul_f32_e32 v23, 0x4b800000, v22
	v_cmp_gt_f32_e32 vcc, s21, v22
	s_add_u32 s11, s0, s12
	s_addc_u32 s15, s1, s13
	v_cndmask_b32_e32 v22, v22, v23, vcc
	v_rsq_f32_e32 v22, v22
	s_nop 0
	v_mul_f32_e32 v23, 0x45800000, v22
	v_cndmask_b32_e32 v24, v22, v23, vcc
	v_mov_b32_e32 v22, s11
	v_add_co_u32_e32 v22, vcc, 0x3b750000, v22
	v_mov_b32_e32 v23, s15
	s_nop 0
	v_addc_co_u32_e32 v23, vcc, 0, v23, vcc
	global_store_dword v[22:23], v24, off offset:12
	s_branch .LBB0_610

; __device__ __forceinline__ float bflo(unsigned u) { return __uint_as_float(u << 16); }
; __device__ __forceinline__ float bfhi(unsigned u) { return __uint_as_float(u & 0xffff0000u); }
; template <int NR, bool XBF, bool WOUT, bool WXB = true>
; __device__ __forceinline__ void rows_final(const float* xp, const float* xs, const bf16_t* __restrict__ Y, const float* __restrict__ ss, const float* __restrict__ gpost, float* out, bf16_t* xb, float* rs, int row0, int lane) {
;     f32x4 v[NR][4]; u32x2 yy[NR][4]; float ssl[NR];
; #pragma unroll
;     for (int r = 0; r < NR; ++r) { const int row = row0 + r;
;         const float* xrow = (row < NP_TOK) ? xp + (size_t)row * DM : xs + (size_t)(row - NP_TOK) * DM;
;         ssl[r] = (lane < 32) ? ss[(size_t)row * 32 + lane] : 0.f;
; #pragma unroll
;         for (int j = 0; j < 4; ++j) {
;             if (XBF) { const u32x2 xw = *((const u32x2*)(xb + (size_t)row * DM) + lane + 64 * j); v[r][j] = (f32x4){bflo(xw.x), bfhi(xw.x), bflo(xw.y), bfhi(xw.y)}; }
;             else v[r][j] = *((const f32x4*)xrow + lane + 64 * j);
;             yy[r][j] = *((const u32x2*)(Y + (size_t)row * DM) + lane + 64 * j); } }
;     f32x4 g[4];
; #pragma unroll
;     for (int j = 0; j < 4; ++j) g[j] = *((const f32x4*)gpost + lane + 64 * j);
.LBB0_632:
	v_mov_b32_e32 v129, 0
	s_waitcnt lgkmcnt(0)
	v_lshl_add_u64 v[18:19], s[0:1], 0, v[84:85]
	v_mov_b32_e32 v120, 0
	s_and_saveexec_b64 s[2:3], s[4:5]
	s_cbranch_execz .LBB0_634
	v_add_co_u32_e32 v20, vcc, 0x3b7a0000, v18
	s_nop 1
	v_addc_co_u32_e32 v21, vcc, 0, v19, vcc
	global_load_dword v120, v[20:21], off
.LBB0_634:
	s_or_b64 exec, exec, s[2:3]
	v_readlane_b32 s48, v253, 29
	s_add_i32 s2, s8, 0xffff0000
	v_readlane_b32 s49, v253, 30
	s_cmp_lt_i32 s8, 0x10000
	v_readlane_b32 s50, v253, 31
	v_readlane_b32 s51, v253, 32
	s_mov_b64 s[16:17], s[48:49]
	s_cselect_b32 s3, s9, 0
	s_cselect_b32 s2, s8, s2
	s_mov_b64 s[18:19], s[50:51]
	s_cselect_b32 s12, s17, s19
	s_cselect_b32 s13, s16, s18
	s_lshl_b64 s[2:3], s[2:3], 12
	s_add_u32 s2, s13, s2
	v_lshl_add_u64 v[90:91], s[0:1], 0, v[82:83]
	s_addc_u32 s3, s12, s3
	v_lshlrev_b32_e32 v20, 4, v0
	v_add_co_u32_e32 v22, vcc, 0xf000000, v90
	v_readlane_b32 s52, v253, 33
	s_waitcnt lgkmcnt(0)
	v_addc_co_u32_e32 v23, vcc, 0, v91, vcc
	global_load_dwordx4 v[78:81], v20, s[2:3]
	global_load_dwordx4 v[74:77], v20, s[2:3] offset:1024
	global_load_dwordx4 v[70:73], v20, s[2:3] offset:2048
	global_load_dwordx4 v[66:69], v20, s[2:3] offset:3072
	global_load_dwordx2 v[118:119], v[22:23], off
	global_load_dwordx2 v[116:117], v[22:23], off offset:512
	global_load_dwordx2 v[114:115], v[22:23], off offset:1024
	global_load_dwordx2 v[112:113], v[22:23], off offset:1536
	v_readlane_b32 s53, v253, 34
	v_readlane_b32 s54, v253, 35
	v_readlane_b32 s55, v253, 36
	v_readlane_b32 s56, v253, 37
	v_readlane_b32 s57, v253, 38
	v_readlane_b32 s58, v253, 39
	v_readlane_b32 s59, v253, 40
	v_readlane_b32 s60, v253, 41
	v_readlane_b32 s61, v253, 42
	v_readlane_b32 s62, v253, 43
	v_readlane_b32 s63, v253, 44
	s_and_saveexec_b64 s[2:3], s[4:5]
	s_cbranch_execz .LBB0_636
	v_add_co_u32_e32 v22, vcc, 0x3b7a0000, v18
	s_nop 1
	v_addc_co_u32_e32 v23, vcc, 0, v19, vcc
	global_load_dword v129, v[22:23], off offset:128
.LBB0_636:
	s_or_b64 exec, exec, s[2:3]
	s_add_u32 s2, s8, 1
	v_readlane_b32 s48, v253, 29
	s_addc_u32 s3, s9, 0
	s_add_i32 s12, s8, 0xffff0001
	v_readlane_b32 s49, v253, 30
	s_cmp_lt_i32 s8, 0xffff
	v_readlane_b32 s50, v253, 31
	v_readlane_b32 s51, v253, 32
	s_mov_b64 s[16:17], s[48:49]
	s_cselect_b32 s3, s3, 0
	s_cselect_b32 s2, s2, s12
	s_mov_b64 s[18:19], s[50:51]
	s_cselect_b32 s12, s17, s19
	s_cselect_b32 s13, s16, s18
	s_lshl_b64 s[2:3], s[2:3], 12
	s_add_u32 s2, s13, s2
	s_addc_u32 s3, s12, s3
	v_add_co_u32_e32 v22, vcc, 0xf000000, v90
	v_mov_b32_e32 v127, 0
	s_nop 0
	v_addc_co_u32_e32 v23, vcc, 0, v91, vcc
	global_load_dwordx4 v[62:65], v20, s[2:3]
	global_load_dwordx4 v[58:61], v20, s[2:3] offset:1024
	global_load_dwordx4 v[54:57], v20, s[2:3] offset:2048
	global_load_dwordx4 v[50:53], v20, s[2:3] offset:3072
	global_load_dwordx2 v[110:111], v[22:23], off offset:2048
	global_load_dwordx2 v[108:109], v[22:23], off offset:2560
	global_load_dwordx2 v[106:107], v[22:23], off offset:3072
	global_load_dwordx2 v[104:105], v[22:23], off offset:3584
	v_mov_b32_e32 v128, 0
	v_readlane_b32 s52, v253, 33
	v_readlane_b32 s53, v253, 34
	v_readlane_b32 s54, v253, 35
	v_readlane_b32 s55, v253, 36
	v_readlane_b32 s56, v253, 37
	v_readlane_b32 s57, v253, 38
	v_readlane_b32 s58, v253, 39
	v_readlane_b32 s59, v253, 40
	v_readlane_b32 s60, v253, 41
	v_readlane_b32 s61, v253, 42
	v_readlane_b32 s62, v253, 43
	v_readlane_b32 s63, v253, 44
	s_and_saveexec_b64 s[2:3], s[4:5]
	s_cbranch_execz .LBB0_638
	v_add_co_u32_e32 v22, vcc, 0x3b7a0000, v18
	s_nop 1
	v_addc_co_u32_e32 v23, vcc, 0, v19, vcc
	global_load_dword v128, v[22:23], off offset:256
.LBB0_638:
	s_or_b64 exec, exec, s[2:3]
	s_add_u32 s2, s8, 2
	v_readlane_b32 s48, v253, 29
	s_addc_u32 s3, s9, 0
	s_add_i32 s12, s8, 0xffff0002
	v_readlane_b32 s49, v253, 30
	s_cmp_lt_i32 s8, 0xfffe
	v_readlane_b32 s50, v253, 31
	v_readlane_b32 s51, v253, 32
	s_mov_b64 s[16:17], s[48:49]
	s_cselect_b32 s3, s3, 0
	s_cselect_b32 s2, s2, s12
	s_mov_b64 s[18:19], s[50:51]
	s_cselect_b32 s12, s17, s19
	s_cselect_b32 s13, s16, s18
	s_lshl_b64 s[2:3], s[2:3], 12
	s_add_u32 s2, s13, s2
	s_addc_u32 s3, s12, s3
	v_add_co_u32_e32 v22, vcc, 0xf001000, v90
	v_readlane_b32 s52, v253, 33
	s_nop 0
	v_addc_co_u32_e32 v23, vcc, 0, v91, vcc
	global_load_dwordx4 v[46:49], v20, s[2:3]
	global_load_dwordx4 v[42:45], v20, s[2:3] offset:1024
	global_load_dwordx4 v[38:41], v20, s[2:3] offset:2048
	global_load_dwordx4 v[34:37], v20, s[2:3] offset:3072
	global_load_dwordx2 v[102:103], v[22:23], off
	global_load_dwordx2 v[100:101], v[22:23], off offset:512
	global_load_dwordx2 v[98:99], v[22:23], off offset:1024
	global_load_dwordx2 v[96:97], v[22:23], off offset:1536
	v_readlane_b32 s53, v253, 34
	v_readlane_b32 s54, v253, 35
	v_readlane_b32 s55, v253, 36
	v_readlane_b32 s56, v253, 37
	v_readlane_b32 s57, v253, 38
	v_readlane_b32 s58, v253, 39
	v_readlane_b32 s59, v253, 40
	v_readlane_b32 s60, v253, 41
	v_readlane_b32 s61, v253, 42
	v_readlane_b32 s62, v253, 43
	v_readlane_b32 s63, v253, 44
	s_and_saveexec_b64 s[2:3], s[4:5]
	s_cbranch_execz .LBB0_640
	v_add_co_u32_e32 v18, vcc, 0x3b7a0000, v18
	s_nop 1
	v_addc_co_u32_e32 v19, vcc, 0, v19, vcc
	global_load_dword v127, v[18:19], off offset:384
; __device__ __forceinline__ unsigned cvtpk(float lo, float hi) { f32x2 v = {lo, hi}; bf16x2_t b = __builtin_convertvector(v, bf16x2_t); return __builtin_bit_cast(unsigned, b); }
; __device__ __forceinline__ float bflo(unsigned u) { return __uint_as_float(u << 16); }
; __device__ __forceinline__ float bfhi(unsigned u) { return __uint_as_float(u & 0xffff0000u); }
; template <int NR, bool XBF, bool WOUT, bool WXB = true>
; __device__ __forceinline__ void rows_final(const float* xp, const float* xs, const bf16_t* __restrict__ Y, const float* __restrict__ ss, const float* __restrict__ gpost, float* out, bf16_t* xb, float* rs, int row0, int lane) {
;     ...
;     for (int r = 0; r < NR; ++r) { const int row = row0 + r;
;         const float rn = rsqrtf(wave_sum(ssl[r]) * (1.f / DM) + EPS); float s = 0.f;
; #pragma unroll
;         for (int j = 0; j < 4; ++j) { const f32x4 yf = {bflo(yy[r][j].x), bfhi(yy[r][j].x), bflo(yy[r][j].y), bfhi(yy[r][j].y)};
;             v[r][j] = v[r][j] + yf * rn * g[j]; s += (v[r][j][0] * v[r][j][0] + v[r][j][1] * v[r][j][1]) + (v[r][j][2] * v[r][j][2] + v[r][j][3] * v[r][j][3]); }
;         s = wave_sum(s);
;         f32x4* oo = (f32x4*)(out + (size_t)row * DM) + lane; u32x2* o = (u32x2*)(xb + (size_t)row * DM) + lane;
; #pragma unroll
;         for (int j = 0; j < 4; ++j) { if (WOUT) oo[64 * j] = v[r][j]; if (WXB) { u32x2 w; w.x = cvtpk(v[r][j][0], v[r][j][1]); w.y = cvtpk(v[r][j][2], v[r][j][3]); o[64 * j] = w; } }
;         if (WXB && lane == 0) rs[row] = rsqrtf(s * (1.f / DM) + EPS); }
.LBB0_640:
	s_or_b64 exec, exec, s[2:3]
	s_waitcnt vmcnt(0)
	s_nop 1
	v_mov_b32_dpp v130, v120 quad_perm:[1,0,3,2] row_mask:0xf bank_mask:0xf
	s_add_u32 s2, s8, 3
	v_readlane_b32 s40, v253, 29
	s_addc_u32 s3, s9, 0
	s_add_i32 s12, s8, 0xffff0003
	s_waitcnt lgkmcnt(0)
	v_add_f32_e32 v120, v120, v130
	s_nop 1
	v_mov_b32_dpp v130, v120 quad_perm:[2,3,0,1] row_mask:0xf bank_mask:0xf
	v_readlane_b32 s41, v253, 30
	s_cmp_lt_i32 s8, 0xfffd
	v_readlane_b32 s42, v253, 31
	v_readlane_b32 s43, v253, 32
	s_mov_b64 s[16:17], s[40:41]
	s_waitcnt lgkmcnt(0)
	v_add_f32_e32 v120, v120, v130
	s_cselect_b32 s3, s3, 0
	s_cselect_b32 s2, s2, s12
	s_mov_b64 s[18:19], s[42:43]
	s_nop 1
	v_mov_b32_dpp v130, v120 row_half_mirror row_mask:0xf bank_mask:0xf
	s_cselect_b32 s12, s17, s19
	s_cselect_b32 s13, s16, s18
	s_lshl_b64 s[2:3], s[2:3], 12
	s_add_u32 s2, s13, s2
	s_addc_u32 s3, s12, s3
	s_mov_b32 s12, 0xf001000
	v_add_co_u32_e32 v86, vcc, s12, v90
	s_waitcnt lgkmcnt(0)
	v_add_f32_e32 v120, v120, v130
	v_addc_co_u32_e32 v87, vcc, 0, v91, vcc
	global_load_dwordx4 v[30:33], v20, s[2:3]
	global_load_dwordx2 v[94:95], v[86:87], off offset:2048
	global_load_dwordx4 v[26:29], v20, s[2:3] offset:1024
	global_load_dwordx2 v[92:93], v[86:87], off offset:2560
	global_load_dwordx4 v[22:25], v20, s[2:3] offset:2048
	global_load_dwordx2 v[88:89], v[86:87], off offset:3072
	s_nop 0
	global_load_dwordx4 v[18:21], v20, s[2:3] offset:3072
	s_nop 0
	global_load_dwordx2 v[86:87], v[86:87], off offset:3584
	s_nop 1
	v_mov_b32_dpp v130, v120 row_mirror row_mask:0xf bank_mask:0xf
	v_and_b32_e32 v131, 0xffff0000, v118
	s_mov_b32 s2, 0x2d000000
	v_readlane_b32 s44, v253, 33
	v_readlane_b32 s45, v253, 34
	s_waitcnt lgkmcnt(0)
	v_add_f32_e32 v120, v120, v130
	v_mov_b32_e32 v130, v120
	v_mov_b32_e32 v254, v120
	s_nop 1
	v_permlane16_swap_b32_e32 v130, v254
	v_readlane_b32 s46, v253, 35
	v_readlane_b32 s47, v253, 36
	v_readlane_b32 s48, v253, 37
	v_readlane_b32 s49, v253, 38
	s_waitcnt lgkmcnt(0)
	v_add_f32_e32 v120, v254, v130
	v_mov_b32_e32 v130, v120
	v_mov_b32_e32 v254, v120
	s_nop 1
	v_permlane32_swap_b32_e32 v130, v254
	v_readlane_b32 s50, v253, 39
	v_readlane_b32 s51, v253, 40
	v_readlane_b32 s52, v253, 41
	v_readlane_b32 s53, v253, 42
	s_waitcnt lgkmcnt(0)
	v_add_f32_e32 v120, v254, v130
	v_fmamk_f32 v120, v120, 0x3a800000, v241
	v_cmp_gt_f32_e32 vcc, s21, v120
	v_mul_f32_e32 v130, 0x4b800000, v120
	v_readlane_b32 s54, v253, 43
	v_cndmask_b32_e32 v120, v120, v130, vcc
	v_rsq_f32_e32 v120, v120
	v_readlane_b32 s55, v253, 44
	v_mul_f32_e32 v130, 0x45800000, v120
	v_cndmask_b32_e32 v120, v120, v130, vcc
	v_lshlrev_b32_e32 v130, 16, v118
	v_lshlrev_b32_e32 v118, 16, v119
	v_and_b32_e32 v119, 0xffff0000, v119
	v_pk_mul_f32 v[130:131], v[120:121], v[130:131] op_sel_hi:[0,1]
	v_pk_mul_f32 v[118:119], v[120:121], v[118:119] op_sel_hi:[0,1]
	v_pk_fma_f32 v[80:81], v[4:5], v[118:119], v[80:81]
	v_pk_fma_f32 v[78:79], v[2:3], v[130:131], v[78:79]
	v_mul_f32_e32 v119, v81, v81
	v_mul_f32_e32 v118, v79, v79
	v_fmac_f32_e32 v118, v78, v78
	v_fmac_f32_e32 v119, v80, v80
	v_add_f32_e32 v130, v118, v119
	v_lshlrev_b32_e32 v118, 16, v116
	v_and_b32_e32 v119, 0xffff0000, v116
	v_lshlrev_b32_e32 v116, 16, v117
	v_and_b32_e32 v117, 0xffff0000, v117
	v_pk_mul_f32 v[118:119], v[120:121], v[118:119] op_sel_hi:[0,1]
	v_pk_mul_f32 v[116:117], v[120:121], v[116:117] op_sel_hi:[0,1]
	v_pk_fma_f32 v[76:77], v[8:9], v[116:117], v[76:77]
	v_pk_fma_f32 v[74:75], v[6:7], v[118:119], v[74:75]
	v_mul_f32_e32 v117, v77, v77
	v_mul_f32_e32 v116, v75, v75
	v_fmac_f32_e32 v116, v74, v74
	v_fmac_f32_e32 v117, v76, v76
	v_add_f32_e32 v116, v116, v117
	v_add_f32_e32 v118, v130, v116
	v_lshlrev_b32_e32 v116, 16, v114
	v_and_b32_e32 v117, 0xffff0000, v114
	v_lshlrev_b32_e32 v114, 16, v115
	v_and_b32_e32 v115, 0xffff0000, v115
	v_pk_mul_f32 v[116:117], v[120:121], v[116:117] op_sel_hi:[0,1]
	v_pk_mul_f32 v[114:115], v[120:121], v[114:115] op_sel_hi:[0,1]
	v_pk_fma_f32 v[72:73], v[12:13], v[114:115], v[72:73]
	v_pk_fma_f32 v[70:71], v[10:11], v[116:117], v[70:71]
	v_mul_f32_e32 v115, v73, v73
	v_mul_f32_e32 v114, v71, v71
	v_fmac_f32_e32 v114, v70, v70
	v_fmac_f32_e32 v115, v72, v72
	v_add_f32_e32 v114, v114, v115
	v_add_f32_e32 v116, v114, v118
	v_lshlrev_b32_e32 v114, 16, v112
	v_and_b32_e32 v115, 0xffff0000, v112
	v_lshlrev_b32_e32 v112, 16, v113
	v_and_b32_e32 v113, 0xffff0000, v113
	v_pk_mul_f32 v[114:115], v[120:121], v[114:115] op_sel_hi:[0,1]
	v_pk_mul_f32 v[112:113], v[120:121], v[112:113] op_sel_hi:[0,1]
	v_pk_fma_f32 v[112:113], v[16:17], v[112:113], v[68:69]
	v_pk_fma_f32 v[114:115], v[14:15], v[114:115], v[66:67]
	v_mul_f32_e32 v67, v113, v113
	v_mul_f32_e32 v66, v115, v115
	v_fmac_f32_e32 v66, v114, v114
	v_fmac_f32_e32 v67, v112, v112
	v_add_f32_e32 v66, v66, v67
	v_add_f32_e32 v66, v66, v116
	s_nop 1
	v_mov_b32_dpp v67, v66 quad_perm:[1,0,3,2] row_mask:0xf bank_mask:0xf
	v_cvt_pk_bf16_f32 v70, v70, v71
	v_cvt_pk_bf16_f32 v71, v72, v73
	v_cvt_pk_bf16_f32 v78, v78, v79
	v_cvt_pk_bf16_f32 v79, v80, v81
	s_waitcnt lgkmcnt(0)
	v_add_f32_e32 v66, v66, v67
	s_nop 1
	v_mov_b32_dpp v67, v66 quad_perm:[2,3,0,1] row_mask:0xf bank_mask:0xf
	v_cvt_pk_bf16_f32 v74, v74, v75
	v_cvt_pk_bf16_f32 v75, v76, v77
	s_waitcnt lgkmcnt(0)
	v_add_f32_e32 v66, v66, v67
	s_nop 1
	v_mov_b32_dpp v67, v66 row_half_mirror row_mask:0xf bank_mask:0xf
	s_waitcnt lgkmcnt(0)
	v_add_f32_e32 v66, v66, v67
	s_nop 1
	v_mov_b32_dpp v67, v66 row_mirror row_mask:0xf bank_mask:0xf
	s_waitcnt lgkmcnt(0)
	v_add_f32_e32 v66, v66, v67
	v_mov_b32_e32 v67, v66
	v_mov_b32_e32 v254, v66
	s_nop 1
	v_permlane16_swap_b32_e32 v67, v254
	s_waitcnt lgkmcnt(0)
	v_add_f32_e32 v68, v254, v67
	v_mov_b32_e32 v69, v68
	v_mov_b32_e32 v254, v68
	s_nop 1
	v_permlane32_swap_b32_e32 v69, v254
	v_add_co_u32_e32 v66, vcc, s2, v90
	s_nop 1
	v_addc_co_u32_e32 v67, vcc, 0, v91, vcc
	global_store_dwordx2 v[66:67], v[70:71], off offset:1024
	v_cvt_pk_bf16_f32 v70, v114, v115
	v_cvt_pk_bf16_f32 v71, v112, v113
	global_store_dwordx2 v[66:67], v[78:79], off
	global_store_dwordx2 v[66:67], v[74:75], off offset:512
	global_store_dwordx2 v[66:67], v[70:71], off offset:1536
	s_and_saveexec_b64 s[2:3], s[6:7]
	s_cbranch_execz .LBB0_642
	s_waitcnt lgkmcnt(0)
	v_add_f32_e32 v68, v254, v69
	v_fmamk_f32 v68, v68, 0x3a800000, v241
	v_mul_f32_e32 v69, 0x4b800000, v68
	v_cmp_gt_f32_e32 vcc, s21, v68
	s_add_u32 s12, s0, s10
	s_addc_u32 s13, s1, s11
	v_cndmask_b32_e32 v68, v68, v69, vcc
	v_rsq_f32_e32 v68, v68
	s_nop 0
	v_mul_f32_e32 v69, 0x45800000, v68
	v_cndmask_b32_e32 v70, v68, v69, vcc
	v_mov_b32_e32 v68, s12
	v_add_co_u32_e32 v68, vcc, 0x3b750000, v68
	v_mov_b32_e32 v69, s13
	s_nop 0
	v_addc_co_u32_e32 v69, vcc, 0, v69, vcc
	global_store_dword v[68:69], v70, off
; __device__ __forceinline__ unsigned cvtpk(float lo, float hi) { f32x2 v = {lo, hi}; bf16x2_t b = __builtin_convertvector(v, bf16x2_t); return __builtin_bit_cast(unsigned, b); }
; __device__ __forceinline__ float bflo(unsigned u) { return __uint_as_float(u << 16); }
; __device__ __forceinline__ float bfhi(unsigned u) { return __uint_as_float(u & 0xffff0000u); }
; __device__ __forceinline__ float wave_sum(float v) {
; #pragma unroll
;     for (int o = 1; o < 64; o <<= 1) v += __shfl_xor(v, o);
;     return v;
; template <int NR, bool XBF, bool WOUT, bool WXB = true>
; __device__ __forceinline__ void rows_final(const float* xp, const float* xs, const bf16_t* __restrict__ Y, const float* __restrict__ ss, const float* __restrict__ gpost, float* out, bf16_t* xb, float* rs, int row0, int lane) {
;     ...
; #pragma unroll
;     for (int r = 0; r < NR; ++r) { const int row = row0 + r;
;         const float rn = rsqrtf(wave_sum(ssl[r]) * (1.f / DM) + EPS); float s = 0.f;
; #pragma unroll
;         for (int j = 0; j < 4; ++j) { const f32x4 yf = {bflo(yy[r][j].x), bfhi(yy[r][j].x), bflo(yy[r][j].y), bfhi(yy[r][j].y)};
;             v[r][j] = v[r][j] + yf * rn * g[j]; s += (v[r][j][0] * v[r][j][0] + v[r][j][1] * v[r][j][1]) + (v[r][j][2] * v[r][j][2] + v[r][j][3] * v[r][j][3]); }
;         s = wave_sum(s);
;         f32x4* oo = (f32x4*)(out + (size_t)row * DM) + lane; u32x2* o = (u32x2*)(xb + (size_t)row * DM) + lane;
; #pragma unroll
;         for (int j = 0; j < 4; ++j) { if (WOUT) oo[64 * j] = v[r][j]; if (WXB) { u32x2 w; w.x = cvtpk(v[r][j][0], v[r][j][1]); w.y = cvtpk(v[r][j][2], v[r][j][3]); o[64 * j] = w; } }
;         if (WXB && lane == 0) rs[row] = rsqrtf(s * (1.f / DM) + EPS); }
.LBB0_642:
	s_or_b64 exec, exec, s[2:3]
	s_nop 1
	v_mov_b32_dpp v68, v129 quad_perm:[1,0,3,2] row_mask:0xf bank_mask:0xf
	v_lshlrev_b32_e32 v70, 16, v110
	v_and_b32_e32 v71, 0xffff0000, v110
	v_lshlrev_b32_e32 v72, 16, v111
	v_and_b32_e32 v73, 0xffff0000, v111
	s_waitcnt lgkmcnt(0)
	v_add_f32_e32 v68, v129, v68
	s_nop 1
	v_mov_b32_dpp v69, v68 quad_perm:[2,3,0,1] row_mask:0xf bank_mask:0xf
	s_waitcnt lgkmcnt(0)
	v_add_f32_e32 v68, v68, v69
	s_nop 1
	v_mov_b32_dpp v69, v68 row_half_mirror row_mask:0xf bank_mask:0xf
	s_waitcnt lgkmcnt(0)
	v_add_f32_e32 v68, v68, v69
	s_nop 1
	v_mov_b32_dpp v69, v68 row_mirror row_mask:0xf bank_mask:0xf
	s_waitcnt lgkmcnt(0)
	v_add_f32_e32 v68, v68, v69
	v_mov_b32_e32 v69, v68
	v_mov_b32_e32 v254, v68
	s_nop 1
	v_permlane16_swap_b32_e32 v69, v254
	s_waitcnt lgkmcnt(0)
	v_add_f32_e32 v68, v254, v69
	v_mov_b32_e32 v69, v68
	v_mov_b32_e32 v254, v68
	s_nop 1
	v_permlane32_swap_b32_e32 v69, v254
	s_waitcnt lgkmcnt(0)
	v_add_f32_e32 v68, v254, v69
	v_fmamk_f32 v68, v68, 0x3a800000, v241
	v_cmp_gt_f32_e32 vcc, s21, v68
	v_mul_f32_e32 v69, 0x4b800000, v68
	s_nop 0
	v_cndmask_b32_e32 v68, v68, v69, vcc
	v_rsq_f32_e32 v68, v68
	s_nop 0
	v_mul_f32_e32 v69, 0x45800000, v68
	v_cndmask_b32_e32 v68, v68, v69, vcc
	v_pk_mul_f32 v[70:71], v[68:69], v[70:71] op_sel_hi:[0,1]
	v_pk_mul_f32 v[72:73], v[68:69], v[72:73] op_sel_hi:[0,1]
	v_pk_fma_f32 v[64:65], v[4:5], v[72:73], v[64:65]
	v_pk_fma_f32 v[62:63], v[2:3], v[70:71], v[62:63]
	v_mul_f32_e32 v70, v65, v65
	v_mul_f32_e32 v69, v63, v63
	v_fmac_f32_e32 v69, v62, v62
	v_fmac_f32_e32 v70, v64, v64
	v_add_f32_e32 v69, v69, v70
	v_lshlrev_b32_e32 v70, 16, v108
	v_and_b32_e32 v71, 0xffff0000, v108
	v_lshlrev_b32_e32 v72, 16, v109
	v_and_b32_e32 v73, 0xffff0000, v109
	v_pk_mul_f32 v[70:71], v[68:69], v[70:71] op_sel_hi:[0,1]
	v_pk_mul_f32 v[72:73], v[68:69], v[72:73] op_sel_hi:[0,1]
	v_pk_fma_f32 v[60:61], v[8:9], v[72:73], v[60:61]
	v_pk_fma_f32 v[58:59], v[6:7], v[70:71], v[58:59]
	v_mul_f32_e32 v71, v61, v61
	v_mul_f32_e32 v70, v59, v59
	v_fmac_f32_e32 v70, v58, v58
	v_fmac_f32_e32 v71, v60, v60
	v_add_f32_e32 v70, v70, v71
	v_add_f32_e32 v69, v69, v70
	v_lshlrev_b32_e32 v70, 16, v106
	v_and_b32_e32 v71, 0xffff0000, v106
	v_lshlrev_b32_e32 v72, 16, v107
	v_and_b32_e32 v73, 0xffff0000, v107
	v_pk_mul_f32 v[70:71], v[68:69], v[70:71] op_sel_hi:[0,1]
	v_pk_mul_f32 v[72:73], v[68:69], v[72:73] op_sel_hi:[0,1]
	v_pk_fma_f32 v[56:57], v[12:13], v[72:73], v[56:57]
	v_pk_fma_f32 v[54:55], v[10:11], v[70:71], v[54:55]
	v_mul_f32_e32 v71, v57, v57
	v_mul_f32_e32 v70, v55, v55
	v_fmac_f32_e32 v70, v54, v54
	v_fmac_f32_e32 v71, v56, v56
	v_add_f32_e32 v70, v70, v71
	v_add_f32_e32 v74, v70, v69
	v_lshlrev_b32_e32 v70, 16, v104
	v_and_b32_e32 v71, 0xffff0000, v104
	v_lshlrev_b32_e32 v72, 16, v105
	v_and_b32_e32 v73, 0xffff0000, v105
	v_pk_mul_f32 v[70:71], v[68:69], v[70:71] op_sel_hi:[0,1]
	v_pk_mul_f32 v[68:69], v[68:69], v[72:73] op_sel_hi:[0,1]
	v_pk_fma_f32 v[52:53], v[16:17], v[68:69], v[52:53]
	v_pk_fma_f32 v[68:69], v[14:15], v[70:71], v[50:51]
	v_mul_f32_e32 v51, v53, v53
	v_mul_f32_e32 v50, v69, v69
	v_fmac_f32_e32 v50, v68, v68
	v_fmac_f32_e32 v51, v52, v52
	v_add_f32_e32 v50, v50, v51
	v_add_f32_e32 v50, v50, v74
	s_nop 1
	v_mov_b32_dpp v51, v50 quad_perm:[1,0,3,2] row_mask:0xf bank_mask:0xf
	v_cvt_pk_bf16_f32 v54, v54, v55
	v_cvt_pk_bf16_f32 v55, v56, v57
	v_cvt_pk_bf16_f32 v62, v62, v63
	v_cvt_pk_bf16_f32 v63, v64, v65
	s_waitcnt lgkmcnt(0)
	v_add_f32_e32 v50, v50, v51
	s_nop 1
	v_mov_b32_dpp v51, v50 quad_perm:[2,3,0,1] row_mask:0xf bank_mask:0xf
	v_cvt_pk_bf16_f32 v58, v58, v59
	v_cvt_pk_bf16_f32 v59, v60, v61
	global_store_dwordx2 v[66:67], v[54:55], off offset:3072
	v_cvt_pk_bf16_f32 v54, v68, v69
	s_waitcnt lgkmcnt(0)
	v_add_f32_e32 v50, v50, v51
	s_nop 1
	v_mov_b32_dpp v51, v50 row_half_mirror row_mask:0xf bank_mask:0xf
	v_cvt_pk_bf16_f32 v55, v52, v53
	global_store_dwordx2 v[66:67], v[62:63], off offset:2048
	global_store_dwordx2 v[66:67], v[58:59], off offset:2560
	global_store_dwordx2 v[66:67], v[54:55], off offset:3584
	s_waitcnt lgkmcnt(0)
	v_add_f32_e32 v50, v50, v51
	s_nop 1
	v_mov_b32_dpp v51, v50 row_mirror row_mask:0xf bank_mask:0xf
	s_waitcnt lgkmcnt(0)
	v_add_f32_e32 v50, v50, v51
	v_mov_b32_e32 v51, v50
	v_mov_b32_e32 v254, v50
	s_nop 1
	v_permlane16_swap_b32_e32 v51, v254
	s_waitcnt lgkmcnt(0)
	v_add_f32_e32 v50, v254, v51
	v_mov_b32_e32 v51, v50
	v_mov_b32_e32 v254, v50
	s_nop 1
	v_permlane32_swap_b32_e32 v51, v254
	s_and_saveexec_b64 s[2:3], s[6:7]
	s_cbranch_execz .LBB0_644
	s_waitcnt lgkmcnt(0)
	v_add_f32_e32 v50, v254, v51
	v_fmamk_f32 v50, v50, 0x3a800000, v241
	v_mul_f32_e32 v51, 0x4b800000, v50
	v_cmp_gt_f32_e32 vcc, s21, v50
	s_add_u32 s12, s0, s10
	s_addc_u32 s13, s1, s11
	v_cndmask_b32_e32 v50, v50, v51, vcc
	v_rsq_f32_e32 v50, v50
	s_nop 0
	v_mul_f32_e32 v51, 0x45800000, v50
	v_cndmask_b32_e32 v52, v50, v51, vcc
	v_mov_b32_e32 v50, s12
	v_add_co_u32_e32 v50, vcc, 0x3b750000, v50
	v_mov_b32_e32 v51, s13
	s_nop 0
	v_addc_co_u32_e32 v51, vcc, 0, v51, vcc
	global_store_dword v[50:51], v52, off offset:4
; __device__ __forceinline__ unsigned cvtpk(float lo, float hi) { f32x2 v = {lo, hi}; bf16x2_t b = __builtin_convertvector(v, bf16x2_t); return __builtin_bit_cast(unsigned, b); }
; __device__ __forceinline__ float bflo(unsigned u) { return __uint_as_float(u << 16); }
; __device__ __forceinline__ float bfhi(unsigned u) { return __uint_as_float(u & 0xffff0000u); }
; __device__ __forceinline__ float wave_sum(float v) {
; #pragma unroll
;     for (int o = 1; o < 64; o <<= 1) v += __shfl_xor(v, o);
;     return v;
; template <int NR, bool XBF, bool WOUT, bool WXB = true>
; __device__ __forceinline__ void rows_final(const float* xp, const float* xs, const bf16_t* __restrict__ Y, const float* __restrict__ ss, const float* __restrict__ gpost, float* out, bf16_t* xb, float* rs, int row0, int lane) {
;     ...
; #pragma unroll
;     for (int r = 0; r < NR; ++r) { const int row = row0 + r;
;         const float rn = rsqrtf(wave_sum(ssl[r]) * (1.f / DM) + EPS); float s = 0.f;
; #pragma unroll
;         for (int j = 0; j < 4; ++j) { const f32x4 yf = {bflo(yy[r][j].x), bfhi(yy[r][j].x), bflo(yy[r][j].y), bfhi(yy[r][j].y)};
;             v[r][j] = v[r][j] + yf * rn * g[j]; s += (v[r][j][0] * v[r][j][0] + v[r][j][1] * v[r][j][1]) + (v[r][j][2] * v[r][j][2] + v[r][j][3] * v[r][j][3]); }
;         s = wave_sum(s);
;         f32x4* oo = (f32x4*)(out + (size_t)row * DM) + lane; u32x2* o = (u32x2*)(xb + (size_t)row * DM) + lane;
; #pragma unroll
;         for (int j = 0; j < 4; ++j) { if (WOUT) oo[64 * j] = v[r][j]; if (WXB) { u32x2 w; w.x = cvtpk(v[r][j][0], v[r][j][1]); w.y = cvtpk(v[r][j][2], v[r][j][3]); o[64 * j] = w; } }
;         if (WXB && lane == 0) rs[row] = rsqrtf(s * (1.f / DM) + EPS); }
.LBB0_644:
	s_or_b64 exec, exec, s[2:3]
	s_nop 1
	v_mov_b32_dpp v50, v128 quad_perm:[1,0,3,2] row_mask:0xf bank_mask:0xf
	v_lshlrev_b32_e32 v52, 16, v102
	v_and_b32_e32 v53, 0xffff0000, v102
	v_lshlrev_b32_e32 v54, 16, v103
	v_and_b32_e32 v55, 0xffff0000, v103
	s_waitcnt lgkmcnt(0)
	v_add_f32_e32 v50, v128, v50
	s_nop 1
	v_mov_b32_dpp v51, v50 quad_perm:[2,3,0,1] row_mask:0xf bank_mask:0xf
	s_mov_b32 s2, 0x2d001000
	s_waitcnt lgkmcnt(0)
	v_add_f32_e32 v50, v50, v51
	s_nop 1
	v_mov_b32_dpp v51, v50 row_half_mirror row_mask:0xf bank_mask:0xf
	s_waitcnt lgkmcnt(0)
	v_add_f32_e32 v50, v50, v51
	s_nop 1
	v_mov_b32_dpp v51, v50 row_mirror row_mask:0xf bank_mask:0xf
	s_waitcnt lgkmcnt(0)
	v_add_f32_e32 v50, v50, v51
	v_mov_b32_e32 v51, v50
	v_mov_b32_e32 v254, v50
	s_nop 1
	v_permlane16_swap_b32_e32 v51, v254
	s_waitcnt lgkmcnt(0)
	v_add_f32_e32 v50, v254, v51
	v_mov_b32_e32 v51, v50
	v_mov_b32_e32 v254, v50
	s_nop 1
	v_permlane32_swap_b32_e32 v51, v254
	s_waitcnt lgkmcnt(0)
	v_add_f32_e32 v50, v254, v51
	v_fmamk_f32 v50, v50, 0x3a800000, v241
	v_cmp_gt_f32_e32 vcc, s21, v50
	v_mul_f32_e32 v51, 0x4b800000, v50
	s_nop 0
	v_cndmask_b32_e32 v50, v50, v51, vcc
	v_rsq_f32_e32 v50, v50
	s_nop 0
	v_mul_f32_e32 v51, 0x45800000, v50
	v_cndmask_b32_e32 v50, v50, v51, vcc
	v_pk_mul_f32 v[52:53], v[50:51], v[52:53] op_sel_hi:[0,1]
	v_pk_mul_f32 v[54:55], v[50:51], v[54:55] op_sel_hi:[0,1]
	v_pk_fma_f32 v[48:49], v[4:5], v[54:55], v[48:49]
	v_pk_fma_f32 v[46:47], v[2:3], v[52:53], v[46:47]
	v_mul_f32_e32 v52, v49, v49
	v_mul_f32_e32 v51, v47, v47
	v_fmac_f32_e32 v51, v46, v46
	v_fmac_f32_e32 v52, v48, v48
	v_add_f32_e32 v51, v51, v52
	v_lshlrev_b32_e32 v52, 16, v100
	v_and_b32_e32 v53, 0xffff0000, v100
	v_lshlrev_b32_e32 v54, 16, v101
	v_and_b32_e32 v55, 0xffff0000, v101
	v_pk_mul_f32 v[52:53], v[50:51], v[52:53] op_sel_hi:[0,1]
	v_pk_mul_f32 v[54:55], v[50:51], v[54:55] op_sel_hi:[0,1]
	v_pk_fma_f32 v[44:45], v[8:9], v[54:55], v[44:45]
	v_pk_fma_f32 v[42:43], v[6:7], v[52:53], v[42:43]
	v_mul_f32_e32 v53, v45, v45
	v_mul_f32_e32 v52, v43, v43
	v_fmac_f32_e32 v52, v42, v42
	v_fmac_f32_e32 v53, v44, v44
	v_add_f32_e32 v52, v52, v53
	v_add_f32_e32 v51, v51, v52
	v_lshlrev_b32_e32 v52, 16, v98
	v_and_b32_e32 v53, 0xffff0000, v98
	v_lshlrev_b32_e32 v54, 16, v99
	v_and_b32_e32 v55, 0xffff0000, v99
	v_pk_mul_f32 v[52:53], v[50:51], v[52:53] op_sel_hi:[0,1]
	v_pk_mul_f32 v[54:55], v[50:51], v[54:55] op_sel_hi:[0,1]
	v_pk_fma_f32 v[40:41], v[12:13], v[54:55], v[40:41]
	v_pk_fma_f32 v[38:39], v[10:11], v[52:53], v[38:39]
	v_mul_f32_e32 v53, v41, v41
	v_mul_f32_e32 v52, v39, v39
	v_fmac_f32_e32 v52, v38, v38
	v_fmac_f32_e32 v53, v40, v40
	v_add_f32_e32 v52, v52, v53
	v_add_f32_e32 v56, v52, v51
	v_lshlrev_b32_e32 v52, 16, v96
	v_and_b32_e32 v53, 0xffff0000, v96
	v_lshlrev_b32_e32 v54, 16, v97
	v_and_b32_e32 v55, 0xffff0000, v97
	v_pk_mul_f32 v[52:53], v[50:51], v[52:53] op_sel_hi:[0,1]
	v_pk_mul_f32 v[50:51], v[50:51], v[54:55] op_sel_hi:[0,1]
	v_pk_fma_f32 v[50:51], v[16:17], v[50:51], v[36:37]
	v_pk_fma_f32 v[52:53], v[14:15], v[52:53], v[34:35]
	v_mul_f32_e32 v35, v51, v51
	v_mul_f32_e32 v34, v53, v53
	v_fmac_f32_e32 v34, v52, v52
	v_fmac_f32_e32 v35, v50, v50
	v_add_f32_e32 v34, v34, v35
	v_add_f32_e32 v34, v34, v56
	s_nop 1
	v_mov_b32_dpp v35, v34 quad_perm:[1,0,3,2] row_mask:0xf bank_mask:0xf
	v_cvt_pk_bf16_f32 v38, v38, v39
	v_cvt_pk_bf16_f32 v39, v40, v41
	v_cvt_pk_bf16_f32 v46, v46, v47
	v_cvt_pk_bf16_f32 v47, v48, v49
	s_waitcnt lgkmcnt(0)
	v_add_f32_e32 v34, v34, v35
	s_nop 1
	v_mov_b32_dpp v35, v34 quad_perm:[2,3,0,1] row_mask:0xf bank_mask:0xf
	v_cvt_pk_bf16_f32 v42, v42, v43
	v_cvt_pk_bf16_f32 v43, v44, v45
	s_waitcnt lgkmcnt(0)
	v_add_f32_e32 v34, v34, v35
	s_nop 1
	v_mov_b32_dpp v35, v34 row_half_mirror row_mask:0xf bank_mask:0xf
	s_waitcnt lgkmcnt(0)
	v_add_f32_e32 v34, v34, v35
	s_nop 1
	v_mov_b32_dpp v35, v34 row_mirror row_mask:0xf bank_mask:0xf
	s_waitcnt lgkmcnt(0)
	v_add_f32_e32 v34, v34, v35
	v_mov_b32_e32 v35, v34
	v_mov_b32_e32 v254, v34
	s_nop 1
	v_permlane16_swap_b32_e32 v35, v254
	s_waitcnt lgkmcnt(0)
	v_add_f32_e32 v36, v254, v35
	v_mov_b32_e32 v37, v36
	v_mov_b32_e32 v254, v36
	s_nop 1
	v_permlane32_swap_b32_e32 v37, v254
	v_add_co_u32_e32 v34, vcc, s2, v90
	s_nop 1
	v_addc_co_u32_e32 v35, vcc, 0, v91, vcc
	global_store_dwordx2 v[34:35], v[38:39], off offset:1024
	v_cvt_pk_bf16_f32 v38, v52, v53
	v_cvt_pk_bf16_f32 v39, v50, v51
	global_store_dwordx2 v[34:35], v[46:47], off
	global_store_dwordx2 v[34:35], v[42:43], off offset:512
	global_store_dwordx2 v[34:35], v[38:39], off offset:1536
	s_and_saveexec_b64 s[2:3], s[6:7]
	s_cbranch_execz .LBB0_646
	s_waitcnt lgkmcnt(0)
	v_add_f32_e32 v36, v254, v37
	v_fmamk_f32 v36, v36, 0x3a800000, v241
	v_mul_f32_e32 v37, 0x4b800000, v36
	v_cmp_gt_f32_e32 vcc, s21, v36
	s_add_u32 s12, s0, s10
	s_addc_u32 s13, s1, s11
	v_cndmask_b32_e32 v36, v36, v37, vcc
	v_rsq_f32_e32 v36, v36
	s_nop 0
	v_mul_f32_e32 v37, 0x45800000, v36
	v_cndmask_b32_e32 v38, v36, v37, vcc
	v_mov_b32_e32 v36, s12
	v_add_co_u32_e32 v36, vcc, 0x3b750000, v36
	v_mov_b32_e32 v37, s13
	s_nop 0
	v_addc_co_u32_e32 v37, vcc, 0, v37, vcc
	global_store_dword v[36:37], v38, off offset:8
; __device__ __forceinline__ unsigned cvtpk(float lo, float hi) { f32x2 v = {lo, hi}; bf16x2_t b = __builtin_convertvector(v, bf16x2_t); return __builtin_bit_cast(unsigned, b); }
; __device__ __forceinline__ float bflo(unsigned u) { return __uint_as_float(u << 16); }
; __device__ __forceinline__ float bfhi(unsigned u) { return __uint_as_float(u & 0xffff0000u); }
; __device__ __forceinline__ float wave_sum(float v) {
; #pragma unroll
;     for (int o = 1; o < 64; o <<= 1) v += __shfl_xor(v, o);
;     return v;
; template <int NR, bool XBF, bool WOUT, bool WXB = true>
; __device__ __forceinline__ void rows_final(const float* xp, const float* xs, const bf16_t* __restrict__ Y, const float* __restrict__ ss, const float* __restrict__ gpost, float* out, bf16_t* xb, float* rs, int row0, int lane) {
;     ...
; #pragma unroll
;     for (int r = 0; r < NR; ++r) { const int row = row0 + r;
;         const float rn = rsqrtf(wave_sum(ssl[r]) * (1.f / DM) + EPS); float s = 0.f;
; #pragma unroll
;         for (int j = 0; j < 4; ++j) { const f32x4 yf = {bflo(yy[r][j].x), bfhi(yy[r][j].x), bflo(yy[r][j].y), bfhi(yy[r][j].y)};
;             v[r][j] = v[r][j] + yf * rn * g[j]; s += (v[r][j][0] * v[r][j][0] + v[r][j][1] * v[r][j][1]) + (v[r][j][2] * v[r][j][2] + v[r][j][3] * v[r][j][3]); }
;         s = wave_sum(s);
;         f32x4* oo = (f32x4*)(out + (size_t)row * DM) + lane; u32x2* o = (u32x2*)(xb + (size_t)row * DM) + lane;
; #pragma unroll
;         for (int j = 0; j < 4; ++j) { if (WOUT) oo[64 * j] = v[r][j]; if (WXB) { u32x2 w; w.x = cvtpk(v[r][j][0], v[r][j][1]); w.y = cvtpk(v[r][j][2], v[r][j][3]); o[64 * j] = w; } }
;         if (WXB && lane == 0) rs[row] = rsqrtf(s * (1.f / DM) + EPS); }
.LBB0_646:
	s_or_b64 exec, exec, s[2:3]
	s_nop 1
	v_mov_b32_dpp v36, v127 quad_perm:[1,0,3,2] row_mask:0xf bank_mask:0xf
	s_waitcnt vmcnt(0)
	v_lshlrev_b32_e32 v38, 16, v94
	v_and_b32_e32 v39, 0xffff0000, v94
	v_lshlrev_b32_e32 v40, 16, v95
	v_and_b32_e32 v41, 0xffff0000, v95
	s_waitcnt lgkmcnt(0)
	v_add_f32_e32 v36, v127, v36
	s_nop 1
	v_mov_b32_dpp v37, v36 quad_perm:[2,3,0,1] row_mask:0xf bank_mask:0xf
	s_waitcnt lgkmcnt(0)
	v_add_f32_e32 v36, v36, v37
	s_nop 1
	v_mov_b32_dpp v37, v36 row_half_mirror row_mask:0xf bank_mask:0xf
	s_waitcnt lgkmcnt(0)
	v_add_f32_e32 v36, v36, v37
	s_nop 1
	v_mov_b32_dpp v37, v36 row_mirror row_mask:0xf bank_mask:0xf
	s_waitcnt lgkmcnt(0)
	v_add_f32_e32 v36, v36, v37
	v_mov_b32_e32 v37, v36
	v_mov_b32_e32 v254, v36
	s_nop 1
	v_permlane16_swap_b32_e32 v37, v254
	s_waitcnt lgkmcnt(0)
	v_add_f32_e32 v36, v254, v37
	v_mov_b32_e32 v37, v36
	v_mov_b32_e32 v254, v36
	s_nop 1
	v_permlane32_swap_b32_e32 v37, v254
	s_waitcnt lgkmcnt(0)
	v_add_f32_e32 v36, v254, v37
	v_fmamk_f32 v36, v36, 0x3a800000, v241
	v_cmp_gt_f32_e32 vcc, s21, v36
	v_mul_f32_e32 v37, 0x4b800000, v36
	s_nop 0
	v_cndmask_b32_e32 v36, v36, v37, vcc
	v_rsq_f32_e32 v36, v36
	s_nop 0
	v_mul_f32_e32 v37, 0x45800000, v36
	v_cndmask_b32_e32 v36, v36, v37, vcc
	v_pk_mul_f32 v[38:39], v[36:37], v[38:39] op_sel_hi:[0,1]
	v_pk_mul_f32 v[40:41], v[36:37], v[40:41] op_sel_hi:[0,1]
	v_pk_fma_f32 v[32:33], v[4:5], v[40:41], v[32:33]
	v_pk_fma_f32 v[30:31], v[2:3], v[38:39], v[30:31]
	v_mul_f32_e32 v38, v33, v33
	v_mul_f32_e32 v37, v31, v31
	v_fmac_f32_e32 v37, v30, v30
	v_fmac_f32_e32 v38, v32, v32
	v_add_f32_e32 v37, v37, v38
	v_lshlrev_b32_e32 v38, 16, v92
	v_and_b32_e32 v39, 0xffff0000, v92
	v_lshlrev_b32_e32 v40, 16, v93
	v_and_b32_e32 v41, 0xffff0000, v93
	v_pk_mul_f32 v[38:39], v[36:37], v[38:39] op_sel_hi:[0,1]
	v_pk_mul_f32 v[40:41], v[36:37], v[40:41] op_sel_hi:[0,1]
	v_pk_fma_f32 v[28:29], v[8:9], v[40:41], v[28:29]
	v_pk_fma_f32 v[26:27], v[6:7], v[38:39], v[26:27]
	v_mul_f32_e32 v39, v29, v29
	v_mul_f32_e32 v38, v27, v27
	v_fmac_f32_e32 v38, v26, v26
	v_fmac_f32_e32 v39, v28, v28
	v_add_f32_e32 v38, v38, v39
	v_add_f32_e32 v37, v37, v38
	v_lshlrev_b32_e32 v38, 16, v88
	v_and_b32_e32 v39, 0xffff0000, v88
	v_lshlrev_b32_e32 v40, 16, v89
	v_and_b32_e32 v41, 0xffff0000, v89
	v_pk_mul_f32 v[38:39], v[36:37], v[38:39] op_sel_hi:[0,1]
	v_pk_mul_f32 v[40:41], v[36:37], v[40:41] op_sel_hi:[0,1]
	v_pk_fma_f32 v[24:25], v[12:13], v[40:41], v[24:25]
	v_pk_fma_f32 v[22:23], v[10:11], v[38:39], v[22:23]
	v_mul_f32_e32 v39, v25, v25
	v_mul_f32_e32 v38, v23, v23
	v_fmac_f32_e32 v38, v22, v22
	v_fmac_f32_e32 v39, v24, v24
	v_add_f32_e32 v38, v38, v39
	v_add_f32_e32 v42, v38, v37
	v_lshlrev_b32_e32 v38, 16, v86
	v_and_b32_e32 v39, 0xffff0000, v86
	v_lshlrev_b32_e32 v40, 16, v87
	v_and_b32_e32 v41, 0xffff0000, v87
	v_pk_mul_f32 v[38:39], v[36:37], v[38:39] op_sel_hi:[0,1]
	v_pk_mul_f32 v[36:37], v[36:37], v[40:41] op_sel_hi:[0,1]
	v_pk_fma_f32 v[20:21], v[16:17], v[36:37], v[20:21]
	v_pk_fma_f32 v[36:37], v[14:15], v[38:39], v[18:19]
	v_mul_f32_e32 v19, v21, v21
	v_mul_f32_e32 v18, v37, v37
	v_fmac_f32_e32 v18, v36, v36
	v_fmac_f32_e32 v19, v20, v20
	v_add_f32_e32 v18, v18, v19
	v_add_f32_e32 v18, v18, v42
	s_nop 1
	v_mov_b32_dpp v19, v18 quad_perm:[1,0,3,2] row_mask:0xf bank_mask:0xf
	v_cvt_pk_bf16_f32 v22, v22, v23
	v_cvt_pk_bf16_f32 v23, v24, v25
	v_cvt_pk_bf16_f32 v30, v30, v31
	v_cvt_pk_bf16_f32 v31, v32, v33
	s_waitcnt lgkmcnt(0)
	v_add_f32_e32 v18, v18, v19
	s_nop 1
	v_mov_b32_dpp v19, v18 quad_perm:[2,3,0,1] row_mask:0xf bank_mask:0xf
	v_cvt_pk_bf16_f32 v26, v26, v27
	v_cvt_pk_bf16_f32 v27, v28, v29
	global_store_dwordx2 v[34:35], v[22:23], off offset:3072
	v_cvt_pk_bf16_f32 v22, v36, v37
	s_waitcnt lgkmcnt(0)
	v_add_f32_e32 v18, v18, v19
	s_nop 1
	v_mov_b32_dpp v19, v18 row_half_mirror row_mask:0xf bank_mask:0xf
	v_cvt_pk_bf16_f32 v23, v20, v21
	global_store_dwordx2 v[34:35], v[30:31], off offset:2048
	global_store_dwordx2 v[34:35], v[26:27], off offset:2560
	global_store_dwordx2 v[34:35], v[22:23], off offset:3584
	s_waitcnt lgkmcnt(0)
	v_add_f32_e32 v18, v18, v19
	s_nop 1
	v_mov_b32_dpp v19, v18 row_mirror row_mask:0xf bank_mask:0xf
	s_waitcnt lgkmcnt(0)
	v_add_f32_e32 v18, v18, v19
	v_mov_b32_e32 v19, v18
	v_mov_b32_e32 v254, v18
	s_nop 1
	v_permlane16_swap_b32_e32 v19, v254
	s_waitcnt lgkmcnt(0)
	v_add_f32_e32 v18, v254, v19
	v_mov_b32_e32 v19, v18
	v_mov_b32_e32 v254, v18
	s_nop 1
	v_permlane32_swap_b32_e32 v19, v254
	s_and_saveexec_b64 s[2:3], s[6:7]
	s_cbranch_execz .LBB0_631
	s_waitcnt lgkmcnt(0)
	v_add_f32_e32 v18, v254, v19
	v_fmamk_f32 v18, v18, 0x3a800000, v241
	v_mul_f32_e32 v19, 0x4b800000, v18
	v_cmp_gt_f32_e32 vcc, s21, v18
	s_add_u32 s12, s0, s10
	s_addc_u32 s13, s1, s11
	v_cndmask_b32_e32 v18, v18, v19, vcc
	v_rsq_f32_e32 v18, v18
	s_nop 0
	v_mul_f32_e32 v19, 0x45800000, v18
	v_cndmask_b32_e32 v20, v18, v19, vcc
	v_mov_b32_e32 v18, s12
	v_add_co_u32_e32 v18, vcc, 0x3b750000, v18
	v_mov_b32_e32 v19, s13
	s_nop 0
	v_addc_co_u32_e32 v19, vcc, 0, v19, vcc
	global_store_dword v[18:19], v20, off offset:12
	s_branch .LBB0_631

; __device__ __forceinline__ float bflo(unsigned u) { return __uint_as_float(u << 16); }
; __device__ __forceinline__ float bfhi(unsigned u) { return __uint_as_float(u & 0xffff0000u); }
; __device__ __forceinline__ float wave_sum(float v) {
; #pragma unroll
;     for (int o = 1; o < 64; o <<= 1) v += __shfl_xor(v, o);
;     return v;
; template <int NR, bool XBF, bool WOUT, bool WXB = true>
; __device__ __forceinline__ void rows_final(const float* xp, const float* xs, const bf16_t* __restrict__ Y, const float* __restrict__ ss, const float* __restrict__ gpost, float* out, bf16_t* xb, float* rs, int row0, int lane) {
;     ...
;     for (int r = 0; r < NR; ++r) { const int row = row0 + r;
;         const float* xrow = (row < NP_TOK) ? xp + (size_t)row * DM : xs + (size_t)(row - NP_TOK) * DM;
;         ssl[r] = (lane < 32) ? ss[(size_t)row * 32 + lane] : 0.f;
; #pragma unroll
;         for (int j = 0; j < 4; ++j) {
;             if (XBF) { const u32x2 xw = *((const u32x2*)(xb + (size_t)row * DM) + lane + 64 * j); v[r][j] = (f32x4){bflo(xw.x), bfhi(xw.x), bflo(xw.y), bfhi(xw.y)}; }
;             else v[r][j] = *((const f32x4*)xrow + lane + 64 * j);
;             yy[r][j] = *((const u32x2*)(Y + (size_t)row * DM) + lane + 64 * j); } }
;     f32x4 g[4];
; #pragma unroll
;     for (int j = 0; j < 4; ++j) g[j] = *((const f32x4*)gpost + lane + 64 * j);
; #pragma unroll
;     for (int r = 0; r < NR; ++r) { const int row = row0 + r;
;         const float rn = rsqrtf(wave_sum(ssl[r]) * (1.f / DM) + EPS); float s = 0.f;
; #pragma unroll
;         for (int j = 0; j < 4; ++j) { const f32x4 yf = {bflo(yy[r][j].x), bfhi(yy[r][j].x), bflo(yy[r][j].y), bfhi(yy[r][j].y)};
;             v[r][j] = v[r][j] + yf * rn * g[j]; s += (v[r][j][0] * v[r][j][0] + v[r][j][1] * v[r][j][1]) + (v[r][j][2] * v[r][j][2] + v[r][j][3] * v[r][j][3]); }
;         s = wave_sum(s);
.LBB0_852:
	s_or_b64 exec, exec, s[8:9]
	s_mov_b32 s7, 0x2d001000
	v_add_co_u32_e32 v34, vcc, s7, v40
	s_waitcnt vmcnt(0) lgkmcnt(0)
	v_lshlrev_b32_e32 v126, 16, v46
	v_addc_co_u32_e32 v35, vcc, 0, v41, vcc
	global_load_dwordx2 v[78:79], v[34:35], off offset:2048
	global_load_dwordx2 v[80:81], v[34:35], off offset:2560
	global_load_dwordx2 v[112:113], v[34:35], off offset:3072
	global_load_dwordx2 v[114:115], v[34:35], off offset:3584
	v_and_b32_e32 v127, 0xffff0000, v46
	v_lshlrev_b32_e32 v128, 16, v47
	v_and_b32_e32 v129, 0xffff0000, v47
	s_nop 1
	v_mov_b32_dpp v47, v37 quad_perm:[1,0,3,2] row_mask:0xf bank_mask:0xf
	s_nop 1
	v_mov_b32_dpp v46, v36 quad_perm:[1,0,3,2] row_mask:0xf bank_mask:0xf
	v_lshlrev_b32_e32 v130, 16, v42
	v_and_b32_e32 v131, 0xffff0000, v42
	v_lshlrev_b32_e32 v132, 16, v43
	v_and_b32_e32 v133, 0xffff0000, v43
	s_waitcnt lgkmcnt(0)
	v_pk_add_f32 v[36:37], v[36:37], v[46:47]
	s_nop 1
	v_mov_b32_dpp v43, v37 quad_perm:[2,3,0,1] row_mask:0xf bank_mask:0xf
	s_nop 1
	v_mov_b32_dpp v42, v36 quad_perm:[2,3,0,1] row_mask:0xf bank_mask:0xf
	v_lshlrev_b32_e32 v136, 16, v86
	v_and_b32_e32 v137, 0xffff0000, v86
	v_lshlrev_b32_e32 v138, 16, v87
	v_and_b32_e32 v139, 0xffff0000, v87
	s_waitcnt lgkmcnt(0)
	v_pk_add_f32 v[134:135], v[36:37], v[42:43]
	s_mov_b32 s7, 0x1e001000
	v_lshlrev_b32_e32 v94, 16, v70
	v_and_b32_e32 v95, 0xffff0000, v70
	v_add_co_u32_e32 v70, vcc, s7, v40
	s_mov_b32 s8, 0x358637bd
	v_lshlrev_b32_e32 v96, 16, v71
	v_and_b32_e32 v97, 0xffff0000, v71
	v_addc_co_u32_e32 v71, vcc, 0, v41, vcc
	v_lshlrev_b32_e32 v140, 16, v84
	v_and_b32_e32 v141, 0xffff0000, v84
	v_lshlrev_b32_e32 v90, 16, v74
	v_and_b32_e32 v91, 0xffff0000, v74
	v_lshlrev_b32_e32 v92, 16, v75
	v_and_b32_e32 v93, 0xffff0000, v75
	v_lshlrev_b32_e32 v98, 16, v64
	v_and_b32_e32 v99, 0xffff0000, v64
	v_lshlrev_b32_e32 v100, 16, v65
	v_and_b32_e32 v101, 0xffff0000, v65
	v_lshlrev_b32_e32 v102, 16, v60
	v_and_b32_e32 v103, 0xffff0000, v60
	v_lshlrev_b32_e32 v124, 16, v61
	v_and_b32_e32 v125, 0xffff0000, v61
	v_lshlrev_b32_e32 v120, 16, v54
	v_and_b32_e32 v121, 0xffff0000, v54
	v_lshlrev_b32_e32 v122, 16, v55
	v_and_b32_e32 v123, 0xffff0000, v55
	v_lshlrev_b32_e32 v116, 16, v52
	v_and_b32_e32 v117, 0xffff0000, v52
	v_lshlrev_b32_e32 v118, 16, v53
	v_and_b32_e32 v119, 0xffff0000, v53
	v_lshlrev_b32_e32 v142, 16, v82
	v_and_b32_e32 v143, 0xffff0000, v82
	v_lshlrev_b32_e32 v82, 16, v83
	v_and_b32_e32 v83, 0xffff0000, v83
	s_movk_i32 s7, 0x1000
	v_lshlrev_b32_e32 v44, 16, v48
	v_and_b32_e32 v45, 0xffff0000, v48
	v_lshlrev_b32_e32 v48, 16, v49
	v_and_b32_e32 v49, 0xffff0000, v49
	v_lshlrev_b32_e32 v66, 16, v68
	v_and_b32_e32 v67, 0xffff0000, v68
	v_lshlrev_b32_e32 v68, 16, v69
	v_and_b32_e32 v69, 0xffff0000, v69
	v_lshlrev_b32_e32 v34, 16, v38
	v_and_b32_e32 v35, 0xffff0000, v38
	v_lshlrev_b32_e32 v56, 16, v58
	v_and_b32_e32 v57, 0xffff0000, v58
	v_lshlrev_b32_e32 v38, 16, v39
	v_and_b32_e32 v39, 0xffff0000, v39
	v_lshlrev_b32_e32 v58, 16, v59
	v_and_b32_e32 v59, 0xffff0000, v59
	s_waitcnt vmcnt(0)
	v_lshlrev_b32_e32 v60, 16, v78
	v_and_b32_e32 v61, 0xffff0000, v78
	v_lshlrev_b32_e32 v42, 16, v112
	v_and_b32_e32 v43, 0xffff0000, v112
	v_lshlrev_b32_e32 v46, 16, v113
	v_and_b32_e32 v47, 0xffff0000, v113
	s_nop 1
	v_mov_b32_dpp v113, v135 row_half_mirror row_mask:0xf bank_mask:0xf
	s_nop 1
	v_mov_b32_dpp v112, v134 row_half_mirror row_mask:0xf bank_mask:0xf
	v_lshlrev_b32_e32 v64, 16, v79
	v_and_b32_e32 v65, 0xffff0000, v79
	v_lshlrev_b32_e32 v52, 16, v80
	v_and_b32_e32 v53, 0xffff0000, v80
	s_waitcnt lgkmcnt(0)
	v_pk_add_f32 v[112:113], v[134:135], v[112:113]
	s_nop 1
	v_mov_b32_dpp v135, v113 row_mirror row_mask:0xf bank_mask:0xf
	s_nop 1
	v_mov_b32_dpp v134, v112 row_mirror row_mask:0xf bank_mask:0xf
	v_lshlrev_b32_e32 v54, 16, v81
	v_and_b32_e32 v55, 0xffff0000, v81
	global_load_dwordx2 v[80:81], v[70:71], off offset:2048
	global_load_dwordx2 v[78:79], v[70:71], off offset:2560
	global_load_dwordx2 v[74:75], v[70:71], off offset:3072
	s_nop 0
	global_load_dwordx2 v[70:71], v[70:71], off offset:3584
	v_lshlrev_b32_e32 v36, 16, v114
	s_waitcnt lgkmcnt(0)
	v_pk_add_f32 v[112:113], v[112:113], v[134:135]
	v_mov_b32_e32 v135, v113
	v_mov_b32_e32 v255, v113
	s_nop 1
	v_permlane16_swap_b32_e32 v135, v255
	v_mov_b32_e32 v134, v112
	v_mov_b32_e32 v254, v112
	s_nop 1
	v_permlane16_swap_b32_e32 v134, v254
	v_and_b32_e32 v37, 0xffff0000, v114
	v_lshlrev_b32_e32 v40, 16, v115
	v_and_b32_e32 v41, 0xffff0000, v115
	v_lshlrev_b32_e32 v114, 16, v88
	s_waitcnt lgkmcnt(0)
	v_pk_add_f32 v[86:87], v[254:255], v[134:135]
	v_mov_b32_e32 v113, v87
	v_mov_b32_e32 v255, v87
	s_nop 1
	v_permlane32_swap_b32_e32 v113, v255
	v_mov_b32_e32 v112, v86
	v_mov_b32_e32 v254, v86
	s_nop 1
	v_permlane32_swap_b32_e32 v112, v254
	v_lshlrev_b32_e32 v134, 16, v85
	v_and_b32_e32 v135, 0xffff0000, v85
	v_mov_b64_e32 v[84:85], s[8:9]
	s_mov_b32 s8, 0x3a800000
	s_waitcnt lgkmcnt(0)
; __device__ __forceinline__ unsigned cvtpk(float lo, float hi) { f32x2 v = {lo, hi}; bf16x2_t b = __builtin_convertvector(v, bf16x2_t); return __builtin_bit_cast(unsigned, b); }
; __device__ __forceinline__ float bflo(unsigned u) { return __uint_as_float(u << 16); }
; __device__ __forceinline__ float bfhi(unsigned u) { return __uint_as_float(u & 0xffff0000u); }
; __device__ __forceinline__ float wave_sum(float v) {
; #pragma unroll
;     for (int o = 1; o < 64; o <<= 1) v += __shfl_xor(v, o);
;     return v;
; template <int NR, bool XBF, bool WOUT, bool WXB = true>
; __device__ __forceinline__ void rows_final(const float* xp, const float* xs, const bf16_t* __restrict__ Y, const float* __restrict__ ss, const float* __restrict__ gpost, float* out, bf16_t* xb, float* rs, int row0, int lane) {
;     ...
;     for (int r = 0; r < NR; ++r) { const int row = row0 + r;
;         const float rn = rsqrtf(wave_sum(ssl[r]) * (1.f / DM) + EPS); float s = 0.f;
; #pragma unroll
;         for (int j = 0; j < 4; ++j) { const f32x4 yf = {bflo(yy[r][j].x), bfhi(yy[r][j].x), bflo(yy[r][j].y), bfhi(yy[r][j].y)};
;             v[r][j] = v[r][j] + yf * rn * g[j]; s += (v[r][j][0] * v[r][j][0] + v[r][j][1] * v[r][j][1]) + (v[r][j][2] * v[r][j][2] + v[r][j][3] * v[r][j][3]); }
;         s = wave_sum(s);
;         f32x4* oo = (f32x4*)(out + (size_t)row * DM) + lane; u32x2* o = (u32x2*)(xb + (size_t)row * DM) + lane;
; #pragma unroll
;         for (int j = 0; j < 4; ++j) { if (WOUT) oo[64 * j] = v[r][j]; if (WXB) { u32x2 w; w.x = cvtpk(v[r][j][0], v[r][j][1]); w.y = cvtpk(v[r][j][2], v[r][j][3]); o[64 * j] = w; } }
	v_pk_add_f32 v[86:87], v[254:255], v[112:113]
	v_and_b32_e32 v115, 0xffff0000, v88
	v_pk_fma_f32 v[144:145], v[86:87], s[8:9], v[84:85] op_sel_hi:[1,0,0]
	v_lshlrev_b32_e32 v88, 16, v89
	v_mul_f32_e32 v0, 0x4b800000, v145
	v_cmp_gt_f32_e32 vcc, s21, v145
	v_and_b32_e32 v89, 0xffff0000, v89
	s_nop 0
	v_cndmask_b32_e32 v0, v145, v0, vcc
	v_rsq_f32_e32 v0, v0
	s_nop 0
	v_mul_f32_e32 v86, 0x45800000, v0
	v_cndmask_b32_e32 v0, v0, v86, vcc
	v_pk_mul_f32 v[112:113], v[0:1], v[136:137] op_sel_hi:[0,1]
	v_pk_mul_f32 v[86:87], v[0:1], v[114:115] op_sel_hi:[0,1]
	v_pk_mul_f32 v[114:115], v[0:1], v[138:139] op_sel_hi:[0,1]
	v_pk_fma_f32 v[112:113], v[6:7], v[112:113], v[126:127]
	v_pk_mul_f32 v[126:127], v[0:1], v[140:141] op_sel_hi:[0,1]
	v_pk_mul_f32 v[88:89], v[0:1], v[88:89] op_sel_hi:[0,1]
	v_pk_fma_f32 v[114:115], v[8:9], v[114:115], v[128:129]
	v_pk_mul_f32 v[128:129], v[0:1], v[134:135] op_sel_hi:[0,1]
	v_pk_fma_f32 v[116:117], v[10:11], v[126:127], v[116:117]
	v_pk_mul_f32 v[126:127], v[0:1], v[142:143] op_sel_hi:[0,1]
	v_pk_mul_f32 v[82:83], v[0:1], v[82:83] op_sel_hi:[0,1]
	v_mul_f32_e32 v0, 0x4b800000, v144
	v_cmp_gt_f32_e32 vcc, s21, v144
	v_pk_fma_f32 v[122:123], v[16:17], v[82:83], v[122:123]
	v_and_b32_e32 v83, 0xffff0000, v76
	v_cndmask_b32_e32 v0, v144, v0, vcc
	v_rsq_f32_e32 v0, v0
	v_pk_fma_f32 v[88:89], v[4:5], v[88:89], v[132:133]
	v_pk_fma_f32 v[86:87], v[2:3], v[86:87], v[130:131]
	global_store_dwordx4 v[20:21], v[86:89], off
	v_mul_f32_e32 v82, 0x45800000, v0
	v_cndmask_b32_e32 v0, v0, v82, vcc
	v_lshlrev_b32_e32 v82, 16, v76
	v_lshlrev_b32_e32 v76, 16, v77
	v_and_b32_e32 v77, 0xffff0000, v77
	v_pk_mul_f32 v[76:77], v[0:1], v[76:77] op_sel_hi:[0,1]
	v_pk_fma_f32 v[88:89], v[4:5], v[76:77], v[124:125]
	v_lshlrev_b32_e32 v76, 16, v72
	v_and_b32_e32 v77, 0xffff0000, v72
	v_lshlrev_b32_e32 v72, 16, v73
	v_and_b32_e32 v73, 0xffff0000, v73
	v_pk_mul_f32 v[72:73], v[0:1], v[72:73] op_sel_hi:[0,1]
	v_pk_fma_f32 v[100:101], v[8:9], v[72:73], v[100:101]
	v_lshlrev_b32_e32 v72, 16, v62
	v_and_b32_e32 v73, 0xffff0000, v62
	v_lshlrev_b32_e32 v62, 16, v63
	v_and_b32_e32 v63, 0xffff0000, v63
	v_pk_mul_f32 v[62:63], v[0:1], v[62:63] op_sel_hi:[0,1]
	v_pk_fma_f32 v[96:97], v[12:13], v[62:63], v[96:97]
	v_lshlrev_b32_e32 v62, 16, v50
	v_and_b32_e32 v63, 0xffff0000, v50
	v_lshlrev_b32_e32 v50, 16, v51
	v_and_b32_e32 v51, 0xffff0000, v51
	v_pk_mul_f32 v[50:51], v[0:1], v[50:51] op_sel_hi:[0,1]
	v_pk_fma_f32 v[92:93], v[16:17], v[50:51], v[92:93]
	s_nop 1
	v_mov_b32_dpp v51, v27 quad_perm:[1,0,3,2] row_mask:0xf bank_mask:0xf
	s_nop 1
	v_mov_b32_dpp v50, v26 quad_perm:[1,0,3,2] row_mask:0xf bank_mask:0xf
	v_pk_mul_f32 v[62:63], v[0:1], v[62:63] op_sel_hi:[0,1]
	v_pk_fma_f32 v[90:91], v[14:15], v[62:63], v[90:91]
	v_add_co_u32_e32 v62, vcc, s7, v20
	s_waitcnt lgkmcnt(0)
	v_pk_add_f32 v[26:27], v[26:27], v[50:51]
	s_nop 1
	v_mov_b32_dpp v51, v27 quad_perm:[2,3,0,1] row_mask:0xf bank_mask:0xf
	s_nop 1
	v_mov_b32_dpp v50, v26 quad_perm:[2,3,0,1] row_mask:0xf bank_mask:0xf
	v_pk_mul_f32 v[72:73], v[0:1], v[72:73] op_sel_hi:[0,1]
	v_addc_co_u32_e32 v63, vcc, 0, v21, vcc
	s_movk_i32 s7, 0x2000
	s_waitcnt lgkmcnt(0)
	v_pk_add_f32 v[26:27], v[26:27], v[50:51]
	s_nop 1
	v_mov_b32_dpp v51, v27 row_half_mirror row_mask:0xf bank_mask:0xf
	s_nop 1
	v_mov_b32_dpp v50, v26 row_half_mirror row_mask:0xf bank_mask:0xf
	v_pk_fma_f32 v[94:95], v[10:11], v[72:73], v[94:95]
	v_add_co_u32_e32 v72, vcc, s7, v20
	v_pk_mul_f32 v[82:83], v[0:1], v[82:83] op_sel_hi:[0,1]
	s_waitcnt lgkmcnt(0)
	v_pk_add_f32 v[26:27], v[26:27], v[50:51]
	s_nop 1
	v_mov_b32_dpp v51, v27 row_mirror row_mask:0xf bank_mask:0xf
	s_nop 1
	v_mov_b32_dpp v50, v26 row_mirror row_mask:0xf bank_mask:0xf
	v_addc_co_u32_e32 v73, vcc, 0, v21, vcc
	v_pk_mul_f32 v[76:77], v[0:1], v[76:77] op_sel_hi:[0,1]
	v_pk_fma_f32 v[86:87], v[2:3], v[82:83], v[102:103]
	s_waitcnt lgkmcnt(0)
	v_pk_add_f32 v[26:27], v[26:27], v[50:51]
	v_mov_b32_e32 v51, v27
	v_mov_b32_e32 v255, v27
	s_nop 1
	v_permlane16_swap_b32_e32 v51, v255
	v_mov_b32_e32 v50, v26
	v_mov_b32_e32 v254, v26
	s_nop 1
	v_permlane16_swap_b32_e32 v50, v254
	v_pk_fma_f32 v[118:119], v[12:13], v[128:129], v[118:119]
	v_pk_fma_f32 v[120:121], v[14:15], v[126:127], v[120:121]
	global_store_dwordx4 v[20:21], v[112:115], off offset:1024
	global_store_dwordx4 v[20:21], v[116:119], off offset:2048
	global_store_dwordx4 v[20:21], v[120:123], off offset:3072
	v_pk_fma_f32 v[98:99], v[6:7], v[76:77], v[98:99]
	s_waitcnt lgkmcnt(0)
	v_pk_add_f32 v[26:27], v[254:255], v[50:51]
	v_mov_b32_e32 v51, v27
	v_mov_b32_e32 v255, v27
	s_nop 1
	v_permlane32_swap_b32_e32 v51, v255
	v_mov_b32_e32 v50, v26
	v_mov_b32_e32 v254, v26
	s_nop 1
	v_permlane32_swap_b32_e32 v50, v254
	global_store_dwordx4 v[72:73], v[86:89], off offset:-4096
	global_store_dwordx4 v[62:63], v[98:101], off offset:1024
	global_store_dwordx4 v[62:63], v[94:97], off offset:2048
	global_store_dwordx4 v[62:63], v[90:93], off offset:3072
	v_lshlrev_b32_e32 v88, 16, v24
	v_and_b32_e32 v89, 0xffff0000, v24
	s_waitcnt lgkmcnt(0)
; __device__ __forceinline__ unsigned cvtpk(float lo, float hi) { f32x2 v = {lo, hi}; bf16x2_t b = __builtin_convertvector(v, bf16x2_t); return __builtin_bit_cast(unsigned, b); }
; __device__ __forceinline__ float bflo(unsigned u) { return __uint_as_float(u << 16); }
; __device__ __forceinline__ float bfhi(unsigned u) { return __uint_as_float(u & 0xffff0000u); }
; template <int NR, bool XBF, bool WOUT, bool WXB = true>
; __device__ __forceinline__ void rows_final(const float* xp, const float* xs, const bf16_t* __restrict__ Y, const float* __restrict__ ss, const float* __restrict__ gpost, float* out, bf16_t* xb, float* rs, int row0, int lane) {
;     ...
;     for (int r = 0; r < NR; ++r) { const int row = row0 + r;
;         const float rn = rsqrtf(wave_sum(ssl[r]) * (1.f / DM) + EPS); float s = 0.f;
; #pragma unroll
;         for (int j = 0; j < 4; ++j) { const f32x4 yf = {bflo(yy[r][j].x), bfhi(yy[r][j].x), bflo(yy[r][j].y), bfhi(yy[r][j].y)};
;             v[r][j] = v[r][j] + yf * rn * g[j]; s += (v[r][j][0] * v[r][j][0] + v[r][j][1] * v[r][j][1]) + (v[r][j][2] * v[r][j][2] + v[r][j][3] * v[r][j][3]); }
;         s = wave_sum(s);
;         f32x4* oo = (f32x4*)(out + (size_t)row * DM) + lane; u32x2* o = (u32x2*)(xb + (size_t)row * DM) + lane;
; #pragma unroll
;         for (int j = 0; j < 4; ++j) { if (WOUT) oo[64 * j] = v[r][j]; if (WXB) { u32x2 w; w.x = cvtpk(v[r][j][0], v[r][j][1]); w.y = cvtpk(v[r][j][2], v[r][j][3]); o[64 * j] = w; } }
	v_pk_add_f32 v[26:27], v[254:255], v[50:51]
	v_lshlrev_b32_e32 v62, 16, v32
	v_pk_fma_f32 v[84:85], v[26:27], s[8:9], v[84:85] op_sel_hi:[1,0,0]
	v_and_b32_e32 v63, 0xffff0000, v32
	v_mul_f32_e32 v0, 0x4b800000, v85
	v_cmp_gt_f32_e32 vcc, s21, v85
	v_lshlrev_b32_e32 v32, 16, v33
	v_and_b32_e32 v33, 0xffff0000, v33
	v_cndmask_b32_e32 v0, v85, v0, vcc
	v_rsq_f32_e32 v0, v0
	v_lshlrev_b32_e32 v82, 16, v28
	v_and_b32_e32 v83, 0xffff0000, v28
	v_lshlrev_b32_e32 v86, 16, v29
	v_mul_f32_e32 v24, 0x45800000, v0
	v_and_b32_e32 v87, 0xffff0000, v29
	v_cndmask_b32_e32 v0, v0, v24, vcc
	v_lshlrev_b32_e32 v76, 16, v30
	v_and_b32_e32 v77, 0xffff0000, v30
	v_lshlrev_b32_e32 v30, 16, v31
	v_and_b32_e32 v31, 0xffff0000, v31
	v_lshlrev_b32_e32 v90, 16, v25
	v_and_b32_e32 v91, 0xffff0000, v25
	v_pk_mul_f32 v[26:27], v[0:1], v[32:33] op_sel_hi:[0,1]
	v_pk_mul_f32 v[32:33], v[0:1], v[82:83] op_sel_hi:[0,1]
	v_pk_mul_f32 v[50:51], v[0:1], v[86:87] op_sel_hi:[0,1]
	v_pk_mul_f32 v[24:25], v[0:1], v[62:63] op_sel_hi:[0,1]
	v_pk_mul_f32 v[28:29], v[0:1], v[76:77] op_sel_hi:[0,1]
	v_pk_mul_f32 v[30:31], v[0:1], v[30:31] op_sel_hi:[0,1]
	v_pk_fma_f32 v[50:51], v[12:13], v[50:51], v[48:49]
	v_pk_fma_f32 v[48:49], v[10:11], v[32:33], v[44:45]
	v_pk_mul_f32 v[32:33], v[0:1], v[88:89] op_sel_hi:[0,1]
	v_pk_mul_f32 v[44:45], v[0:1], v[90:91] op_sel_hi:[0,1]
	v_mul_f32_e32 v0, 0x4b800000, v84
	v_cmp_gt_f32_e32 vcc, s21, v84
	v_pk_fma_f32 v[26:27], v[4:5], v[26:27], v[68:69]
	v_pk_fma_f32 v[24:25], v[2:3], v[24:25], v[66:67]
	v_cndmask_b32_e32 v0, v84, v0, vcc
	v_rsq_f32_e32 v0, v0
	global_store_dwordx4 v[72:73], v[24:27], off
	v_readlane_b32 s8, v252, 40
	v_pk_fma_f32 v[28:29], v[6:7], v[28:29], v[56:57]
	v_mul_f32_e32 v24, 0x45800000, v0
	v_pk_fma_f32 v[56:57], v[14:15], v[32:33], v[34:35]
	v_cndmask_b32_e32 v0, v0, v24, vcc
	s_waitcnt vmcnt(0)
	v_lshlrev_b32_e32 v32, 16, v74
	v_and_b32_e32 v33, 0xffff0000, v74
	v_readlane_b32 s9, v252, 41
	v_pk_mul_f32 v[32:33], v[0:1], v[32:33] op_sel_hi:[0,1]
	s_add_i32 s6, s6, s8
	v_readlane_b32 s8, v252, 34
	v_pk_fma_f32 v[30:31], v[8:9], v[30:31], v[58:59]
	v_pk_fma_f32 v[58:59], v[16:17], v[44:45], v[38:39]
	v_pk_fma_f32 v[32:33], v[10:11], v[32:33], v[42:43]
	v_lshlrev_b32_e32 v38, 16, v70
	v_and_b32_e32 v39, 0xffff0000, v70
	v_lshlrev_b32_e32 v42, 16, v71
	v_and_b32_e32 v43, 0xffff0000, v71
	v_readlane_b32 s9, v252, 35
	v_pk_mul_f32 v[44:45], v[0:1], v[38:39] op_sel_hi:[0,1]
	v_pk_mul_f32 v[38:39], v[0:1], v[42:43] op_sel_hi:[0,1]
	s_movk_i32 s7, 0x3000
	v_lshl_add_u64 v[18:19], v[18:19], 0, s[8:9]
	v_readlane_b32 s8, v252, 42
	v_pk_fma_f32 v[38:39], v[16:17], v[38:39], v[40:41]
	v_add_co_u32_e32 v40, vcc, s7, v20
	v_readlane_b32 s9, v252, 43
	v_lshlrev_b32_e32 v24, 16, v80
	v_and_b32_e32 v25, 0xffff0000, v80
	v_lshlrev_b32_e32 v26, 16, v81
	v_and_b32_e32 v27, 0xffff0000, v81
	v_addc_co_u32_e32 v41, vcc, 0, v21, vcc
	v_lshl_add_u64 v[20:21], v[20:21], 0, s[8:9]
	v_readlane_b32 s8, v252, 38
	global_store_dwordx4 v[72:73], v[28:31], off offset:1024
	global_store_dwordx4 v[72:73], v[48:51], off offset:2048
	global_store_dwordx4 v[72:73], v[56:59], off offset:3072
	v_pk_mul_f32 v[24:25], v[0:1], v[24:25] op_sel_hi:[0,1]
	v_pk_mul_f32 v[26:27], v[0:1], v[26:27] op_sel_hi:[0,1]
	v_lshlrev_b32_e32 v28, 16, v78
	v_and_b32_e32 v29, 0xffff0000, v78
	v_lshlrev_b32_e32 v30, 16, v79
	v_and_b32_e32 v31, 0xffff0000, v79
	v_lshlrev_b32_e32 v34, 16, v75
	v_and_b32_e32 v35, 0xffff0000, v75
	v_readlane_b32 s9, v252, 39
	v_pk_fma_f32 v[26:27], v[4:5], v[26:27], v[64:65]
	v_pk_fma_f32 v[24:25], v[2:3], v[24:25], v[60:61]
	v_pk_mul_f32 v[28:29], v[0:1], v[28:29] op_sel_hi:[0,1]
	v_pk_mul_f32 v[30:31], v[0:1], v[30:31] op_sel_hi:[0,1]
	v_pk_mul_f32 v[34:35], v[0:1], v[34:35] op_sel_hi:[0,1]
	s_cmp_lt_i32 s6, 0x14000
	v_lshl_add_u64 v[22:23], v[22:23], 0, s[8:9]
	v_pk_fma_f32 v[30:31], v[8:9], v[30:31], v[54:55]
	v_pk_fma_f32 v[28:29], v[6:7], v[28:29], v[52:53]
	v_pk_fma_f32 v[34:35], v[12:13], v[34:35], v[46:47]
	v_pk_fma_f32 v[36:37], v[14:15], v[44:45], v[36:37]
	global_store_dwordx4 v[40:41], v[24:27], off
	global_store_dwordx4 v[40:41], v[28:31], off offset:1024
	global_store_dwordx4 v[40:41], v[32:35], off offset:2048
	global_store_dwordx4 v[40:41], v[36:39], off offset:3072
	s_cbranch_scc0 .LBB0_861
; __device__ __forceinline__ float bflo(unsigned u) { return __uint_as_float(u << 16); }
; __device__ __forceinline__ float bfhi(unsigned u) { return __uint_as_float(u & 0xffff0000u); }
; template <int NR, bool XBF, bool WOUT, bool WXB = true>
; __device__ __forceinline__ void rows_final(const float* xp, const float* xs, const bf16_t* __restrict__ Y, const float* __restrict__ ss, const float* __restrict__ gpost, float* out, bf16_t* xb, float* rs, int row0, int lane) {
;     ...
;     for (int r = 0; r < NR; ++r) { const int row = row0 + r;
;         const float* xrow = (row < NP_TOK) ? xp + (size_t)row * DM : xs + (size_t)(row - NP_TOK) * DM;
;         ssl[r] = (lane < 32) ? ss[(size_t)row * 32 + lane] : 0.f;
; #pragma unroll
;         for (int j = 0; j < 4; ++j) {
;             if (XBF) { const u32x2 xw = *((const u32x2*)(xb + (size_t)row * DM) + lane + 64 * j); v[r][j] = (f32x4){bflo(xw.x), bfhi(xw.x), bflo(xw.y), bfhi(xw.y)}; }
;             else v[r][j] = *((const f32x4*)xrow + lane + 64 * j);
;             yy[r][j] = *((const u32x2*)(Y + (size_t)row * DM) + lane + 64 * j); } }
.LBB0_853:
	s_nop 0
	v_mov_b32_e32 v36, 0
	v_lshl_add_u64 v[34:35], s[0:1], 0, v[18:19]
	v_mov_b32_e32 v37, 0
	s_and_saveexec_b64 s[8:9], s[2:3]
	s_cbranch_execz .LBB0_855
	v_add_co_u32_e32 v24, vcc, 0x3c1a0000, v34
	s_nop 1
	v_addc_co_u32_e32 v25, vcc, 0, v35, vcc
	global_load_dword v37, v[24:25], off
.LBB0_855:
	s_or_b64 exec, exec, s[8:9]
	v_lshl_add_u64 v[40:41], s[0:1], 0, v[22:23]
	v_add_co_u32_e32 v24, vcc, 0x2d000000, v40
	s_nop 1
	v_addc_co_u32_e32 v25, vcc, 0, v41, vcc
	v_add_co_u32_e32 v26, vcc, 0x1e000000, v40
	s_nop 1
	v_addc_co_u32_e32 v27, vcc, 0, v41, vcc
	global_load_dwordx2 v[42:43], v[24:25], off
	global_load_dwordx2 v[46:47], v[24:25], off offset:512
	global_load_dwordx2 v[52:53], v[24:25], off offset:1024
	global_load_dwordx2 v[54:55], v[24:25], off offset:1536
	global_load_dwordx2 v[88:89], v[26:27], off
	global_load_dwordx2 v[86:87], v[26:27], off offset:512
	global_load_dwordx2 v[84:85], v[26:27], off offset:1024
	global_load_dwordx2 v[82:83], v[26:27], off offset:1536
	s_and_saveexec_b64 s[8:9], s[2:3]
	s_cbranch_execz .LBB0_857
	v_add_co_u32_e32 v24, vcc, 0x3c1a0000, v34
	s_nop 1
	v_addc_co_u32_e32 v25, vcc, 0, v35, vcc
	global_load_dword v36, v[24:25], off offset:128
.LBB0_857:
	s_or_b64 exec, exec, s[8:9]
	v_add_co_u32_e32 v24, vcc, 0x2d000000, v40
	s_nop 1
	v_addc_co_u32_e32 v25, vcc, 0, v41, vcc
	v_add_co_u32_e32 v26, vcc, 0x1e000000, v40
	s_nop 1
	v_addc_co_u32_e32 v27, vcc, 0, v41, vcc
	global_load_dwordx2 v[60:61], v[24:25], off offset:2048
	global_load_dwordx2 v[64:65], v[24:25], off offset:2560
	global_load_dwordx2 v[70:71], v[24:25], off offset:3072
	global_load_dwordx2 v[74:75], v[24:25], off offset:3584
	global_load_dwordx2 v[76:77], v[26:27], off offset:2048
	global_load_dwordx2 v[72:73], v[26:27], off offset:2560
	global_load_dwordx2 v[62:63], v[26:27], off offset:3072
	global_load_dwordx2 v[50:51], v[26:27], off offset:3584
	v_mov_b32_e32 v26, 0
	v_mov_b32_e32 v27, 0
	s_and_saveexec_b64 s[8:9], s[2:3]
	s_cbranch_execz .LBB0_859
	v_add_co_u32_e32 v24, vcc, 0x3c1a0000, v34
	s_nop 1
	v_addc_co_u32_e32 v25, vcc, 0, v35, vcc
	global_load_dword v27, v[24:25], off offset:256
.LBB0_859:
	s_or_b64 exec, exec, s[8:9]
	v_add_co_u32_e32 v24, vcc, 0x2d001000, v40
	s_nop 1
	v_addc_co_u32_e32 v25, vcc, 0, v41, vcc
	v_add_co_u32_e32 v44, vcc, 0x1e001000, v40
	s_nop 1
	v_addc_co_u32_e32 v45, vcc, 0, v41, vcc
	global_load_dwordx2 v[68:69], v[24:25], off
	global_load_dwordx2 v[58:59], v[24:25], off offset:512
	global_load_dwordx2 v[48:49], v[24:25], off offset:1024
	global_load_dwordx2 v[38:39], v[24:25], off offset:1536
	global_load_dwordx2 v[32:33], v[44:45], off
	global_load_dwordx2 v[30:31], v[44:45], off offset:512
	global_load_dwordx2 v[28:29], v[44:45], off offset:1024
	s_nop 0
	global_load_dwordx2 v[24:25], v[44:45], off offset:1536
	s_and_saveexec_b64 s[8:9], s[2:3]
	s_cbranch_execz .LBB0_852
	v_add_co_u32_e32 v34, vcc, 0x3c1a0000, v34
	s_nop 1
	v_addc_co_u32_e32 v35, vcc, 0, v35, vcc
	global_load_dword v26, v[34:35], off offset:384
	s_branch .LBB0_852

; __device__ __forceinline__ float bflo(unsigned u) { return __uint_as_float(u << 16); }
; __device__ __forceinline__ float bfhi(unsigned u) { return __uint_as_float(u & 0xffff0000u); }
; __device__ __forceinline__ float wave_sum(float v) {
; #pragma unroll
;     for (int o = 1; o < 64; o <<= 1) v += __shfl_xor(v, o);
;     return v;
; template <int NR, bool XBF, bool WOUT, bool WXB = true>
; __device__ __forceinline__ void rows_final(const float* xp, const float* xs, const bf16_t* __restrict__ Y, const float* __restrict__ ss, const float* __restrict__ gpost, float* out, bf16_t* xb, float* rs, int row0, int lane) {
;     ...
;     for (int r = 0; r < NR; ++r) { const int row = row0 + r;
;         const float* xrow = (row < NP_TOK) ? xp + (size_t)row * DM : xs + (size_t)(row - NP_TOK) * DM;
;         ssl[r] = (lane < 32) ? ss[(size_t)row * 32 + lane] : 0.f;
; #pragma unroll
;         for (int j = 0; j < 4; ++j) {
;             if (XBF) { const u32x2 xw = *((const u32x2*)(xb + (size_t)row * DM) + lane + 64 * j); v[r][j] = (f32x4){bflo(xw.x), bfhi(xw.x), bflo(xw.y), bfhi(xw.y)}; }
;             else v[r][j] = *((const f32x4*)xrow + lane + 64 * j);
;             yy[r][j] = *((const u32x2*)(Y + (size_t)row * DM) + lane + 64 * j); } }
;     f32x4 g[4];
; #pragma unroll
;     for (int j = 0; j < 4; ++j) g[j] = *((const f32x4*)gpost + lane + 64 * j);
; #pragma unroll
;     for (int r = 0; r < NR; ++r) { const int row = row0 + r;
;         const float rn = rsqrtf(wave_sum(ssl[r]) * (1.f / DM) + EPS); float s = 0.f;
.LBB0_866:
	v_mov_b32_e32 v87, 0
	v_lshl_add_u64 v[30:31], s[0:1], 0, v[18:19]
	v_mov_b32_e32 v34, 0
	s_and_saveexec_b64 s[10:11], s[2:3]
	s_cbranch_execz .LBB0_868
	v_add_co_u32_e32 v22, vcc, 0x3c1a0000, v30
	s_waitcnt lgkmcnt(0)
	s_nop 0
	v_addc_co_u32_e32 v23, vcc, 0, v31, vcc
	global_load_dword v34, v[22:23], off
.LBB0_868:
	s_or_b64 exec, exec, s[10:11]
	s_waitcnt lgkmcnt(0)
	v_lshl_add_u64 v[22:23], s[0:1], 0, v[20:21]
	v_add_co_u32_e32 v24, vcc, 0x2d000000, v22
	s_nop 1
	v_addc_co_u32_e32 v25, vcc, 0, v23, vcc
	v_add_co_u32_e32 v36, vcc, 0x1e000000, v22
	s_nop 1
	v_addc_co_u32_e32 v37, vcc, 0, v23, vcc
	global_load_dwordx2 v[32:33], v[24:25], off
	global_load_dwordx2 v[28:29], v[24:25], off offset:512
	global_load_dwordx2 v[26:27], v[24:25], off offset:1024
	s_nop 0
	global_load_dwordx2 v[24:25], v[24:25], off offset:1536
	s_nop 0
	global_load_dwordx2 v[78:79], v[36:37], off
	global_load_dwordx2 v[76:77], v[36:37], off offset:512
	global_load_dwordx2 v[74:75], v[36:37], off offset:1024
	global_load_dwordx2 v[72:73], v[36:37], off offset:1536
	s_and_saveexec_b64 s[10:11], s[2:3]
	s_cbranch_execz .LBB0_870
	v_add_co_u32_e32 v36, vcc, 0x3c1a0000, v30
	s_nop 1
	v_addc_co_u32_e32 v37, vcc, 0, v31, vcc
	global_load_dword v87, v[36:37], off offset:128
.LBB0_870:
	s_or_b64 exec, exec, s[10:11]
	v_add_co_u32_e32 v36, vcc, 0x2d000000, v22
	v_mov_b32_e32 v85, 0
	s_nop 0
	v_addc_co_u32_e32 v37, vcc, 0, v23, vcc
	v_add_co_u32_e32 v38, vcc, 0x1e000000, v22
	v_mov_b32_e32 v86, 0
	s_nop 0
	v_addc_co_u32_e32 v39, vcc, 0, v23, vcc
	global_load_dwordx2 v[70:71], v[36:37], off offset:2048
	global_load_dwordx2 v[68:69], v[36:37], off offset:2560
	global_load_dwordx2 v[66:67], v[36:37], off offset:3072
	global_load_dwordx2 v[64:65], v[36:37], off offset:3584
	global_load_dwordx2 v[62:63], v[38:39], off offset:2048
	global_load_dwordx2 v[60:61], v[38:39], off offset:2560
	global_load_dwordx2 v[58:59], v[38:39], off offset:3072
	global_load_dwordx2 v[56:57], v[38:39], off offset:3584
	s_and_saveexec_b64 s[10:11], s[2:3]
	s_cbranch_execz .LBB0_872
	v_add_co_u32_e32 v36, vcc, 0x3c1a0000, v30
	s_nop 1
	v_addc_co_u32_e32 v37, vcc, 0, v31, vcc
	global_load_dword v86, v[36:37], off offset:256
.LBB0_872:
	s_or_b64 exec, exec, s[10:11]
	v_add_co_u32_e32 v36, vcc, 0x2d001000, v22
	s_nop 1
	v_addc_co_u32_e32 v37, vcc, 0, v23, vcc
	v_add_co_u32_e32 v38, vcc, 0x1e001000, v22
	s_nop 1
	v_addc_co_u32_e32 v39, vcc, 0, v23, vcc
	global_load_dwordx2 v[54:55], v[36:37], off
	global_load_dwordx2 v[52:53], v[36:37], off offset:512
	global_load_dwordx2 v[50:51], v[36:37], off offset:1024
	global_load_dwordx2 v[48:49], v[36:37], off offset:1536
	global_load_dwordx2 v[46:47], v[38:39], off
	global_load_dwordx2 v[44:45], v[38:39], off offset:512
	global_load_dwordx2 v[42:43], v[38:39], off offset:1024
	global_load_dwordx2 v[40:41], v[38:39], off offset:1536
	s_and_saveexec_b64 s[10:11], s[2:3]
	s_cbranch_execz .LBB0_874
	v_add_co_u32_e32 v30, vcc, 0x3c1a0000, v30
	s_nop 1
	v_addc_co_u32_e32 v31, vcc, 0, v31, vcc
	global_load_dword v85, v[30:31], off offset:384
.LBB0_874:
	s_or_b64 exec, exec, s[10:11]
	s_waitcnt vmcnt(0) lgkmcnt(0)
	s_nop 1
	v_mov_b32_dpp v30, v34 quad_perm:[1,0,3,2] row_mask:0xf bank_mask:0xf
	v_lshlrev_b32_e32 v92, 16, v28
	v_and_b32_e32 v93, 0xffff0000, v28
	v_lshlrev_b32_e32 v94, 16, v29
	v_and_b32_e32 v95, 0xffff0000, v29
	s_waitcnt lgkmcnt(0)
	v_add_f32_e32 v28, v34, v30
	s_nop 1
	v_mov_b32_dpp v29, v28 quad_perm:[2,3,0,1] row_mask:0xf bank_mask:0xf
	v_lshlrev_b32_e32 v96, 16, v26
	v_and_b32_e32 v97, 0xffff0000, v26
	v_lshlrev_b32_e32 v98, 16, v27
	v_and_b32_e32 v99, 0xffff0000, v27
	s_waitcnt lgkmcnt(0)
	v_add_f32_e32 v26, v28, v29
	s_nop 1
	v_mov_b32_dpp v27, v26 row_half_mirror row_mask:0xf bank_mask:0xf
	s_mov_b32 s7, 0x2d001000
	v_lshlrev_b32_e32 v100, 16, v24
	v_and_b32_e32 v101, 0xffff0000, v24
	v_add_co_u32_e32 v24, vcc, s7, v22
	s_waitcnt lgkmcnt(0)
	v_add_f32_e32 v26, v26, v27
	s_nop 1
	v_mov_b32_dpp v27, v26 row_mirror row_mask:0xf bank_mask:0xf
	v_lshlrev_b32_e32 v102, 16, v25
	v_and_b32_e32 v103, 0xffff0000, v25
	v_addc_co_u32_e32 v25, vcc, 0, v23, vcc
	s_waitcnt lgkmcnt(0)
	v_add_f32_e32 v26, v26, v27
	v_mov_b32_e32 v27, v26
	v_mov_b32_e32 v254, v26
	s_nop 1
	v_permlane16_swap_b32_e32 v27, v254
	s_mov_b32 s7, 0x1e001000
	v_lshlrev_b32_e32 v88, 16, v32
	v_and_b32_e32 v89, 0xffff0000, v32
	v_lshlrev_b32_e32 v90, 16, v33
	s_waitcnt lgkmcnt(0)
	v_add_f32_e32 v26, v254, v27
	v_mov_b32_e32 v27, v26
	v_mov_b32_e32 v254, v26
	s_nop 1
	v_permlane32_swap_b32_e32 v27, v254
	v_and_b32_e32 v91, 0xffff0000, v33
	v_add_co_u32_e32 v104, vcc, s7, v22
	global_load_dwordx2 v[38:39], v[24:25], off offset:2048
	global_load_dwordx2 v[36:37], v[24:25], off offset:2560
	global_load_dwordx2 v[34:35], v[24:25], off offset:3072
	global_load_dwordx2 v[32:33], v[24:25], off offset:3584
	s_waitcnt lgkmcnt(0)
; __device__ __forceinline__ unsigned cvtpk(float lo, float hi) { f32x2 v = {lo, hi}; bf16x2_t b = __builtin_convertvector(v, bf16x2_t); return __builtin_bit_cast(unsigned, b); }
; __device__ __forceinline__ float bflo(unsigned u) { return __uint_as_float(u << 16); }
; __device__ __forceinline__ float bfhi(unsigned u) { return __uint_as_float(u & 0xffff0000u); }
; __device__ __forceinline__ float wave_sum(float v) {
; #pragma unroll
;     for (int o = 1; o < 64; o <<= 1) v += __shfl_xor(v, o);
;     return v;
; template <int NR, bool XBF, bool WOUT, bool WXB = true>
; __device__ __forceinline__ void rows_final(const float* xp, const float* xs, const bf16_t* __restrict__ Y, const float* __restrict__ ss, const float* __restrict__ gpost, float* out, bf16_t* xb, float* rs, int row0, int lane) {
;     ...
;     for (int r = 0; r < NR; ++r) { const int row = row0 + r;
;         const float rn = rsqrtf(wave_sum(ssl[r]) * (1.f / DM) + EPS); float s = 0.f;
; #pragma unroll
;         for (int j = 0; j < 4; ++j) { const f32x4 yf = {bflo(yy[r][j].x), bfhi(yy[r][j].x), bflo(yy[r][j].y), bfhi(yy[r][j].y)};
;             v[r][j] = v[r][j] + yf * rn * g[j]; s += (v[r][j][0] * v[r][j][0] + v[r][j][1] * v[r][j][1]) + (v[r][j][2] * v[r][j][2] + v[r][j][3] * v[r][j][3]); }
;         s = wave_sum(s);
;         f32x4* oo = (f32x4*)(out + (size_t)row * DM) + lane; u32x2* o = (u32x2*)(xb + (size_t)row * DM) + lane;
; #pragma unroll
;         for (int j = 0; j < 4; ++j) { if (WOUT) oo[64 * j] = v[r][j]; if (WXB) { u32x2 w; w.x = cvtpk(v[r][j][0], v[r][j][1]); w.y = cvtpk(v[r][j][2], v[r][j][3]); o[64 * j] = w; } }
;         if (WXB && lane == 0) rs[row] = rsqrtf(s * (1.f / DM) + EPS); }
	v_add_f32_e32 v24, v254, v27
	v_addc_co_u32_e32 v105, vcc, 0, v23, vcc
	v_fmamk_f32 v24, v24, 0x3a800000, v241
	v_mul_f32_e32 v25, 0x4b800000, v24
	v_cmp_gt_f32_e32 vcc, s21, v24
	v_and_b32_e32 v107, 0xffff0000, v78
	s_mov_b64 s[10:11], 0x2d000000
	v_cndmask_b32_e32 v24, v24, v25, vcc
	v_rsq_f32_e32 v106, v24
	global_load_dwordx2 v[30:31], v[104:105], off offset:2048
	global_load_dwordx2 v[28:29], v[104:105], off offset:2560
	global_load_dwordx2 v[26:27], v[104:105], off offset:3072
	global_load_dwordx2 v[24:25], v[104:105], off offset:3584
	v_mul_f32_e32 v104, 0x45800000, v106
	v_cndmask_b32_e32 v104, v106, v104, vcc
	v_lshlrev_b32_e32 v106, 16, v78
	v_lshlrev_b32_e32 v78, 16, v79
	v_and_b32_e32 v79, 0xffff0000, v79
	v_pk_mul_f32 v[106:107], v[104:105], v[106:107] op_sel_hi:[0,1]
	v_pk_mul_f32 v[78:79], v[104:105], v[78:79] op_sel_hi:[0,1]
	v_pk_fma_f32 v[78:79], v[4:5], v[78:79], v[90:91]
	v_pk_fma_f32 v[88:89], v[2:3], v[106:107], v[88:89]
	v_mul_f32_e32 v91, v79, v79
	v_mul_f32_e32 v90, v89, v89
	v_fmac_f32_e32 v90, v88, v88
	v_fmac_f32_e32 v91, v78, v78
	v_add_f32_e32 v105, v90, v91
	v_lshlrev_b32_e32 v90, 16, v76
	v_and_b32_e32 v91, 0xffff0000, v76
	v_lshlrev_b32_e32 v76, 16, v77
	v_and_b32_e32 v77, 0xffff0000, v77
	v_pk_mul_f32 v[90:91], v[104:105], v[90:91] op_sel_hi:[0,1]
	v_pk_mul_f32 v[76:77], v[104:105], v[76:77] op_sel_hi:[0,1]
	v_pk_fma_f32 v[76:77], v[8:9], v[76:77], v[94:95]
	v_pk_fma_f32 v[90:91], v[6:7], v[90:91], v[92:93]
	v_mul_f32_e32 v93, v77, v77
	v_mul_f32_e32 v92, v91, v91
	v_fmac_f32_e32 v92, v90, v90
	v_fmac_f32_e32 v93, v76, v76
	v_add_f32_e32 v92, v92, v93
	v_add_f32_e32 v94, v105, v92
	v_lshlrev_b32_e32 v92, 16, v74
	v_and_b32_e32 v93, 0xffff0000, v74
	v_lshlrev_b32_e32 v74, 16, v75
	v_and_b32_e32 v75, 0xffff0000, v75
	v_pk_mul_f32 v[92:93], v[104:105], v[92:93] op_sel_hi:[0,1]
	v_pk_mul_f32 v[74:75], v[104:105], v[74:75] op_sel_hi:[0,1]
	v_pk_fma_f32 v[74:75], v[12:13], v[74:75], v[98:99]
	v_pk_fma_f32 v[92:93], v[10:11], v[92:93], v[96:97]
	v_mul_f32_e32 v96, v75, v75
	v_mul_f32_e32 v95, v93, v93
	v_fmac_f32_e32 v95, v92, v92
	v_fmac_f32_e32 v96, v74, v74
	v_add_f32_e32 v95, v95, v96
	v_add_f32_e32 v98, v95, v94
	v_lshlrev_b32_e32 v94, 16, v72
	v_and_b32_e32 v95, 0xffff0000, v72
	v_lshlrev_b32_e32 v72, 16, v73
	v_and_b32_e32 v73, 0xffff0000, v73
	v_pk_mul_f32 v[94:95], v[104:105], v[94:95] op_sel_hi:[0,1]
	v_pk_mul_f32 v[72:73], v[104:105], v[72:73] op_sel_hi:[0,1]
	v_pk_fma_f32 v[96:97], v[16:17], v[72:73], v[102:103]
	v_pk_fma_f32 v[94:95], v[14:15], v[94:95], v[100:101]
	v_mul_f32_e32 v73, v97, v97
	v_mul_f32_e32 v72, v95, v95
	v_fmac_f32_e32 v72, v94, v94
	v_fmac_f32_e32 v73, v96, v96
	v_add_f32_e32 v72, v72, v73
	v_add_f32_e32 v72, v72, v98
	s_nop 1
	v_mov_b32_dpp v73, v72 quad_perm:[1,0,3,2] row_mask:0xf bank_mask:0xf
	v_lshl_add_u64 v[98:99], v[22:23], 0, s[10:11]
	s_mov_b64 s[10:11], 0x2d000200
	v_lshl_add_u64 v[100:101], v[22:23], 0, s[10:11]
	s_mov_b64 s[10:11], 0x2d000400
	s_waitcnt lgkmcnt(0)
	v_add_f32_e32 v72, v72, v73
	s_nop 1
	v_mov_b32_dpp v73, v72 quad_perm:[2,3,0,1] row_mask:0xf bank_mask:0xf
	v_lshl_add_u64 v[102:103], v[22:23], 0, s[10:11]
	s_mov_b64 s[10:11], 0x2d000600
	v_lshl_add_u64 v[104:105], v[22:23], 0, s[10:11]
	v_cvt_pk_bf16_f32 v88, v88, v89
	s_waitcnt lgkmcnt(0)
	v_add_f32_e32 v72, v72, v73
	s_nop 1
	v_mov_b32_dpp v73, v72 row_half_mirror row_mask:0xf bank_mask:0xf
	v_cvt_pk_bf16_f32 v89, v78, v79
	v_cvt_pk_bf16_f32 v78, v90, v91
	v_cvt_pk_bf16_f32 v79, v76, v77
	v_cvt_pk_bf16_f32 v76, v92, v93
	s_waitcnt lgkmcnt(0)
	v_add_f32_e32 v72, v72, v73
	s_nop 1
	v_mov_b32_dpp v73, v72 row_mirror row_mask:0xf bank_mask:0xf
	v_cvt_pk_bf16_f32 v77, v74, v75
	v_cvt_pk_bf16_f32 v74, v94, v95
	v_cvt_pk_bf16_f32 v75, v96, v97
	global_store_dwordx2 v[98:99], v[88:89], off
	s_waitcnt lgkmcnt(0)
	v_add_f32_e32 v72, v72, v73
	v_mov_b32_e32 v73, v72
	v_mov_b32_e32 v254, v72
	s_nop 1
	v_permlane16_swap_b32_e32 v73, v254
	global_store_dwordx2 v[100:101], v[78:79], off
	global_store_dwordx2 v[102:103], v[76:77], off
	global_store_dwordx2 v[104:105], v[74:75], off
	s_waitcnt lgkmcnt(0)
	v_add_f32_e32 v72, v254, v73
	v_mov_b32_e32 v73, v72
	v_mov_b32_e32 v254, v72
	s_nop 1
	v_permlane32_swap_b32_e32 v73, v254
	s_and_saveexec_b64 s[10:11], s[4:5]
	s_cbranch_execz .LBB0_876
	s_waitcnt lgkmcnt(0)
	v_add_f32_e32 v72, v254, v73
	v_fmamk_f32 v72, v72, 0x3a800000, v241
	v_mul_f32_e32 v73, 0x4b800000, v72
	v_cmp_gt_f32_e32 vcc, s21, v72
	s_add_u32 s7, s0, s8
	s_addc_u32 s12, s1, s9
	v_cndmask_b32_e32 v72, v72, v73, vcc
	v_rsq_f32_e32 v72, v72
	s_nop 0
	v_mul_f32_e32 v73, 0x45800000, v72
	v_cndmask_b32_e32 v74, v72, v73, vcc
	v_mov_b32_e32 v72, s7
	v_add_co_u32_e32 v72, vcc, 0x3b700000, v72
	v_mov_b32_e32 v73, s12
	s_nop 0
	v_addc_co_u32_e32 v73, vcc, 0, v73, vcc
	global_store_dword v[72:73], v74, off
; __device__ __forceinline__ unsigned cvtpk(float lo, float hi) { f32x2 v = {lo, hi}; bf16x2_t b = __builtin_convertvector(v, bf16x2_t); return __builtin_bit_cast(unsigned, b); }
; __device__ __forceinline__ float bflo(unsigned u) { return __uint_as_float(u << 16); }
; __device__ __forceinline__ float bfhi(unsigned u) { return __uint_as_float(u & 0xffff0000u); }
; __device__ __forceinline__ float wave_sum(float v) {
; #pragma unroll
;     for (int o = 1; o < 64; o <<= 1) v += __shfl_xor(v, o);
;     return v;
; template <int NR, bool XBF, bool WOUT, bool WXB = true>
; __device__ __forceinline__ void rows_final(const float* xp, const float* xs, const bf16_t* __restrict__ Y, const float* __restrict__ ss, const float* __restrict__ gpost, float* out, bf16_t* xb, float* rs, int row0, int lane) {
;     ...
;     for (int r = 0; r < NR; ++r) { const int row = row0 + r;
;         const float rn = rsqrtf(wave_sum(ssl[r]) * (1.f / DM) + EPS); float s = 0.f;
; #pragma unroll
;         for (int j = 0; j < 4; ++j) { const f32x4 yf = {bflo(yy[r][j].x), bfhi(yy[r][j].x), bflo(yy[r][j].y), bfhi(yy[r][j].y)};
;             v[r][j] = v[r][j] + yf * rn * g[j]; s += (v[r][j][0] * v[r][j][0] + v[r][j][1] * v[r][j][1]) + (v[r][j][2] * v[r][j][2] + v[r][j][3] * v[r][j][3]); }
;         s = wave_sum(s);
;         f32x4* oo = (f32x4*)(out + (size_t)row * DM) + lane; u32x2* o = (u32x2*)(xb + (size_t)row * DM) + lane;
; #pragma unroll
;         for (int j = 0; j < 4; ++j) { if (WOUT) oo[64 * j] = v[r][j]; if (WXB) { u32x2 w; w.x = cvtpk(v[r][j][0], v[r][j][1]); w.y = cvtpk(v[r][j][2], v[r][j][3]); o[64 * j] = w; } }
;         if (WXB && lane == 0) rs[row] = rsqrtf(s * (1.f / DM) + EPS); }
.LBB0_876:
	s_or_b64 exec, exec, s[10:11]
	s_nop 1
	v_mov_b32_dpp v72, v87 quad_perm:[1,0,3,2] row_mask:0xf bank_mask:0xf
	v_and_b32_e32 v91, 0xffff0000, v60
	v_and_b32_e32 v89, 0xffff0000, v62
	s_waitcnt lgkmcnt(0)
	v_and_b32_e32 v73, 0xffff0000, v70
	s_mov_b64 s[10:11], 0x2d000800
	v_add_f32_e32 v74, v87, v72
	s_nop 1
	v_mov_b32_dpp v75, v74 quad_perm:[2,3,0,1] row_mask:0xf bank_mask:0xf
	v_lshlrev_b32_e32 v72, 16, v70
	v_lshlrev_b32_e32 v70, 16, v71
	v_and_b32_e32 v71, 0xffff0000, v71
	s_waitcnt lgkmcnt(0)
	v_add_f32_e32 v76, v74, v75
	s_nop 1
	v_mov_b32_dpp v77, v76 row_half_mirror row_mask:0xf bank_mask:0xf
	v_lshlrev_b32_e32 v74, 16, v68
	v_and_b32_e32 v75, 0xffff0000, v68
	v_lshlrev_b32_e32 v68, 16, v69
	v_and_b32_e32 v69, 0xffff0000, v69
	s_waitcnt lgkmcnt(0)
	v_add_f32_e32 v78, v76, v77
	s_nop 1
	v_mov_b32_dpp v79, v78 row_mirror row_mask:0xf bank_mask:0xf
	v_lshlrev_b32_e32 v76, 16, v66
	v_and_b32_e32 v77, 0xffff0000, v66
	v_lshlrev_b32_e32 v66, 16, v67
	v_and_b32_e32 v67, 0xffff0000, v67
	s_waitcnt lgkmcnt(0)
	v_add_f32_e32 v87, v78, v79
	v_mov_b32_e32 v88, v87
	v_mov_b32_e32 v254, v87
	s_nop 1
	v_permlane16_swap_b32_e32 v88, v254
	v_lshlrev_b32_e32 v78, 16, v64
	v_and_b32_e32 v79, 0xffff0000, v64
	v_lshlrev_b32_e32 v64, 16, v65
	v_and_b32_e32 v65, 0xffff0000, v65
	s_waitcnt lgkmcnt(0)
	v_add_f32_e32 v87, v254, v88
	v_mov_b32_e32 v90, v87
	v_mov_b32_e32 v254, v87
	s_nop 1
	v_permlane32_swap_b32_e32 v90, v254
	v_lshlrev_b32_e32 v88, 16, v62
	v_lshlrev_b32_e32 v62, 16, v63
	v_and_b32_e32 v63, 0xffff0000, v63
	s_waitcnt lgkmcnt(0)
	v_add_f32_e32 v87, v254, v90
	v_fmamk_f32 v87, v87, 0x3a800000, v241
	v_mul_f32_e32 v90, 0x4b800000, v87
	v_cmp_gt_f32_e32 vcc, s21, v87
	s_nop 1
	v_cndmask_b32_e32 v87, v87, v90, vcc
	v_rsq_f32_e32 v87, v87
	v_lshlrev_b32_e32 v90, 16, v60
	v_mul_f32_e32 v60, 0x45800000, v87
	v_cndmask_b32_e32 v60, v87, v60, vcc
	v_pk_mul_f32 v[88:89], v[60:61], v[88:89] op_sel_hi:[0,1]
	v_pk_mul_f32 v[62:63], v[60:61], v[62:63] op_sel_hi:[0,1]
	v_pk_fma_f32 v[62:63], v[4:5], v[62:63], v[70:71]
	v_pk_fma_f32 v[70:71], v[2:3], v[88:89], v[72:73]
	v_mul_f32_e32 v73, v63, v63
	v_mul_f32_e32 v72, v71, v71
	v_fmac_f32_e32 v72, v70, v70
	v_fmac_f32_e32 v73, v62, v62
	v_add_f32_e32 v87, v72, v73
	v_lshlrev_b32_e32 v72, 16, v61
	v_and_b32_e32 v73, 0xffff0000, v61
	v_pk_mul_f32 v[88:89], v[60:61], v[90:91] op_sel_hi:[0,1]
	v_pk_mul_f32 v[72:73], v[60:61], v[72:73] op_sel_hi:[0,1]
	v_pk_fma_f32 v[68:69], v[8:9], v[72:73], v[68:69]
	v_pk_fma_f32 v[72:73], v[6:7], v[88:89], v[74:75]
	v_mul_f32_e32 v74, v69, v69
	v_mul_f32_e32 v61, v73, v73
	v_fmac_f32_e32 v61, v72, v72
	v_fmac_f32_e32 v74, v68, v68
	v_add_f32_e32 v61, v61, v74
	v_add_f32_e32 v61, v87, v61
	v_lshlrev_b32_e32 v74, 16, v58
	v_and_b32_e32 v75, 0xffff0000, v58
	v_lshlrev_b32_e32 v58, 16, v59
	v_and_b32_e32 v59, 0xffff0000, v59
	v_pk_mul_f32 v[74:75], v[60:61], v[74:75] op_sel_hi:[0,1]
	v_pk_mul_f32 v[58:59], v[60:61], v[58:59] op_sel_hi:[0,1]
	v_pk_fma_f32 v[58:59], v[12:13], v[58:59], v[66:67]
	v_pk_fma_f32 v[66:67], v[10:11], v[74:75], v[76:77]
	v_mul_f32_e32 v75, v59, v59
	v_mul_f32_e32 v74, v67, v67
	v_fmac_f32_e32 v74, v66, v66
	v_fmac_f32_e32 v75, v58, v58
	v_add_f32_e32 v74, v74, v75
	v_add_f32_e32 v76, v74, v61
	v_lshlrev_b32_e32 v74, 16, v56
	v_and_b32_e32 v75, 0xffff0000, v56
	v_lshlrev_b32_e32 v56, 16, v57
	v_and_b32_e32 v57, 0xffff0000, v57
	v_pk_mul_f32 v[74:75], v[60:61], v[74:75] op_sel_hi:[0,1]
	v_pk_mul_f32 v[56:57], v[60:61], v[56:57] op_sel_hi:[0,1]
	v_pk_fma_f32 v[60:61], v[16:17], v[56:57], v[64:65]
	v_pk_fma_f32 v[64:65], v[14:15], v[74:75], v[78:79]
	v_mul_f32_e32 v57, v61, v61
	v_mul_f32_e32 v56, v65, v65
	v_fmac_f32_e32 v56, v64, v64
	v_fmac_f32_e32 v57, v60, v60
	v_add_f32_e32 v56, v56, v57
	v_add_f32_e32 v56, v56, v76
	s_nop 1
	v_mov_b32_dpp v57, v56 quad_perm:[1,0,3,2] row_mask:0xf bank_mask:0xf
	v_lshl_add_u64 v[74:75], v[22:23], 0, s[10:11]
	s_mov_b64 s[10:11], 0x2d000a00
	v_lshl_add_u64 v[76:77], v[22:23], 0, s[10:11]
	s_mov_b64 s[10:11], 0x2d000c00
	s_waitcnt lgkmcnt(0)
	v_add_f32_e32 v56, v56, v57
	s_nop 1
	v_mov_b32_dpp v57, v56 quad_perm:[2,3,0,1] row_mask:0xf bank_mask:0xf
	v_lshl_add_u64 v[78:79], v[22:23], 0, s[10:11]
	s_mov_b64 s[10:11], 0x2d000e00
	v_cvt_pk_bf16_f32 v70, v70, v71
	v_cvt_pk_bf16_f32 v71, v62, v63
	s_waitcnt lgkmcnt(0)
	v_add_f32_e32 v56, v56, v57
	s_nop 1
	v_mov_b32_dpp v57, v56 row_half_mirror row_mask:0xf bank_mask:0xf
	v_cvt_pk_bf16_f32 v62, v72, v73
	v_cvt_pk_bf16_f32 v63, v68, v69
	v_lshl_add_u64 v[88:89], v[22:23], 0, s[10:11]
	global_store_dwordx2 v[76:77], v[62:63], off
	s_waitcnt lgkmcnt(0)
	v_add_f32_e32 v56, v56, v57
	s_nop 1
	v_mov_b32_dpp v57, v56 row_mirror row_mask:0xf bank_mask:0xf
	v_cvt_pk_bf16_f32 v62, v66, v67
	v_cvt_pk_bf16_f32 v63, v58, v59
	v_cvt_pk_bf16_f32 v58, v64, v65
	v_cvt_pk_bf16_f32 v59, v60, v61
	s_waitcnt lgkmcnt(0)
	v_add_f32_e32 v56, v56, v57
	v_mov_b32_e32 v57, v56
	v_mov_b32_e32 v254, v56
	s_nop 1
	v_permlane16_swap_b32_e32 v57, v254
	global_store_dwordx2 v[74:75], v[70:71], off
	global_store_dwordx2 v[78:79], v[62:63], off
	global_store_dwordx2 v[88:89], v[58:59], off
	s_waitcnt lgkmcnt(0)
	v_add_f32_e32 v56, v254, v57
	v_mov_b32_e32 v57, v56
	v_mov_b32_e32 v254, v56
	s_nop 1
	v_permlane32_swap_b32_e32 v57, v254
	s_and_saveexec_b64 s[10:11], s[4:5]
	s_cbranch_execz .LBB0_878
	s_waitcnt lgkmcnt(0)
	v_add_f32_e32 v56, v254, v57
	v_fmamk_f32 v56, v56, 0x3a800000, v241
	v_mul_f32_e32 v57, 0x4b800000, v56
	v_cmp_gt_f32_e32 vcc, s21, v56
	s_add_u32 s7, s0, s8
	s_addc_u32 s12, s1, s9
	v_cndmask_b32_e32 v56, v56, v57, vcc
	v_rsq_f32_e32 v56, v56
	s_nop 0
	v_mul_f32_e32 v57, 0x45800000, v56
	v_cndmask_b32_e32 v58, v56, v57, vcc
	v_mov_b32_e32 v56, s7
	v_add_co_u32_e32 v56, vcc, 0x3b700000, v56
	v_mov_b32_e32 v57, s12
	s_nop 0
	v_addc_co_u32_e32 v57, vcc, 0, v57, vcc
	global_store_dword v[56:57], v58, off offset:4
; __device__ __forceinline__ unsigned cvtpk(float lo, float hi) { f32x2 v = {lo, hi}; bf16x2_t b = __builtin_convertvector(v, bf16x2_t); return __builtin_bit_cast(unsigned, b); }
; __device__ __forceinline__ float bflo(unsigned u) { return __uint_as_float(u << 16); }
; __device__ __forceinline__ float bfhi(unsigned u) { return __uint_as_float(u & 0xffff0000u); }
; __device__ __forceinline__ float wave_sum(float v) {
; #pragma unroll
;     for (int o = 1; o < 64; o <<= 1) v += __shfl_xor(v, o);
;     return v;
; template <int NR, bool XBF, bool WOUT, bool WXB = true>
; __device__ __forceinline__ void rows_final(const float* xp, const float* xs, const bf16_t* __restrict__ Y, const float* __restrict__ ss, const float* __restrict__ gpost, float* out, bf16_t* xb, float* rs, int row0, int lane) {
;     ...
;     for (int r = 0; r < NR; ++r) { const int row = row0 + r;
;         const float rn = rsqrtf(wave_sum(ssl[r]) * (1.f / DM) + EPS); float s = 0.f;
; #pragma unroll
;         for (int j = 0; j < 4; ++j) { const f32x4 yf = {bflo(yy[r][j].x), bfhi(yy[r][j].x), bflo(yy[r][j].y), bfhi(yy[r][j].y)};
;             v[r][j] = v[r][j] + yf * rn * g[j]; s += (v[r][j][0] * v[r][j][0] + v[r][j][1] * v[r][j][1]) + (v[r][j][2] * v[r][j][2] + v[r][j][3] * v[r][j][3]); }
;         s = wave_sum(s);
;         f32x4* oo = (f32x4*)(out + (size_t)row * DM) + lane; u32x2* o = (u32x2*)(xb + (size_t)row * DM) + lane;
; #pragma unroll
;         for (int j = 0; j < 4; ++j) { if (WOUT) oo[64 * j] = v[r][j]; if (WXB) { u32x2 w; w.x = cvtpk(v[r][j][0], v[r][j][1]); w.y = cvtpk(v[r][j][2], v[r][j][3]); o[64 * j] = w; } }
;         if (WXB && lane == 0) rs[row] = rsqrtf(s * (1.f / DM) + EPS); }
.LBB0_878:
	s_or_b64 exec, exec, s[10:11]
	s_nop 1
	v_mov_b32_dpp v56, v86 quad_perm:[1,0,3,2] row_mask:0xf bank_mask:0xf
	s_waitcnt lgkmcnt(0)
	v_and_b32_e32 v57, 0xffff0000, v54
	s_mov_b64 s[10:11], 0x2d001000
	v_add_f32_e32 v58, v86, v56
	s_nop 1
	v_mov_b32_dpp v59, v58 quad_perm:[2,3,0,1] row_mask:0xf bank_mask:0xf
	v_lshlrev_b32_e32 v56, 16, v54
	v_lshlrev_b32_e32 v54, 16, v55
	v_and_b32_e32 v55, 0xffff0000, v55
	s_waitcnt lgkmcnt(0)
	v_add_f32_e32 v60, v58, v59
	s_nop 1
	v_mov_b32_dpp v61, v60 row_half_mirror row_mask:0xf bank_mask:0xf
	v_lshlrev_b32_e32 v58, 16, v52
	v_and_b32_e32 v59, 0xffff0000, v52
	v_lshlrev_b32_e32 v52, 16, v53
	v_and_b32_e32 v53, 0xffff0000, v53
	s_waitcnt lgkmcnt(0)
	v_add_f32_e32 v62, v60, v61
	s_nop 1
	v_mov_b32_dpp v63, v62 row_mirror row_mask:0xf bank_mask:0xf
	v_lshlrev_b32_e32 v60, 16, v50
	v_and_b32_e32 v61, 0xffff0000, v50
	v_lshlrev_b32_e32 v50, 16, v51
	v_and_b32_e32 v51, 0xffff0000, v51
	s_waitcnt lgkmcnt(0)
	v_add_f32_e32 v64, v62, v63
	v_mov_b32_e32 v65, v64
	v_mov_b32_e32 v254, v64
	s_nop 1
	v_permlane16_swap_b32_e32 v65, v254
	v_lshlrev_b32_e32 v62, 16, v48
	v_and_b32_e32 v63, 0xffff0000, v48
	v_lshlrev_b32_e32 v48, 16, v49
	v_and_b32_e32 v49, 0xffff0000, v49
	s_waitcnt lgkmcnt(0)
	v_add_f32_e32 v66, v254, v65
	v_mov_b32_e32 v67, v66
	v_mov_b32_e32 v254, v66
	s_nop 1
	v_permlane32_swap_b32_e32 v67, v254
	v_lshlrev_b32_e32 v64, 16, v46
	v_and_b32_e32 v65, 0xffff0000, v46
	v_lshlrev_b32_e32 v46, 16, v47
	v_and_b32_e32 v47, 0xffff0000, v47
	s_waitcnt lgkmcnt(0)
	v_add_f32_e32 v66, v254, v67
	v_fmamk_f32 v66, v66, 0x3a800000, v241
	v_mul_f32_e32 v67, 0x4b800000, v66
	v_cmp_gt_f32_e32 vcc, s21, v66
	s_nop 1
	v_cndmask_b32_e32 v66, v66, v67, vcc
	v_rsq_f32_e32 v68, v66
	v_lshlrev_b32_e32 v66, 16, v44
	v_and_b32_e32 v67, 0xffff0000, v44
	v_mul_f32_e32 v44, 0x45800000, v68
	v_cndmask_b32_e32 v44, v68, v44, vcc
	v_pk_mul_f32 v[64:65], v[44:45], v[64:65] op_sel_hi:[0,1]
	v_pk_mul_f32 v[46:47], v[44:45], v[46:47] op_sel_hi:[0,1]
	v_pk_fma_f32 v[46:47], v[4:5], v[46:47], v[54:55]
	v_pk_fma_f32 v[54:55], v[2:3], v[64:65], v[56:57]
	v_mul_f32_e32 v57, v47, v47
	v_mul_f32_e32 v56, v55, v55
	v_fmac_f32_e32 v56, v54, v54
	v_fmac_f32_e32 v57, v46, v46
	v_add_f32_e32 v68, v56, v57
	v_lshlrev_b32_e32 v56, 16, v45
	v_and_b32_e32 v57, 0xffff0000, v45
	v_pk_mul_f32 v[64:65], v[44:45], v[66:67] op_sel_hi:[0,1]
	v_pk_mul_f32 v[56:57], v[44:45], v[56:57] op_sel_hi:[0,1]
	v_pk_fma_f32 v[52:53], v[8:9], v[56:57], v[52:53]
	v_pk_fma_f32 v[56:57], v[6:7], v[64:65], v[58:59]
	v_mul_f32_e32 v58, v53, v53
	v_mul_f32_e32 v45, v57, v57
	v_fmac_f32_e32 v45, v56, v56
	v_fmac_f32_e32 v58, v52, v52
	v_add_f32_e32 v45, v45, v58
	v_add_f32_e32 v45, v68, v45
	v_lshlrev_b32_e32 v58, 16, v42
	v_and_b32_e32 v59, 0xffff0000, v42
	v_lshlrev_b32_e32 v42, 16, v43
	v_and_b32_e32 v43, 0xffff0000, v43
	v_pk_mul_f32 v[58:59], v[44:45], v[58:59] op_sel_hi:[0,1]
	v_pk_mul_f32 v[42:43], v[44:45], v[42:43] op_sel_hi:[0,1]
	v_pk_fma_f32 v[42:43], v[12:13], v[42:43], v[50:51]
	v_pk_fma_f32 v[50:51], v[10:11], v[58:59], v[60:61]
	v_mul_f32_e32 v59, v43, v43
	v_mul_f32_e32 v58, v51, v51
	v_fmac_f32_e32 v58, v50, v50
	v_fmac_f32_e32 v59, v42, v42
	v_add_f32_e32 v58, v58, v59
	v_add_f32_e32 v60, v58, v45
	v_lshlrev_b32_e32 v58, 16, v40
	v_and_b32_e32 v59, 0xffff0000, v40
	v_lshlrev_b32_e32 v40, 16, v41
	v_and_b32_e32 v41, 0xffff0000, v41
	v_pk_mul_f32 v[58:59], v[44:45], v[58:59] op_sel_hi:[0,1]
	v_pk_mul_f32 v[40:41], v[44:45], v[40:41] op_sel_hi:[0,1]
	v_pk_fma_f32 v[44:45], v[16:17], v[40:41], v[48:49]
	v_pk_fma_f32 v[48:49], v[14:15], v[58:59], v[62:63]
	v_mul_f32_e32 v41, v45, v45
	v_mul_f32_e32 v40, v49, v49
	v_fmac_f32_e32 v40, v48, v48
	v_fmac_f32_e32 v41, v44, v44
	v_add_f32_e32 v40, v40, v41
	v_add_f32_e32 v40, v40, v60
	s_nop 1
	v_mov_b32_dpp v41, v40 quad_perm:[1,0,3,2] row_mask:0xf bank_mask:0xf
	v_lshl_add_u64 v[58:59], v[22:23], 0, s[10:11]
	s_mov_b64 s[10:11], 0x2d001200
	v_lshl_add_u64 v[60:61], v[22:23], 0, s[10:11]
	s_mov_b64 s[10:11], 0x2d001400
	s_waitcnt lgkmcnt(0)
	v_add_f32_e32 v40, v40, v41
	s_nop 1
	v_mov_b32_dpp v41, v40 quad_perm:[2,3,0,1] row_mask:0xf bank_mask:0xf
	v_lshl_add_u64 v[62:63], v[22:23], 0, s[10:11]
	s_mov_b64 s[10:11], 0x2d001600
	v_cvt_pk_bf16_f32 v54, v54, v55
	v_cvt_pk_bf16_f32 v55, v46, v47
	s_waitcnt lgkmcnt(0)
	v_add_f32_e32 v40, v40, v41
	s_nop 1
	v_mov_b32_dpp v41, v40 row_half_mirror row_mask:0xf bank_mask:0xf
	v_cvt_pk_bf16_f32 v46, v56, v57
	v_cvt_pk_bf16_f32 v47, v52, v53
	v_lshl_add_u64 v[64:65], v[22:23], 0, s[10:11]
	global_store_dwordx2 v[60:61], v[46:47], off
	s_waitcnt lgkmcnt(0)
	v_add_f32_e32 v40, v40, v41
	s_nop 1
	v_mov_b32_dpp v41, v40 row_mirror row_mask:0xf bank_mask:0xf
	v_cvt_pk_bf16_f32 v46, v50, v51
	v_cvt_pk_bf16_f32 v47, v42, v43
	v_cvt_pk_bf16_f32 v42, v48, v49
	v_cvt_pk_bf16_f32 v43, v44, v45
	s_waitcnt lgkmcnt(0)
	v_add_f32_e32 v40, v40, v41
	v_mov_b32_e32 v41, v40
	v_mov_b32_e32 v254, v40
	s_nop 1
	v_permlane16_swap_b32_e32 v41, v254
	global_store_dwordx2 v[58:59], v[54:55], off
	global_store_dwordx2 v[62:63], v[46:47], off
	global_store_dwordx2 v[64:65], v[42:43], off
	s_waitcnt lgkmcnt(0)
	v_add_f32_e32 v40, v254, v41
	v_mov_b32_e32 v41, v40
	v_mov_b32_e32 v254, v40
	s_nop 1
	v_permlane32_swap_b32_e32 v41, v254
	s_and_saveexec_b64 s[10:11], s[4:5]
	s_cbranch_execz .LBB0_880
	s_waitcnt lgkmcnt(0)
	v_add_f32_e32 v40, v254, v41
	v_fmamk_f32 v40, v40, 0x3a800000, v241
	v_mul_f32_e32 v41, 0x4b800000, v40
	v_cmp_gt_f32_e32 vcc, s21, v40
	s_add_u32 s7, s0, s8
	s_addc_u32 s12, s1, s9
	v_cndmask_b32_e32 v40, v40, v41, vcc
	v_rsq_f32_e32 v40, v40
	s_nop 0
	v_mul_f32_e32 v41, 0x45800000, v40
	v_cndmask_b32_e32 v42, v40, v41, vcc
	v_mov_b32_e32 v40, s7
	v_add_co_u32_e32 v40, vcc, 0x3b700000, v40
	v_mov_b32_e32 v41, s12
	s_nop 0
	v_addc_co_u32_e32 v41, vcc, 0, v41, vcc
	global_store_dword v[40:41], v42, off offset:8
; __device__ __forceinline__ unsigned cvtpk(float lo, float hi) { f32x2 v = {lo, hi}; bf16x2_t b = __builtin_convertvector(v, bf16x2_t); return __builtin_bit_cast(unsigned, b); }
; __device__ __forceinline__ float bflo(unsigned u) { return __uint_as_float(u << 16); }
; __device__ __forceinline__ float bfhi(unsigned u) { return __uint_as_float(u & 0xffff0000u); }
; __device__ __forceinline__ float wave_sum(float v) {
; #pragma unroll
;     for (int o = 1; o < 64; o <<= 1) v += __shfl_xor(v, o);
;     return v;
; template <int NR, bool XBF, bool WOUT, bool WXB = true>
; __device__ __forceinline__ void rows_final(const float* xp, const float* xs, const bf16_t* __restrict__ Y, const float* __restrict__ ss, const float* __restrict__ gpost, float* out, bf16_t* xb, float* rs, int row0, int lane) {
;     ...
;     for (int r = 0; r < NR; ++r) { const int row = row0 + r;
;         const float rn = rsqrtf(wave_sum(ssl[r]) * (1.f / DM) + EPS); float s = 0.f;
; #pragma unroll
;         for (int j = 0; j < 4; ++j) { const f32x4 yf = {bflo(yy[r][j].x), bfhi(yy[r][j].x), bflo(yy[r][j].y), bfhi(yy[r][j].y)};
;             v[r][j] = v[r][j] + yf * rn * g[j]; s += (v[r][j][0] * v[r][j][0] + v[r][j][1] * v[r][j][1]) + (v[r][j][2] * v[r][j][2] + v[r][j][3] * v[r][j][3]); }
;         s = wave_sum(s);
;         f32x4* oo = (f32x4*)(out + (size_t)row * DM) + lane; u32x2* o = (u32x2*)(xb + (size_t)row * DM) + lane;
; #pragma unroll
;         for (int j = 0; j < 4; ++j) { if (WOUT) oo[64 * j] = v[r][j]; if (WXB) { u32x2 w; w.x = cvtpk(v[r][j][0], v[r][j][1]); w.y = cvtpk(v[r][j][2], v[r][j][3]); o[64 * j] = w; } }
;         if (WXB && lane == 0) rs[row] = rsqrtf(s * (1.f / DM) + EPS); }
.LBB0_880:
	s_or_b64 exec, exec, s[10:11]
	s_nop 1
	v_mov_b32_dpp v40, v85 quad_perm:[1,0,3,2] row_mask:0xf bank_mask:0xf
	s_waitcnt vmcnt(0) lgkmcnt(0)
	v_and_b32_e32 v41, 0xffff0000, v38
	s_mov_b64 s[10:11], 0x2d001800
	v_add_f32_e32 v42, v85, v40
	s_nop 1
	v_mov_b32_dpp v43, v42 quad_perm:[2,3,0,1] row_mask:0xf bank_mask:0xf
	v_lshlrev_b32_e32 v40, 16, v38
	v_lshlrev_b32_e32 v38, 16, v39
	v_and_b32_e32 v39, 0xffff0000, v39
	s_waitcnt lgkmcnt(0)
	v_add_f32_e32 v44, v42, v43
	s_nop 1
	v_mov_b32_dpp v45, v44 row_half_mirror row_mask:0xf bank_mask:0xf
	v_lshlrev_b32_e32 v42, 16, v36
	v_and_b32_e32 v43, 0xffff0000, v36
	v_lshlrev_b32_e32 v36, 16, v37
	v_and_b32_e32 v37, 0xffff0000, v37
	s_waitcnt lgkmcnt(0)
	v_add_f32_e32 v46, v44, v45
	s_nop 1
	v_mov_b32_dpp v47, v46 row_mirror row_mask:0xf bank_mask:0xf
	v_lshlrev_b32_e32 v44, 16, v34
	v_and_b32_e32 v45, 0xffff0000, v34
	v_lshlrev_b32_e32 v34, 16, v35
	v_and_b32_e32 v35, 0xffff0000, v35
	s_waitcnt lgkmcnt(0)
	v_add_f32_e32 v48, v46, v47
	v_mov_b32_e32 v49, v48
	v_mov_b32_e32 v254, v48
	s_nop 1
	v_permlane16_swap_b32_e32 v49, v254
	v_lshlrev_b32_e32 v46, 16, v32
	v_and_b32_e32 v47, 0xffff0000, v32
	v_lshlrev_b32_e32 v32, 16, v33
	v_and_b32_e32 v33, 0xffff0000, v33
	s_waitcnt lgkmcnt(0)
	v_add_f32_e32 v50, v254, v49
	v_mov_b32_e32 v51, v50
	v_mov_b32_e32 v254, v50
	s_nop 1
	v_permlane32_swap_b32_e32 v51, v254
	v_lshlrev_b32_e32 v48, 16, v30
	v_and_b32_e32 v49, 0xffff0000, v30
	v_lshlrev_b32_e32 v30, 16, v31
	v_and_b32_e32 v31, 0xffff0000, v31
	s_waitcnt lgkmcnt(0)
	v_add_f32_e32 v50, v254, v51
	v_fmamk_f32 v50, v50, 0x3a800000, v241
	v_mul_f32_e32 v51, 0x4b800000, v50
	v_cmp_gt_f32_e32 vcc, s21, v50
	s_nop 1
	v_cndmask_b32_e32 v50, v50, v51, vcc
	v_rsq_f32_e32 v52, v50
	v_lshlrev_b32_e32 v50, 16, v28
	v_and_b32_e32 v51, 0xffff0000, v28
	v_mul_f32_e32 v28, 0x45800000, v52
	v_cndmask_b32_e32 v28, v52, v28, vcc
	v_pk_mul_f32 v[48:49], v[28:29], v[48:49] op_sel_hi:[0,1]
	v_pk_mul_f32 v[30:31], v[28:29], v[30:31] op_sel_hi:[0,1]
	v_pk_fma_f32 v[30:31], v[4:5], v[30:31], v[38:39]
	v_pk_fma_f32 v[38:39], v[2:3], v[48:49], v[40:41]
	v_mul_f32_e32 v41, v31, v31
	v_mul_f32_e32 v40, v39, v39
	v_fmac_f32_e32 v40, v38, v38
	v_fmac_f32_e32 v41, v30, v30
	v_add_f32_e32 v52, v40, v41
	v_lshlrev_b32_e32 v40, 16, v29
	v_and_b32_e32 v41, 0xffff0000, v29
	v_pk_mul_f32 v[48:49], v[28:29], v[50:51] op_sel_hi:[0,1]
	v_pk_mul_f32 v[40:41], v[28:29], v[40:41] op_sel_hi:[0,1]
	v_pk_fma_f32 v[36:37], v[8:9], v[40:41], v[36:37]
	v_pk_fma_f32 v[40:41], v[6:7], v[48:49], v[42:43]
	v_mul_f32_e32 v42, v37, v37
	v_mul_f32_e32 v29, v41, v41
	v_fmac_f32_e32 v29, v40, v40
	v_fmac_f32_e32 v42, v36, v36
	v_add_f32_e32 v29, v29, v42
	v_add_f32_e32 v29, v52, v29
	v_lshlrev_b32_e32 v42, 16, v26
	v_and_b32_e32 v43, 0xffff0000, v26
	v_lshlrev_b32_e32 v26, 16, v27
	v_and_b32_e32 v27, 0xffff0000, v27
	v_pk_mul_f32 v[42:43], v[28:29], v[42:43] op_sel_hi:[0,1]
	v_pk_mul_f32 v[26:27], v[28:29], v[26:27] op_sel_hi:[0,1]
	v_pk_fma_f32 v[26:27], v[12:13], v[26:27], v[34:35]
	v_pk_fma_f32 v[34:35], v[10:11], v[42:43], v[44:45]
	v_mul_f32_e32 v43, v27, v27
	v_mul_f32_e32 v42, v35, v35
	v_fmac_f32_e32 v42, v34, v34
	v_fmac_f32_e32 v43, v26, v26
	v_add_f32_e32 v42, v42, v43
	v_add_f32_e32 v44, v42, v29
	v_lshlrev_b32_e32 v42, 16, v24
	v_and_b32_e32 v43, 0xffff0000, v24
	v_lshlrev_b32_e32 v24, 16, v25
	v_and_b32_e32 v25, 0xffff0000, v25
	v_pk_mul_f32 v[42:43], v[28:29], v[42:43] op_sel_hi:[0,1]
	v_pk_mul_f32 v[24:25], v[28:29], v[24:25] op_sel_hi:[0,1]
	v_pk_fma_f32 v[24:25], v[16:17], v[24:25], v[32:33]
	v_pk_fma_f32 v[28:29], v[14:15], v[42:43], v[46:47]
	v_mul_f32_e32 v33, v25, v25
	v_mul_f32_e32 v32, v29, v29
	v_fmac_f32_e32 v32, v28, v28
	v_fmac_f32_e32 v33, v24, v24
	v_add_f32_e32 v32, v32, v33
	v_add_f32_e32 v32, v32, v44
	s_nop 1
	v_mov_b32_dpp v33, v32 quad_perm:[1,0,3,2] row_mask:0xf bank_mask:0xf
	v_cvt_pk_bf16_f32 v38, v38, v39
	v_cvt_pk_bf16_f32 v39, v30, v31
	v_cvt_pk_bf16_f32 v30, v40, v41
	v_cvt_pk_bf16_f32 v31, v36, v37
	s_waitcnt lgkmcnt(0)
	v_add_f32_e32 v32, v32, v33
	s_nop 1
	v_mov_b32_dpp v33, v32 quad_perm:[2,3,0,1] row_mask:0xf bank_mask:0xf
	s_waitcnt lgkmcnt(0)
	v_add_f32_e32 v32, v32, v33
	s_nop 1
	v_mov_b32_dpp v33, v32 row_half_mirror row_mask:0xf bank_mask:0xf
	s_waitcnt lgkmcnt(0)
	v_add_f32_e32 v32, v32, v33
	s_nop 1
	v_mov_b32_dpp v33, v32 row_mirror row_mask:0xf bank_mask:0xf
	s_waitcnt lgkmcnt(0)
	v_add_f32_e32 v48, v32, v33
	v_mov_b32_e32 v49, v48
	v_mov_b32_e32 v254, v48
	s_nop 1
	v_permlane16_swap_b32_e32 v49, v254
	v_lshl_add_u64 v[32:33], v[22:23], 0, s[10:11]
	s_mov_b64 s[10:11], 0x2d001a00
	v_lshl_add_u64 v[42:43], v[22:23], 0, s[10:11]
	s_mov_b64 s[10:11], 0x2d001c00
	v_lshl_add_u64 v[44:45], v[22:23], 0, s[10:11]
	s_mov_b64 s[10:11], 0x2d001e00
	v_lshl_add_u64 v[46:47], v[22:23], 0, s[10:11]
	s_waitcnt lgkmcnt(0)
	v_add_f32_e32 v22, v254, v49
	v_mov_b32_e32 v23, v22
	v_mov_b32_e32 v254, v22
	s_nop 1
	v_permlane32_swap_b32_e32 v23, v254
	global_store_dwordx2 v[42:43], v[30:31], off
	v_cvt_pk_bf16_f32 v30, v34, v35
	v_cvt_pk_bf16_f32 v31, v26, v27
	v_cvt_pk_bf16_f32 v26, v28, v29
	v_cvt_pk_bf16_f32 v27, v24, v25
	global_store_dwordx2 v[32:33], v[38:39], off
	global_store_dwordx2 v[44:45], v[30:31], off
	global_store_dwordx2 v[46:47], v[26:27], off
	s_and_saveexec_b64 s[10:11], s[4:5]
	s_cbranch_execz .LBB0_865
	s_waitcnt lgkmcnt(0)
	v_add_f32_e32 v22, v254, v23
	v_fmamk_f32 v22, v22, 0x3a800000, v241
	v_mul_f32_e32 v23, 0x4b800000, v22
	v_cmp_gt_f32_e32 vcc, s21, v22
	s_add_u32 s7, s0, s8
	s_addc_u32 s12, s1, s9
	v_cndmask_b32_e32 v22, v22, v23, vcc
	v_rsq_f32_e32 v22, v22
	s_nop 0
	v_mul_f32_e32 v23, 0x45800000, v22
	v_cndmask_b32_e32 v24, v22, v23, vcc
	v_mov_b32_e32 v22, s7
	v_add_co_u32_e32 v22, vcc, 0x3b700000, v22
	v_mov_b32_e32 v23, s12
	s_nop 0
	v_addc_co_u32_e32 v23, vcc, 0, v23, vcc
	flat_store_dword v[22:23], v24 offset:12
	s_branch .LBB0_865

; __global__ void __launch_bounds__(512, 2) mk_fwd(Params p) {
	.amdhsa_kernel _Z6mk_fwd6Params
		.amdhsa_group_segment_fixed_size 0
		.amdhsa_private_segment_fixed_size 0
		.amdhsa_kernarg_size 440
		.amdhsa_user_sgpr_count 2
		.amdhsa_user_sgpr_dispatch_ptr 0
		.amdhsa_user_sgpr_queue_ptr 0
		.amdhsa_user_sgpr_kernarg_segment_ptr 1
		.amdhsa_user_sgpr_dispatch_id 0
		.amdhsa_user_sgpr_kernarg_preload_length 0
		.amdhsa_user_sgpr_kernarg_preload_offset 0
		.amdhsa_user_sgpr_private_segment_size 0
		.amdhsa_uses_dynamic_stack 0
		.amdhsa_enable_private_segment 0
		.amdhsa_system_sgpr_workgroup_id_x 1
		.amdhsa_system_sgpr_workgroup_id_y 0
		.amdhsa_system_sgpr_workgroup_id_z 0
		.amdhsa_system_sgpr_workgroup_info 0
		.amdhsa_system_vgpr_workitem_id 2
		.amdhsa_next_free_vgpr 256
		.amdhsa_next_free_sgpr 98
		.amdhsa_accum_offset 256
		.amdhsa_reserve_vcc 1
		.amdhsa_float_round_mode_32 0
		.amdhsa_float_round_mode_16_64 0
		.amdhsa_float_denorm_mode_32 3
		.amdhsa_float_denorm_mode_16_64 3
		.amdhsa_dx10_clamp 1
		.amdhsa_ieee_mode 1
		.amdhsa_fp16_overflow 0
		.amdhsa_tg_split 0
		.amdhsa_exception_fp_ieee_invalid_op 0
		.amdhsa_exception_fp_denorm_src 0
		.amdhsa_exception_fp_ieee_div_zero 0
		.amdhsa_exception_fp_ieee_overflow 0
		.amdhsa_exception_fp_ieee_underflow 0
		.amdhsa_exception_fp_ieee_inexact 0
		.amdhsa_exception_int_div_zero 0
	.end_amdhsa_kernel

; __global__ void __launch_bounds__(512, 2) mk_fwd(Params p) {
amdhsa.kernels:
  - .agpr_count:     0
    .args:
      - .offset:         0
        .size:           184
        .value_kind:     by_value
      - .offset:         184
        .size:           4
        .value_kind:     hidden_block_count_x
      - .offset:         188
        .size:           4
        .value_kind:     hidden_block_count_y
      - .offset:         192
        .size:           4
        .value_kind:     hidden_block_count_z
      - .offset:         196
        .size:           2
        .value_kind:     hidden_group_size_x
      - .offset:         198
        .size:           2
        .value_kind:     hidden_group_size_y
      - .offset:         200
        .size:           2
        .value_kind:     hidden_group_size_z
      - .offset:         202
        .size:           2
        .value_kind:     hidden_remainder_x
      - .offset:         204
        .size:           2
        .value_kind:     hidden_remainder_y
      - .offset:         206
        .size:           2
        .value_kind:     hidden_remainder_z
      - .offset:         224
        .size:           8
        .value_kind:     hidden_global_offset_x
      - .offset:         232
        .size:           8
        .value_kind:     hidden_global_offset_y
      - .offset:         240
        .size:           8
        .value_kind:     hidden_global_offset_z
      - .offset:         248
        .size:           2
        .value_kind:     hidden_grid_dims
      - .offset:         272
        .size:           8
        .value_kind:     hidden_multigrid_sync_arg
      - .offset:         304
        .size:           4
        .value_kind:     hidden_dynamic_lds_size
    .group_segment_fixed_size: 0
    .kernarg_segment_align: 8
    .kernarg_segment_size: 440
    .language:       OpenCL C
    .language_version:
      - 2
      - 0
    .max_flat_workgroup_size: 512
    .name:           _Z6mk_fwd6Params
    .private_segment_fixed_size: 0
    .sgpr_count:     104
    .sgpr_spill_count: 117
    .symbol:         _Z6mk_fwd6Params.kd
    .uniform_work_group_size: 1
    .uses_dynamic_stack: false
    .vgpr_count:     256
    .vgpr_spill_count: 0
    .wavefront_size: 64
